# V tiles: K-loop with swapped MFMA operands (transposed acc) + packed 8B V^T stores; redundant s_nop before DPP groups dropped; preamble load burst
# baseline (speedup 1.0000x reference)
; #define PG8_STAGE(bufoff, gbase, voff) do { _Pragma("unroll") for (int _i = 0; _i < 2; ++_i) \
;         __builtin_amdgcn_global_load_lds((const unsigned*)((const char*)(gbase) + (voff)[_i]), (PG8_LAS unsigned*)(lds + (bufoff) + ldsw + _i * 8192), 16, 0, 0); } while (0)
; #define PG8_LDA(dst, b, h) do { _Pragma("unroll") for (int m = 0; m < 4; ++m) _Pragma("unroll") for (int k = 0; k < 2; ++k) dst[m][k] = *(const PG8_LAS bf16x8*)(lds + PG8_SA(b, h) + aoff + m * 2048 + k * 1024); } while (0)
; #define PG8_LDB(dst, b, h) do { _Pragma("unroll") for (int n = 0; n < 2; ++n) _Pragma("unroll") for (int k = 0; k < 2; ++k) dst[n][k] = *(const PG8_LAS bf16x8*)(lds + PG8_SB(b, h) + boff + n * 2048 + k * 1024); } while (0)
; #define PG8_MMA(ai, bj, At, Bt) do { __builtin_amdgcn_s_setprio(1); _Pragma("unroll") for (int m = 0; m < 4; ++m) _Pragma("unroll") for (int n = 0; n < 2; ++n) _Pragma("unroll") for (int k = 0; k < 2; ++k) \
;         acc[ai][bj][m][n] = __builtin_amdgcn_mfma_f32_16x16x32_bf16(Bt[n][k], At[m][k], acc[ai][bj][m][n], 0, 0, 0); __builtin_amdgcn_s_setprio(0); } while (0)
; #define PG8_WAIT_V(n) asm volatile("s_waitcnt vmcnt(" #n ")" ::: "memory")
; #define PG8_WAIT_L(n) asm volatile("s_waitcnt lgkmcnt(" #n ")" ::: "memory")
; #define PG8_BAR __builtin_amdgcn_s_barrier()
; #define PG8_SCHED __builtin_amdgcn_sched_barrier(0)
; template <class Epi, class Sched, bool ALIGN_EPI = false, bool SP2 = false>
; __device__ __forceinline__ void gemm_phase(PG8_LAS unsigned char* lds, const Gemm g, const Sched& S, const Epi& E) {
;     ...
;             PG8_LDB(B0, 0, 0); PG8_LDB(B1, 0, 1); PG8_SCHED; PG8_LDA(At, 0, 0); PG8_STAGE(PG8_SA(1, 1), a1 + hstep, voffA);
;             PG8_WAIT_V(8); PG8_WAIT_L(0); PG8_BAR; PG8_MMA(0, 0, At, B0); PG8_MMA(0, 1, At, B1); PG8_BAR; PG8_SCHED;
;             PG8_LDA(At, 0, 1); PG8_STAGE(PG8_SB(0, 0), b2, voffB); PG8_STAGE(PG8_SB(0, 1), b2 + hstep, voffB); PG8_STAGE(PG8_SA(0, 0), a2, voffA);
;             PG8_WAIT_V(8); PG8_WAIT_L(0); PG8_BAR; PG8_MMA(1, 0, At, B0); PG8_MMA(1, 1, At, B1); PG8_BAR; PG8_SCHED;
;     __device__ __forceinline__ void operator()(const f32x4 (&acc)[2][2][4][2], const pg8::Unit& u, int wr, int wc, int fr, int fq) const {
;     ...
;         } else if (pn < 6) {
;             const int head = 4 * (pn & 1) + wc, b = u.pm >> 3;
.LBB0_274:
	s_lshr_b32 s32, s21, 1
	s_cmp_eq_u32 s32, 2
	s_cbranch_scc1 .Lp2_vloop
	ds_read_b128 v[146:149], v169
	ds_read_b128 v[150:153], v169 offset:1024
	ds_read_b128 v[178:181], v169 offset:2048
	ds_read_b128 v[182:185], v169 offset:3072
	ds_read_b128 v[186:189], v170
	ds_read_b128 v[190:193], v170 offset:1024
	ds_read_b128 v[194:197], v170 offset:2048
	ds_read_b128 v[198:201], v170 offset:3072
	s_add_u32 s0, s14, 0xfffc0080
	s_addc_u32 s1, s15, -1
	s_cmp_eq_u32 s93, 12
	s_cselect_b32 s53, s45, s1
	s_cselect_b32 s52, s89, s0
	s_cselect_b32 s51, s43, s92
	s_cselect_b32 s50, s90, s91
	v_lshl_add_u64 v[206:207], s[14:15], 0, v[138:139]
	s_add_i32 m0, s56, 0xc000
	ds_read_b128 v[202:205], v171
	ds_read_b128 v[210:213], v171 offset:1024
	ds_read_b128 v[214:217], v171 offset:2048
	ds_read_b128 v[218:221], v171 offset:3072
	ds_read_b128 v[222:225], v171 offset:4096
	ds_read_b128 v[226:229], v171 offset:5120
	ds_read_b128 v[230:233], v171 offset:6144
	ds_read_b128 v[234:237], v171 offset:7168
	global_load_lds_dwordx4 v[206:207], off
	v_lshl_add_u64 v[206:207], s[14:15], 0, v[140:141]
	s_add_i32 m0, s56, 0xe000
	s_nop 0
	global_load_lds_dwordx4 v[206:207], off
	s_waitcnt vmcnt(8)
	s_waitcnt lgkmcnt(0)
	s_barrier
	s_setprio 1
	s_waitcnt lgkmcnt(0)
	v_mfma_f32_16x16x32_bf16 v[124:127], v[146:149], v[202:205], v[124:127]
	v_mfma_f32_16x16x32_bf16 v[120:123], v[178:181], v[202:205], v[120:123]
	v_mfma_f32_16x16x32_bf16 v[112:115], v[146:149], v[214:217], v[112:115]
	v_mfma_f32_16x16x32_bf16 v[104:107], v[178:181], v[214:217], v[104:107]
	v_mfma_f32_16x16x32_bf16 v[96:99], v[146:149], v[222:225], v[96:99]
	v_mfma_f32_16x16x32_bf16 v[88:91], v[178:181], v[222:225], v[88:91]
	v_mfma_f32_16x16x32_bf16 v[80:83], v[146:149], v[230:233], v[80:83]
	v_mfma_f32_16x16x32_bf16 v[72:75], v[178:181], v[230:233], v[72:75]
	v_mfma_f32_16x16x32_bf16 v[124:127], v[150:153], v[210:213], v[124:127]
	v_mfma_f32_16x16x32_bf16 v[120:123], v[182:185], v[210:213], v[120:123]
	v_mfma_f32_16x16x32_bf16 v[112:115], v[150:153], v[218:221], v[112:115]
	v_mfma_f32_16x16x32_bf16 v[104:107], v[182:185], v[218:221], v[104:107]
	v_mfma_f32_16x16x32_bf16 v[96:99], v[150:153], v[226:229], v[96:99]
	v_mfma_f32_16x16x32_bf16 v[88:91], v[182:185], v[226:229], v[88:91]
	v_mfma_f32_16x16x32_bf16 v[80:83], v[150:153], v[234:237], v[80:83]
	v_mfma_f32_16x16x32_bf16 v[72:75], v[182:185], v[234:237], v[72:75]
	s_setprio 0
	s_setprio 1
	v_mfma_f32_16x16x32_bf16 v[116:119], v[186:189], v[202:205], v[116:119]
	v_mfma_f32_16x16x32_bf16 v[108:111], v[194:197], v[202:205], v[108:111]
	v_mfma_f32_16x16x32_bf16 v[100:103], v[186:189], v[214:217], v[100:103]
	v_mfma_f32_16x16x32_bf16 v[92:95], v[194:197], v[214:217], v[92:95]
	v_mfma_f32_16x16x32_bf16 v[84:87], v[186:189], v[222:225], v[84:87]
	v_mfma_f32_16x16x32_bf16 v[76:79], v[194:197], v[222:225], v[76:79]
	v_mfma_f32_16x16x32_bf16 v[68:71], v[186:189], v[230:233], v[68:71]
	v_mfma_f32_16x16x32_bf16 v[64:67], v[194:197], v[230:233], v[64:67]
	v_mfma_f32_16x16x32_bf16 v[116:119], v[190:193], v[210:213], v[116:119]
	v_mfma_f32_16x16x32_bf16 v[108:111], v[198:201], v[210:213], v[108:111]
	v_mfma_f32_16x16x32_bf16 v[100:103], v[190:193], v[218:221], v[100:103]
	v_mfma_f32_16x16x32_bf16 v[92:95], v[198:201], v[218:221], v[92:95]
	v_mfma_f32_16x16x32_bf16 v[84:87], v[190:193], v[226:229], v[84:87]
	v_mfma_f32_16x16x32_bf16 v[76:79], v[198:201], v[226:229], v[76:79]
	v_mfma_f32_16x16x32_bf16 v[68:71], v[190:193], v[234:237], v[68:71]
	v_mfma_f32_16x16x32_bf16 v[64:67], v[198:201], v[234:237], v[64:67]
	s_setprio 0
	s_barrier
	s_add_i32 s0, s74, s29
	v_lshl_add_u64 v[206:207], s[50:51], 0, v[132:133]
	s_mov_b32 m0, s0
	ds_read_b128 v[202:205], v171 offset:16384
	ds_read_b128 v[210:213], v171 offset:17408
	ds_read_b128 v[214:217], v171 offset:18432
	ds_read_b128 v[218:221], v171 offset:19456
	ds_read_b128 v[222:225], v171 offset:20480
	ds_read_b128 v[226:229], v171 offset:21504
	ds_read_b128 v[230:233], v171 offset:22528
	ds_read_b128 v[234:237], v171 offset:23552
	global_load_lds_dwordx4 v[206:207], off
	s_add_i32 m0, s0, 0x2000
	s_add_u32 s94, s50, 0x40000
	v_lshl_add_u64 v[238:239], s[50:51], 0, v[128:129]
	s_addc_u32 s95, s51, 0
	s_add_i32 s0, s75, s29
	global_load_lds_dwordx4 v[238:239], off
	v_lshl_add_u64 v[240:241], s[94:95], 0, v[132:133]
	s_mov_b32 m0, s0
	v_lshl_add_u64 v[242:243], s[52:53], 0, v[130:131]
	global_load_lds_dwordx4 v[240:241], off
	v_lshl_add_u64 v[240:241], s[94:95], 0, v[128:129]
	s_add_i32 m0, s0, 0x2000
	s_nop 0
	global_load_lds_dwordx4 v[240:241], off
	v_lshl_add_u64 v[240:241], s[52:53], 0, v[134:135]
	s_mov_b32 m0, s56
	s_nop 0
	global_load_lds_dwordx4 v[240:241], off
	s_mov_b32 m0, s57
	s_nop 0
	global_load_lds_dwordx4 v[242:243], off
	s_waitcnt vmcnt(8)
	s_waitcnt lgkmcnt(0)
	s_barrier
; #define PG8_STAGE(bufoff, gbase, voff) do { _Pragma("unroll") for (int _i = 0; _i < 2; ++_i) \
;         __builtin_amdgcn_global_load_lds((const unsigned*)((const char*)(gbase) + (voff)[_i]), (PG8_LAS unsigned*)(lds + (bufoff) + ldsw + _i * 8192), 16, 0, 0); } while (0)
; #define PG8_LDA(dst, b, h) do { _Pragma("unroll") for (int m = 0; m < 4; ++m) _Pragma("unroll") for (int k = 0; k < 2; ++k) dst[m][k] = *(const PG8_LAS bf16x8*)(lds + PG8_SA(b, h) + aoff + m * 2048 + k * 1024); } while (0)
; #define PG8_LDB(dst, b, h) do { _Pragma("unroll") for (int n = 0; n < 2; ++n) _Pragma("unroll") for (int k = 0; k < 2; ++k) dst[n][k] = *(const PG8_LAS bf16x8*)(lds + PG8_SB(b, h) + boff + n * 2048 + k * 1024); } while (0)
; #define PG8_MMA(ai, bj, At, Bt) do { __builtin_amdgcn_s_setprio(1); _Pragma("unroll") for (int m = 0; m < 4; ++m) _Pragma("unroll") for (int n = 0; n < 2; ++n) _Pragma("unroll") for (int k = 0; k < 2; ++k) \
;         acc[ai][bj][m][n] = __builtin_amdgcn_mfma_f32_16x16x32_bf16(Bt[n][k], At[m][k], acc[ai][bj][m][n], 0, 0, 0); __builtin_amdgcn_s_setprio(0); } while (0)
; #define PG8_WAIT_V(n) asm volatile("s_waitcnt vmcnt(" #n ")" ::: "memory")
; #define PG8_WAIT_L(n) asm volatile("s_waitcnt lgkmcnt(" #n ")" ::: "memory")
; #define PG8_BAR __builtin_amdgcn_s_barrier()
; #define PG8_SCHED __builtin_amdgcn_sched_barrier(0)
; template <class Epi, class Sched, bool ALIGN_EPI = false, bool SP2 = false>
; __device__ __forceinline__ void gemm_phase(PG8_LAS unsigned char* lds, const Gemm g, const Sched& S, const Epi& E) {
;     ...
;             PG8_WAIT_V(8); PG8_WAIT_L(0); PG8_BAR; PG8_MMA(1, 0, At, B0); PG8_MMA(1, 1, At, B1); PG8_BAR; PG8_SCHED;
;             PG8_LDB(B0, 1, 0); PG8_LDB(B1, 1, 1); PG8_SCHED; PG8_LDA(At, 1, 0); PG8_STAGE(PG8_SA(0, 1), a2 + hstep, voffA);
;             PG8_WAIT_V(8); PG8_WAIT_L(0); PG8_BAR; PG8_MMA(0, 0, At, B0); PG8_MMA(0, 1, At, B1); PG8_BAR; PG8_SCHED;
	s_setprio 1
	s_waitcnt lgkmcnt(0)
	v_mfma_f32_16x16x32_bf16 v[60:63], v[146:149], v[202:205], v[60:63]
	v_mfma_f32_16x16x32_bf16 v[56:59], v[178:181], v[202:205], v[56:59]
	v_mfma_f32_16x16x32_bf16 v[48:51], v[146:149], v[214:217], v[48:51]
	v_mfma_f32_16x16x32_bf16 v[40:43], v[178:181], v[214:217], v[40:43]
	v_mfma_f32_16x16x32_bf16 v[32:35], v[146:149], v[222:225], v[32:35]
	v_mfma_f32_16x16x32_bf16 v[24:27], v[178:181], v[222:225], v[24:27]
	v_mfma_f32_16x16x32_bf16 v[16:19], v[146:149], v[230:233], v[16:19]
	v_mfma_f32_16x16x32_bf16 v[8:11], v[178:181], v[230:233], v[8:11]
	v_mfma_f32_16x16x32_bf16 v[60:63], v[150:153], v[210:213], v[60:63]
	v_mfma_f32_16x16x32_bf16 v[56:59], v[182:185], v[210:213], v[56:59]
	v_mfma_f32_16x16x32_bf16 v[48:51], v[150:153], v[218:221], v[48:51]
	v_mfma_f32_16x16x32_bf16 v[40:43], v[182:185], v[218:221], v[40:43]
	v_mfma_f32_16x16x32_bf16 v[32:35], v[150:153], v[226:229], v[32:35]
	v_mfma_f32_16x16x32_bf16 v[24:27], v[182:185], v[226:229], v[24:27]
	v_mfma_f32_16x16x32_bf16 v[16:19], v[150:153], v[234:237], v[16:19]
	v_mfma_f32_16x16x32_bf16 v[8:11], v[182:185], v[234:237], v[8:11]
	s_setprio 0
	s_setprio 1
	v_mfma_f32_16x16x32_bf16 v[52:55], v[186:189], v[202:205], v[52:55]
	v_mfma_f32_16x16x32_bf16 v[44:47], v[194:197], v[202:205], v[44:47]
	v_mfma_f32_16x16x32_bf16 v[36:39], v[186:189], v[214:217], v[36:39]
	v_mfma_f32_16x16x32_bf16 v[28:31], v[194:197], v[214:217], v[28:31]
	v_mfma_f32_16x16x32_bf16 v[20:23], v[186:189], v[222:225], v[20:23]
	v_mfma_f32_16x16x32_bf16 v[12:15], v[194:197], v[222:225], v[12:15]
	v_mfma_f32_16x16x32_bf16 v[4:7], v[186:189], v[230:233], v[4:7]
	v_mfma_f32_16x16x32_bf16 v[0:3], v[194:197], v[230:233], v[0:3]
	v_mfma_f32_16x16x32_bf16 v[52:55], v[190:193], v[210:213], v[52:55]
	v_mfma_f32_16x16x32_bf16 v[44:47], v[198:201], v[210:213], v[44:47]
	v_mfma_f32_16x16x32_bf16 v[36:39], v[190:193], v[218:221], v[36:39]
	v_mfma_f32_16x16x32_bf16 v[28:31], v[198:201], v[218:221], v[28:31]
	v_mfma_f32_16x16x32_bf16 v[20:23], v[190:193], v[226:229], v[20:23]
	v_mfma_f32_16x16x32_bf16 v[12:15], v[198:201], v[226:229], v[12:15]
	v_mfma_f32_16x16x32_bf16 v[4:7], v[190:193], v[234:237], v[4:7]
	v_mfma_f32_16x16x32_bf16 v[0:3], v[198:201], v[234:237], v[0:3]
	s_setprio 0
	s_barrier
	s_add_i32 s0, 0, 0x18000
	v_add_u32_e32 v136, s0, v158
	s_add_i32 s1, 0, 0x1c000
	ds_read_b128 v[146:149], v136
	ds_read_b128 v[150:153], v136 offset:1024
	ds_read_b128 v[178:181], v136 offset:2048
	ds_read_b128 v[182:185], v136 offset:3072
	v_add_u32_e32 v136, s1, v158
	ds_read_b128 v[186:189], v136
	ds_read_b128 v[190:193], v136 offset:1024
	ds_read_b128 v[194:197], v136 offset:2048
	ds_read_b128 v[198:201], v136 offset:3072
	s_add_u32 s52, s52, 0x40000
	s_addc_u32 s53, s53, 0
	s_mov_b32 m0, s59
	v_lshl_add_u64 v[244:245], s[52:53], 0, v[134:135]
	ds_read_b128 v[202:205], v171 offset:32768
	ds_read_b128 v[210:213], v171 offset:33792
	ds_read_b128 v[214:217], v171 offset:34816
	ds_read_b128 v[218:221], v171 offset:35840
	ds_read_b128 v[222:225], v171 offset:36864
	ds_read_b128 v[226:229], v171 offset:37888
	ds_read_b128 v[230:233], v171 offset:38912
	ds_read_b128 v[234:237], v171 offset:39936
	global_load_lds_dwordx4 v[244:245], off
	v_lshl_add_u64 v[244:245], s[52:53], 0, v[130:131]
	s_mov_b32 m0, s60
	s_nop 0
	global_load_lds_dwordx4 v[244:245], off
	s_waitcnt vmcnt(8)
	s_waitcnt lgkmcnt(0)
	s_barrier
	s_setprio 1
	s_waitcnt lgkmcnt(0)
	v_mfma_f32_16x16x32_bf16 v[124:127], v[146:149], v[202:205], v[124:127]
	v_mfma_f32_16x16x32_bf16 v[120:123], v[178:181], v[202:205], v[120:123]
	v_mfma_f32_16x16x32_bf16 v[112:115], v[146:149], v[214:217], v[112:115]
	v_mfma_f32_16x16x32_bf16 v[104:107], v[178:181], v[214:217], v[104:107]
	v_mfma_f32_16x16x32_bf16 v[96:99], v[146:149], v[222:225], v[96:99]
	v_mfma_f32_16x16x32_bf16 v[88:91], v[178:181], v[222:225], v[88:91]
	v_mfma_f32_16x16x32_bf16 v[80:83], v[146:149], v[230:233], v[80:83]
	v_mfma_f32_16x16x32_bf16 v[72:75], v[178:181], v[230:233], v[72:75]
	v_mfma_f32_16x16x32_bf16 v[124:127], v[150:153], v[210:213], v[124:127]
	v_mfma_f32_16x16x32_bf16 v[120:123], v[182:185], v[210:213], v[120:123]
	v_mfma_f32_16x16x32_bf16 v[112:115], v[150:153], v[218:221], v[112:115]
	v_mfma_f32_16x16x32_bf16 v[104:107], v[182:185], v[218:221], v[104:107]
	v_mfma_f32_16x16x32_bf16 v[96:99], v[150:153], v[226:229], v[96:99]
	v_mfma_f32_16x16x32_bf16 v[88:91], v[182:185], v[226:229], v[88:91]
	v_mfma_f32_16x16x32_bf16 v[80:83], v[150:153], v[234:237], v[80:83]
	v_mfma_f32_16x16x32_bf16 v[72:75], v[182:185], v[234:237], v[72:75]
	s_setprio 0
	s_setprio 1
	v_mfma_f32_16x16x32_bf16 v[116:119], v[186:189], v[202:205], v[116:119]
	v_mfma_f32_16x16x32_bf16 v[108:111], v[194:197], v[202:205], v[108:111]
	v_mfma_f32_16x16x32_bf16 v[100:103], v[186:189], v[214:217], v[100:103]
	v_mfma_f32_16x16x32_bf16 v[92:95], v[194:197], v[214:217], v[92:95]
	v_mfma_f32_16x16x32_bf16 v[84:87], v[186:189], v[222:225], v[84:87]
	v_mfma_f32_16x16x32_bf16 v[76:79], v[194:197], v[222:225], v[76:79]
	v_mfma_f32_16x16x32_bf16 v[68:71], v[186:189], v[230:233], v[68:71]
	v_mfma_f32_16x16x32_bf16 v[64:67], v[194:197], v[230:233], v[64:67]
	v_mfma_f32_16x16x32_bf16 v[116:119], v[190:193], v[210:213], v[116:119]
	v_mfma_f32_16x16x32_bf16 v[108:111], v[198:201], v[210:213], v[108:111]
	v_mfma_f32_16x16x32_bf16 v[100:103], v[190:193], v[218:221], v[100:103]
	v_mfma_f32_16x16x32_bf16 v[92:95], v[198:201], v[218:221], v[92:95]
	v_mfma_f32_16x16x32_bf16 v[84:87], v[190:193], v[226:229], v[84:87]
	v_mfma_f32_16x16x32_bf16 v[76:79], v[198:201], v[226:229], v[76:79]
	v_mfma_f32_16x16x32_bf16 v[68:71], v[190:193], v[234:237], v[68:71]
	v_mfma_f32_16x16x32_bf16 v[64:67], v[198:201], v[234:237], v[64:67]
	s_setprio 0
	s_barrier
; #define PG8_STAGE(bufoff, gbase, voff) do { _Pragma("unroll") for (int _i = 0; _i < 2; ++_i) \
;         __builtin_amdgcn_global_load_lds((const unsigned*)((const char*)(gbase) + (voff)[_i]), (PG8_LAS unsigned*)(lds + (bufoff) + ldsw + _i * 8192), 16, 0, 0); } while (0)
; #define PG8_LDA(dst, b, h) do { _Pragma("unroll") for (int m = 0; m < 4; ++m) _Pragma("unroll") for (int k = 0; k < 2; ++k) dst[m][k] = *(const PG8_LAS bf16x8*)(lds + PG8_SA(b, h) + aoff + m * 2048 + k * 1024); } while (0)
; #define PG8_MMA(ai, bj, At, Bt) do { __builtin_amdgcn_s_setprio(1); _Pragma("unroll") for (int m = 0; m < 4; ++m) _Pragma("unroll") for (int n = 0; n < 2; ++n) _Pragma("unroll") for (int k = 0; k < 2; ++k) \
;         acc[ai][bj][m][n] = __builtin_amdgcn_mfma_f32_16x16x32_bf16(Bt[n][k], At[m][k], acc[ai][bj][m][n], 0, 0, 0); __builtin_amdgcn_s_setprio(0); } while (0)
; #define PG8_WAIT_V(n) asm volatile("s_waitcnt vmcnt(" #n ")" ::: "memory")
; #define PG8_WAIT_L(n) asm volatile("s_waitcnt lgkmcnt(" #n ")" ::: "memory")
; #define PG8_BAR __builtin_amdgcn_s_barrier()
; #define PG8_SCHED __builtin_amdgcn_sched_barrier(0)
; template <class Epi, class Sched, bool ALIGN_EPI = false, bool SP2 = false>
; __device__ __forceinline__ void gemm_phase(PG8_LAS unsigned char* lds, const Gemm g, const Sched& S, const Epi& E) {
;     ...
;             PG8_WAIT_V(8); PG8_WAIT_L(0); PG8_BAR; PG8_MMA(0, 0, At, B0); PG8_MMA(0, 1, At, B1); PG8_BAR; PG8_SCHED;
;             PG8_LDA(At, 1, 1); PG8_STAGE(PG8_SB(1, 0), b3, voffB); PG8_STAGE(PG8_SB(1, 1), b3 + hstep, voffB); PG8_STAGE(PG8_SA(1, 0), a3, voffA);
;             PG8_WAIT_V(8); PG8_WAIT_L(0); PG8_BAR; PG8_MMA(1, 0, At, B0); PG8_MMA(1, 1, At, B1); PG8_BAR; PG8_SCHED;
;     ...
;         if constexpr (ALIGN_EPI) { if (wr == 0) PG8_BAR; }
	s_add_i32 s0, s0, s29
	v_lshl_add_u64 v[206:207], v[206:207], 0, s[38:39]
	s_mov_b32 m0, s0
	ds_read_b128 v[202:205], v171 offset:49152
	ds_read_b128 v[210:213], v171 offset:50176
	ds_read_b128 v[214:217], v171 offset:51200
	ds_read_b128 v[218:221], v171 offset:52224
	ds_read_b128 v[222:225], v171 offset:53248
	ds_read_b128 v[226:229], v171 offset:54272
	ds_read_b128 v[230:233], v171 offset:55296
	ds_read_b128 v[234:237], v171 offset:56320
	global_load_lds_dwordx4 v[206:207], off
	s_add_i32 m0, s0, 0x2000
	s_add_u32 s50, s50, 0x40080
	v_lshl_add_u64 v[206:207], v[238:239], 0, s[38:39]
	s_addc_u32 s51, s51, 0
	s_add_i32 s0, s1, s29
	global_load_lds_dwordx4 v[206:207], off
	v_lshl_add_u64 v[206:207], s[50:51], 0, v[132:133]
	s_mov_b32 m0, s0
	s_nop 0
	global_load_lds_dwordx4 v[206:207], off
	v_lshl_add_u64 v[206:207], s[50:51], 0, v[128:129]
	s_add_i32 m0, s0, 0x2000
	s_nop 0
	global_load_lds_dwordx4 v[206:207], off
	v_lshl_add_u64 v[206:207], v[240:241], 0, s[38:39]
	s_mov_b32 m0, s69
	s_nop 0
	global_load_lds_dwordx4 v[206:207], off
	v_lshl_add_u64 v[206:207], v[242:243], 0, s[38:39]
	s_mov_b32 m0, s70
	s_nop 0
	global_load_lds_dwordx4 v[206:207], off
	s_waitcnt vmcnt(8)
	s_waitcnt lgkmcnt(0)
	s_barrier
	s_setprio 1
	s_waitcnt lgkmcnt(0)
	v_mfma_f32_16x16x32_bf16 v[60:63], v[146:149], v[202:205], v[60:63]
	v_mfma_f32_16x16x32_bf16 v[56:59], v[178:181], v[202:205], v[56:59]
	v_mfma_f32_16x16x32_bf16 v[48:51], v[146:149], v[214:217], v[48:51]
	v_mfma_f32_16x16x32_bf16 v[40:43], v[178:181], v[214:217], v[40:43]
	v_mfma_f32_16x16x32_bf16 v[32:35], v[146:149], v[222:225], v[32:35]
	v_mfma_f32_16x16x32_bf16 v[24:27], v[178:181], v[222:225], v[24:27]
	v_mfma_f32_16x16x32_bf16 v[16:19], v[146:149], v[230:233], v[16:19]
	v_mfma_f32_16x16x32_bf16 v[8:11], v[178:181], v[230:233], v[8:11]
	v_mfma_f32_16x16x32_bf16 v[60:63], v[150:153], v[210:213], v[60:63]
	v_mfma_f32_16x16x32_bf16 v[56:59], v[182:185], v[210:213], v[56:59]
	v_mfma_f32_16x16x32_bf16 v[48:51], v[150:153], v[218:221], v[48:51]
	v_mfma_f32_16x16x32_bf16 v[40:43], v[182:185], v[218:221], v[40:43]
	v_mfma_f32_16x16x32_bf16 v[32:35], v[150:153], v[226:229], v[32:35]
	v_mfma_f32_16x16x32_bf16 v[24:27], v[182:185], v[226:229], v[24:27]
	v_mfma_f32_16x16x32_bf16 v[16:19], v[150:153], v[234:237], v[16:19]
	v_mfma_f32_16x16x32_bf16 v[8:11], v[182:185], v[234:237], v[8:11]
	s_setprio 0
	s_setprio 1
	v_mfma_f32_16x16x32_bf16 v[52:55], v[186:189], v[202:205], v[52:55]
	v_mfma_f32_16x16x32_bf16 v[44:47], v[194:197], v[202:205], v[44:47]
	v_mfma_f32_16x16x32_bf16 v[36:39], v[186:189], v[214:217], v[36:39]
	v_mfma_f32_16x16x32_bf16 v[28:31], v[194:197], v[214:217], v[28:31]
	v_mfma_f32_16x16x32_bf16 v[20:23], v[186:189], v[222:225], v[20:23]
	v_mfma_f32_16x16x32_bf16 v[12:15], v[194:197], v[222:225], v[12:15]
	v_mfma_f32_16x16x32_bf16 v[4:7], v[186:189], v[230:233], v[4:7]
	v_mfma_f32_16x16x32_bf16 v[0:3], v[194:197], v[230:233], v[0:3]
	v_mfma_f32_16x16x32_bf16 v[52:55], v[190:193], v[210:213], v[52:55]
	v_mfma_f32_16x16x32_bf16 v[44:47], v[198:201], v[210:213], v[44:47]
	v_mfma_f32_16x16x32_bf16 v[36:39], v[190:193], v[218:221], v[36:39]
	v_mfma_f32_16x16x32_bf16 v[28:31], v[198:201], v[218:221], v[28:31]
	v_mfma_f32_16x16x32_bf16 v[20:23], v[190:193], v[226:229], v[20:23]
	v_mfma_f32_16x16x32_bf16 v[12:15], v[198:201], v[226:229], v[12:15]
	v_mfma_f32_16x16x32_bf16 v[4:7], v[190:193], v[234:237], v[4:7]
	v_mfma_f32_16x16x32_bf16 v[0:3], v[198:201], v[234:237], v[0:3]
	s_setprio 0
	s_barrier
	s_add_i32 s93, s93, 2
	s_add_u32 s14, s14, 0x100
	s_addc_u32 s15, s15, 0
	s_add_u32 s91, s91, 0x100
	s_addc_u32 s92, s92, 0
	s_cmp_gt_u32 s93, 13
	s_cbranch_scc0 .LBB0_274
.Lp2_kexit:
	s_and_b64 vcc, exec, s[40:41]
	s_cbranch_vccz .LBB0_277
	s_barrier

; #define PG8_STAGE(bufoff, gbase, voff) do { _Pragma("unroll") for (int _i = 0; _i < 2; ++_i) \
;         __builtin_amdgcn_global_load_lds((const unsigned*)((const char*)(gbase) + (voff)[_i]), (PG8_LAS unsigned*)(lds + (bufoff) + ldsw + _i * 8192), 16, 0, 0); } while (0)
; #define PG8_LDA(dst, b, h) do { _Pragma("unroll") for (int m = 0; m < 4; ++m) _Pragma("unroll") for (int k = 0; k < 2; ++k) dst[m][k] = *(const PG8_LAS bf16x8*)(lds + PG8_SA(b, h) + aoff + m * 2048 + k * 1024); } while (0)
; #define PG8_LDB(dst, b, h) do { _Pragma("unroll") for (int n = 0; n < 2; ++n) _Pragma("unroll") for (int k = 0; k < 2; ++k) dst[n][k] = *(const PG8_LAS bf16x8*)(lds + PG8_SB(b, h) + boff + n * 2048 + k * 1024); } while (0)
; #define PG8_MMA(ai, bj, At, Bt) do { __builtin_amdgcn_s_setprio(1); _Pragma("unroll") for (int m = 0; m < 4; ++m) _Pragma("unroll") for (int n = 0; n < 2; ++n) _Pragma("unroll") for (int k = 0; k < 2; ++k) \
;         acc[ai][bj][m][n] = __builtin_amdgcn_mfma_f32_16x16x32_bf16(Bt[n][k], At[m][k], acc[ai][bj][m][n], 0, 0, 0); __builtin_amdgcn_s_setprio(0); } while (0)
; #define PG8_WAIT_V(n) asm volatile("s_waitcnt vmcnt(" #n ")" ::: "memory")
; #define PG8_WAIT_L(n) asm volatile("s_waitcnt lgkmcnt(" #n ")" ::: "memory")
; #define PG8_BAR __builtin_amdgcn_s_barrier()
; #define PG8_SCHED __builtin_amdgcn_sched_barrier(0)
; template <class Epi, class Sched, bool ALIGN_EPI = false, bool SP2 = false>
; __device__ __forceinline__ void gemm_phase(PG8_LAS unsigned char* lds, const Gemm g, const Sched& S, const Epi& E) {
;     ...
;             PG8_LDB(B0, 0, 0); PG8_LDB(B1, 0, 1); PG8_SCHED; PG8_LDA(At, 0, 0); PG8_STAGE(PG8_SA(1, 1), a1 + hstep, voffA);
;             PG8_WAIT_V(8); PG8_WAIT_L(0); PG8_BAR; PG8_MMA(0, 0, At, B0); PG8_MMA(0, 1, At, B1); PG8_BAR; PG8_SCHED;
;             PG8_LDA(At, 0, 1); PG8_STAGE(PG8_SB(0, 0), b2, voffB); PG8_STAGE(PG8_SB(0, 1), b2 + hstep, voffB); PG8_STAGE(PG8_SA(0, 0), a2, voffA);
;             PG8_WAIT_V(8); PG8_WAIT_L(0); PG8_BAR; PG8_MMA(1, 0, At, B0); PG8_MMA(1, 1, At, B1); PG8_BAR; PG8_SCHED;
.Lp2_vloop:
	ds_read_b128 v[146:149], v169
	ds_read_b128 v[150:153], v169 offset:1024
	ds_read_b128 v[178:181], v169 offset:2048
	ds_read_b128 v[182:185], v169 offset:3072
	ds_read_b128 v[186:189], v170
	ds_read_b128 v[190:193], v170 offset:1024
	ds_read_b128 v[194:197], v170 offset:2048
	ds_read_b128 v[198:201], v170 offset:3072
	s_add_u32 s0, s14, 0xfffc0080
	s_addc_u32 s1, s15, -1
	s_cmp_eq_u32 s93, 12
	s_cselect_b32 s53, s45, s1
	s_cselect_b32 s52, s89, s0
	s_cselect_b32 s51, s43, s92
	s_cselect_b32 s50, s90, s91
	v_lshl_add_u64 v[206:207], s[14:15], 0, v[138:139]
	s_add_i32 m0, s56, 0xc000
	ds_read_b128 v[202:205], v171
	ds_read_b128 v[210:213], v171 offset:1024
	ds_read_b128 v[214:217], v171 offset:2048
	ds_read_b128 v[218:221], v171 offset:3072
	ds_read_b128 v[222:225], v171 offset:4096
	ds_read_b128 v[226:229], v171 offset:5120
	ds_read_b128 v[230:233], v171 offset:6144
	ds_read_b128 v[234:237], v171 offset:7168
	global_load_lds_dwordx4 v[206:207], off
	v_lshl_add_u64 v[206:207], s[14:15], 0, v[140:141]
	s_add_i32 m0, s56, 0xe000
	s_nop 0
	global_load_lds_dwordx4 v[206:207], off
	s_waitcnt vmcnt(8)
	s_waitcnt lgkmcnt(0)
	s_barrier
	s_setprio 1
	s_waitcnt lgkmcnt(0)
	v_mfma_f32_16x16x32_bf16 v[124:127], v[202:205], v[146:149], v[124:127]
	v_mfma_f32_16x16x32_bf16 v[120:123], v[202:205], v[178:181], v[120:123]
	v_mfma_f32_16x16x32_bf16 v[112:115], v[214:217], v[146:149], v[112:115]
	v_mfma_f32_16x16x32_bf16 v[104:107], v[214:217], v[178:181], v[104:107]
	v_mfma_f32_16x16x32_bf16 v[96:99], v[222:225], v[146:149], v[96:99]
	v_mfma_f32_16x16x32_bf16 v[88:91], v[222:225], v[178:181], v[88:91]
	v_mfma_f32_16x16x32_bf16 v[80:83], v[230:233], v[146:149], v[80:83]
	v_mfma_f32_16x16x32_bf16 v[72:75], v[230:233], v[178:181], v[72:75]
	v_mfma_f32_16x16x32_bf16 v[124:127], v[210:213], v[150:153], v[124:127]
	v_mfma_f32_16x16x32_bf16 v[120:123], v[210:213], v[182:185], v[120:123]
	v_mfma_f32_16x16x32_bf16 v[112:115], v[218:221], v[150:153], v[112:115]
	v_mfma_f32_16x16x32_bf16 v[104:107], v[218:221], v[182:185], v[104:107]
	v_mfma_f32_16x16x32_bf16 v[96:99], v[226:229], v[150:153], v[96:99]
	v_mfma_f32_16x16x32_bf16 v[88:91], v[226:229], v[182:185], v[88:91]
	v_mfma_f32_16x16x32_bf16 v[80:83], v[234:237], v[150:153], v[80:83]
	v_mfma_f32_16x16x32_bf16 v[72:75], v[234:237], v[182:185], v[72:75]
	s_setprio 0
	s_setprio 1
	v_mfma_f32_16x16x32_bf16 v[116:119], v[202:205], v[186:189], v[116:119]
	v_mfma_f32_16x16x32_bf16 v[108:111], v[202:205], v[194:197], v[108:111]
	v_mfma_f32_16x16x32_bf16 v[100:103], v[214:217], v[186:189], v[100:103]
	v_mfma_f32_16x16x32_bf16 v[92:95], v[214:217], v[194:197], v[92:95]
	v_mfma_f32_16x16x32_bf16 v[84:87], v[222:225], v[186:189], v[84:87]
	v_mfma_f32_16x16x32_bf16 v[76:79], v[222:225], v[194:197], v[76:79]
	v_mfma_f32_16x16x32_bf16 v[68:71], v[230:233], v[186:189], v[68:71]
	v_mfma_f32_16x16x32_bf16 v[64:67], v[230:233], v[194:197], v[64:67]
	v_mfma_f32_16x16x32_bf16 v[116:119], v[210:213], v[190:193], v[116:119]
	v_mfma_f32_16x16x32_bf16 v[108:111], v[210:213], v[198:201], v[108:111]
	v_mfma_f32_16x16x32_bf16 v[100:103], v[218:221], v[190:193], v[100:103]
	v_mfma_f32_16x16x32_bf16 v[92:95], v[218:221], v[198:201], v[92:95]
	v_mfma_f32_16x16x32_bf16 v[84:87], v[226:229], v[190:193], v[84:87]
	v_mfma_f32_16x16x32_bf16 v[76:79], v[226:229], v[198:201], v[76:79]
	v_mfma_f32_16x16x32_bf16 v[68:71], v[234:237], v[190:193], v[68:71]
	v_mfma_f32_16x16x32_bf16 v[64:67], v[234:237], v[198:201], v[64:67]
	s_setprio 0
	s_barrier
	s_add_i32 s0, s74, s29
	v_lshl_add_u64 v[206:207], s[50:51], 0, v[132:133]
	s_mov_b32 m0, s0
	ds_read_b128 v[202:205], v171 offset:16384
	ds_read_b128 v[210:213], v171 offset:17408
	ds_read_b128 v[214:217], v171 offset:18432
	ds_read_b128 v[218:221], v171 offset:19456
	ds_read_b128 v[222:225], v171 offset:20480
	ds_read_b128 v[226:229], v171 offset:21504
	ds_read_b128 v[230:233], v171 offset:22528
	ds_read_b128 v[234:237], v171 offset:23552
	global_load_lds_dwordx4 v[206:207], off
	s_add_i32 m0, s0, 0x2000
	s_add_u32 s94, s50, 0x40000
	v_lshl_add_u64 v[238:239], s[50:51], 0, v[128:129]
	s_addc_u32 s95, s51, 0
	s_add_i32 s0, s75, s29
	global_load_lds_dwordx4 v[238:239], off
	v_lshl_add_u64 v[240:241], s[94:95], 0, v[132:133]
	s_mov_b32 m0, s0
	v_lshl_add_u64 v[242:243], s[52:53], 0, v[130:131]
	global_load_lds_dwordx4 v[240:241], off
	v_lshl_add_u64 v[240:241], s[94:95], 0, v[128:129]
	s_add_i32 m0, s0, 0x2000
	s_nop 0
	global_load_lds_dwordx4 v[240:241], off
	v_lshl_add_u64 v[240:241], s[52:53], 0, v[134:135]
	s_mov_b32 m0, s56
	s_nop 0
	global_load_lds_dwordx4 v[240:241], off
	s_mov_b32 m0, s57
	s_nop 0
	global_load_lds_dwordx4 v[242:243], off
	s_waitcnt vmcnt(8)
	s_waitcnt lgkmcnt(0)
	s_barrier
; #define PG8_STAGE(bufoff, gbase, voff) do { _Pragma("unroll") for (int _i = 0; _i < 2; ++_i) \
;         __builtin_amdgcn_global_load_lds((const unsigned*)((const char*)(gbase) + (voff)[_i]), (PG8_LAS unsigned*)(lds + (bufoff) + ldsw + _i * 8192), 16, 0, 0); } while (0)
; #define PG8_LDA(dst, b, h) do { _Pragma("unroll") for (int m = 0; m < 4; ++m) _Pragma("unroll") for (int k = 0; k < 2; ++k) dst[m][k] = *(const PG8_LAS bf16x8*)(lds + PG8_SA(b, h) + aoff + m * 2048 + k * 1024); } while (0)
; #define PG8_LDB(dst, b, h) do { _Pragma("unroll") for (int n = 0; n < 2; ++n) _Pragma("unroll") for (int k = 0; k < 2; ++k) dst[n][k] = *(const PG8_LAS bf16x8*)(lds + PG8_SB(b, h) + boff + n * 2048 + k * 1024); } while (0)
; #define PG8_MMA(ai, bj, At, Bt) do { __builtin_amdgcn_s_setprio(1); _Pragma("unroll") for (int m = 0; m < 4; ++m) _Pragma("unroll") for (int n = 0; n < 2; ++n) _Pragma("unroll") for (int k = 0; k < 2; ++k) \
;         acc[ai][bj][m][n] = __builtin_amdgcn_mfma_f32_16x16x32_bf16(Bt[n][k], At[m][k], acc[ai][bj][m][n], 0, 0, 0); __builtin_amdgcn_s_setprio(0); } while (0)
; #define PG8_WAIT_V(n) asm volatile("s_waitcnt vmcnt(" #n ")" ::: "memory")
; #define PG8_WAIT_L(n) asm volatile("s_waitcnt lgkmcnt(" #n ")" ::: "memory")
; #define PG8_BAR __builtin_amdgcn_s_barrier()
; #define PG8_SCHED __builtin_amdgcn_sched_barrier(0)
; template <class Epi, class Sched, bool ALIGN_EPI = false, bool SP2 = false>
; __device__ __forceinline__ void gemm_phase(PG8_LAS unsigned char* lds, const Gemm g, const Sched& S, const Epi& E) {
;     ...
;             PG8_WAIT_V(8); PG8_WAIT_L(0); PG8_BAR; PG8_MMA(1, 0, At, B0); PG8_MMA(1, 1, At, B1); PG8_BAR; PG8_SCHED;
;             PG8_LDB(B0, 1, 0); PG8_LDB(B1, 1, 1); PG8_SCHED; PG8_LDA(At, 1, 0); PG8_STAGE(PG8_SA(0, 1), a2 + hstep, voffA);
;             PG8_WAIT_V(8); PG8_WAIT_L(0); PG8_BAR; PG8_MMA(0, 0, At, B0); PG8_MMA(0, 1, At, B1); PG8_BAR; PG8_SCHED;
	s_setprio 1
	s_waitcnt lgkmcnt(0)
	v_mfma_f32_16x16x32_bf16 v[60:63], v[202:205], v[146:149], v[60:63]
	v_mfma_f32_16x16x32_bf16 v[56:59], v[202:205], v[178:181], v[56:59]
	v_mfma_f32_16x16x32_bf16 v[48:51], v[214:217], v[146:149], v[48:51]
	v_mfma_f32_16x16x32_bf16 v[40:43], v[214:217], v[178:181], v[40:43]
	v_mfma_f32_16x16x32_bf16 v[32:35], v[222:225], v[146:149], v[32:35]
	v_mfma_f32_16x16x32_bf16 v[24:27], v[222:225], v[178:181], v[24:27]
	v_mfma_f32_16x16x32_bf16 v[16:19], v[230:233], v[146:149], v[16:19]
	v_mfma_f32_16x16x32_bf16 v[8:11], v[230:233], v[178:181], v[8:11]
	v_mfma_f32_16x16x32_bf16 v[60:63], v[210:213], v[150:153], v[60:63]
	v_mfma_f32_16x16x32_bf16 v[56:59], v[210:213], v[182:185], v[56:59]
	v_mfma_f32_16x16x32_bf16 v[48:51], v[218:221], v[150:153], v[48:51]
	v_mfma_f32_16x16x32_bf16 v[40:43], v[218:221], v[182:185], v[40:43]
	v_mfma_f32_16x16x32_bf16 v[32:35], v[226:229], v[150:153], v[32:35]
	v_mfma_f32_16x16x32_bf16 v[24:27], v[226:229], v[182:185], v[24:27]
	v_mfma_f32_16x16x32_bf16 v[16:19], v[234:237], v[150:153], v[16:19]
	v_mfma_f32_16x16x32_bf16 v[8:11], v[234:237], v[182:185], v[8:11]
	s_setprio 0
	s_setprio 1
	v_mfma_f32_16x16x32_bf16 v[52:55], v[202:205], v[186:189], v[52:55]
	v_mfma_f32_16x16x32_bf16 v[44:47], v[202:205], v[194:197], v[44:47]
	v_mfma_f32_16x16x32_bf16 v[36:39], v[214:217], v[186:189], v[36:39]
	v_mfma_f32_16x16x32_bf16 v[28:31], v[214:217], v[194:197], v[28:31]
	v_mfma_f32_16x16x32_bf16 v[20:23], v[222:225], v[186:189], v[20:23]
	v_mfma_f32_16x16x32_bf16 v[12:15], v[222:225], v[194:197], v[12:15]
	v_mfma_f32_16x16x32_bf16 v[4:7], v[230:233], v[186:189], v[4:7]
	v_mfma_f32_16x16x32_bf16 v[0:3], v[230:233], v[194:197], v[0:3]
	v_mfma_f32_16x16x32_bf16 v[52:55], v[210:213], v[190:193], v[52:55]
	v_mfma_f32_16x16x32_bf16 v[44:47], v[210:213], v[198:201], v[44:47]
	v_mfma_f32_16x16x32_bf16 v[36:39], v[218:221], v[190:193], v[36:39]
	v_mfma_f32_16x16x32_bf16 v[28:31], v[218:221], v[198:201], v[28:31]
	v_mfma_f32_16x16x32_bf16 v[20:23], v[226:229], v[190:193], v[20:23]
	v_mfma_f32_16x16x32_bf16 v[12:15], v[226:229], v[198:201], v[12:15]
	v_mfma_f32_16x16x32_bf16 v[4:7], v[234:237], v[190:193], v[4:7]
	v_mfma_f32_16x16x32_bf16 v[0:3], v[234:237], v[198:201], v[0:3]
	s_setprio 0
	s_barrier
	s_add_i32 s0, 0, 0x18000
	v_add_u32_e32 v136, s0, v158
	s_add_i32 s1, 0, 0x1c000
	ds_read_b128 v[146:149], v136
	ds_read_b128 v[150:153], v136 offset:1024
	ds_read_b128 v[178:181], v136 offset:2048
	ds_read_b128 v[182:185], v136 offset:3072
	v_add_u32_e32 v136, s1, v158
	ds_read_b128 v[186:189], v136
	ds_read_b128 v[190:193], v136 offset:1024
	ds_read_b128 v[194:197], v136 offset:2048
	ds_read_b128 v[198:201], v136 offset:3072
	s_add_u32 s52, s52, 0x40000
	s_addc_u32 s53, s53, 0
	s_mov_b32 m0, s59
	v_lshl_add_u64 v[244:245], s[52:53], 0, v[134:135]
	ds_read_b128 v[202:205], v171 offset:32768
	ds_read_b128 v[210:213], v171 offset:33792
	ds_read_b128 v[214:217], v171 offset:34816
	ds_read_b128 v[218:221], v171 offset:35840
	ds_read_b128 v[222:225], v171 offset:36864
	ds_read_b128 v[226:229], v171 offset:37888
	ds_read_b128 v[230:233], v171 offset:38912
	ds_read_b128 v[234:237], v171 offset:39936
	global_load_lds_dwordx4 v[244:245], off
	v_lshl_add_u64 v[244:245], s[52:53], 0, v[130:131]
	s_mov_b32 m0, s60
	s_nop 0
	global_load_lds_dwordx4 v[244:245], off
	s_waitcnt vmcnt(8)
	s_waitcnt lgkmcnt(0)
	s_barrier
	s_setprio 1
	s_waitcnt lgkmcnt(0)
	v_mfma_f32_16x16x32_bf16 v[124:127], v[202:205], v[146:149], v[124:127]
	v_mfma_f32_16x16x32_bf16 v[120:123], v[202:205], v[178:181], v[120:123]
	v_mfma_f32_16x16x32_bf16 v[112:115], v[214:217], v[146:149], v[112:115]
	v_mfma_f32_16x16x32_bf16 v[104:107], v[214:217], v[178:181], v[104:107]
	v_mfma_f32_16x16x32_bf16 v[96:99], v[222:225], v[146:149], v[96:99]
	v_mfma_f32_16x16x32_bf16 v[88:91], v[222:225], v[178:181], v[88:91]
	v_mfma_f32_16x16x32_bf16 v[80:83], v[230:233], v[146:149], v[80:83]
	v_mfma_f32_16x16x32_bf16 v[72:75], v[230:233], v[178:181], v[72:75]
	v_mfma_f32_16x16x32_bf16 v[124:127], v[210:213], v[150:153], v[124:127]
	v_mfma_f32_16x16x32_bf16 v[120:123], v[210:213], v[182:185], v[120:123]
	v_mfma_f32_16x16x32_bf16 v[112:115], v[218:221], v[150:153], v[112:115]
	v_mfma_f32_16x16x32_bf16 v[104:107], v[218:221], v[182:185], v[104:107]
	v_mfma_f32_16x16x32_bf16 v[96:99], v[226:229], v[150:153], v[96:99]
	v_mfma_f32_16x16x32_bf16 v[88:91], v[226:229], v[182:185], v[88:91]
	v_mfma_f32_16x16x32_bf16 v[80:83], v[234:237], v[150:153], v[80:83]
	v_mfma_f32_16x16x32_bf16 v[72:75], v[234:237], v[182:185], v[72:75]
	s_setprio 0
	s_setprio 1
	v_mfma_f32_16x16x32_bf16 v[116:119], v[202:205], v[186:189], v[116:119]
	v_mfma_f32_16x16x32_bf16 v[108:111], v[202:205], v[194:197], v[108:111]
	v_mfma_f32_16x16x32_bf16 v[100:103], v[214:217], v[186:189], v[100:103]
	v_mfma_f32_16x16x32_bf16 v[92:95], v[214:217], v[194:197], v[92:95]
	v_mfma_f32_16x16x32_bf16 v[84:87], v[222:225], v[186:189], v[84:87]
	v_mfma_f32_16x16x32_bf16 v[76:79], v[222:225], v[194:197], v[76:79]
	v_mfma_f32_16x16x32_bf16 v[68:71], v[230:233], v[186:189], v[68:71]
	v_mfma_f32_16x16x32_bf16 v[64:67], v[230:233], v[194:197], v[64:67]
	v_mfma_f32_16x16x32_bf16 v[116:119], v[210:213], v[190:193], v[116:119]
	v_mfma_f32_16x16x32_bf16 v[108:111], v[210:213], v[198:201], v[108:111]
	v_mfma_f32_16x16x32_bf16 v[100:103], v[218:221], v[190:193], v[100:103]
	v_mfma_f32_16x16x32_bf16 v[92:95], v[218:221], v[198:201], v[92:95]
	v_mfma_f32_16x16x32_bf16 v[84:87], v[226:229], v[190:193], v[84:87]
	v_mfma_f32_16x16x32_bf16 v[76:79], v[226:229], v[198:201], v[76:79]
	v_mfma_f32_16x16x32_bf16 v[68:71], v[234:237], v[190:193], v[68:71]
	v_mfma_f32_16x16x32_bf16 v[64:67], v[234:237], v[198:201], v[64:67]
	s_setprio 0
	s_barrier
; #define PG8_STAGE(bufoff, gbase, voff) do { _Pragma("unroll") for (int _i = 0; _i < 2; ++_i) \
;         __builtin_amdgcn_global_load_lds((const unsigned*)((const char*)(gbase) + (voff)[_i]), (PG8_LAS unsigned*)(lds + (bufoff) + ldsw + _i * 8192), 16, 0, 0); } while (0)
; #define PG8_LDA(dst, b, h) do { _Pragma("unroll") for (int m = 0; m < 4; ++m) _Pragma("unroll") for (int k = 0; k < 2; ++k) dst[m][k] = *(const PG8_LAS bf16x8*)(lds + PG8_SA(b, h) + aoff + m * 2048 + k * 1024); } while (0)
; #define PG8_MMA(ai, bj, At, Bt) do { __builtin_amdgcn_s_setprio(1); _Pragma("unroll") for (int m = 0; m < 4; ++m) _Pragma("unroll") for (int n = 0; n < 2; ++n) _Pragma("unroll") for (int k = 0; k < 2; ++k) \
;         acc[ai][bj][m][n] = __builtin_amdgcn_mfma_f32_16x16x32_bf16(Bt[n][k], At[m][k], acc[ai][bj][m][n], 0, 0, 0); __builtin_amdgcn_s_setprio(0); } while (0)
; #define PG8_WAIT_V(n) asm volatile("s_waitcnt vmcnt(" #n ")" ::: "memory")
; #define PG8_WAIT_L(n) asm volatile("s_waitcnt lgkmcnt(" #n ")" ::: "memory")
; #define PG8_BAR __builtin_amdgcn_s_barrier()
; #define PG8_SCHED __builtin_amdgcn_sched_barrier(0)
; template <class Epi, class Sched, bool ALIGN_EPI = false, bool SP2 = false>
; __device__ __forceinline__ void gemm_phase(PG8_LAS unsigned char* lds, const Gemm g, const Sched& S, const Epi& E) {
;     ...
;             PG8_WAIT_V(8); PG8_WAIT_L(0); PG8_BAR; PG8_MMA(0, 0, At, B0); PG8_MMA(0, 1, At, B1); PG8_BAR; PG8_SCHED;
;             PG8_LDA(At, 1, 1); PG8_STAGE(PG8_SB(1, 0), b3, voffB); PG8_STAGE(PG8_SB(1, 1), b3 + hstep, voffB); PG8_STAGE(PG8_SA(1, 0), a3, voffA);
;             PG8_WAIT_V(8); PG8_WAIT_L(0); PG8_BAR; PG8_MMA(1, 0, At, B0); PG8_MMA(1, 1, At, B1); PG8_BAR; PG8_SCHED;
	s_add_i32 s0, s0, s29
	v_lshl_add_u64 v[206:207], v[206:207], 0, s[38:39]
	s_mov_b32 m0, s0
	ds_read_b128 v[202:205], v171 offset:49152
	ds_read_b128 v[210:213], v171 offset:50176
	ds_read_b128 v[214:217], v171 offset:51200
	ds_read_b128 v[218:221], v171 offset:52224
	ds_read_b128 v[222:225], v171 offset:53248
	ds_read_b128 v[226:229], v171 offset:54272
	ds_read_b128 v[230:233], v171 offset:55296
	ds_read_b128 v[234:237], v171 offset:56320
	global_load_lds_dwordx4 v[206:207], off
	s_add_i32 m0, s0, 0x2000
	s_add_u32 s50, s50, 0x40080
	v_lshl_add_u64 v[206:207], v[238:239], 0, s[38:39]
	s_addc_u32 s51, s51, 0
	s_add_i32 s0, s1, s29
	global_load_lds_dwordx4 v[206:207], off
	v_lshl_add_u64 v[206:207], s[50:51], 0, v[132:133]
	s_mov_b32 m0, s0
	s_nop 0
	global_load_lds_dwordx4 v[206:207], off
	v_lshl_add_u64 v[206:207], s[50:51], 0, v[128:129]
	s_add_i32 m0, s0, 0x2000
	s_nop 0
	global_load_lds_dwordx4 v[206:207], off
	v_lshl_add_u64 v[206:207], v[240:241], 0, s[38:39]
	s_mov_b32 m0, s69
	s_nop 0
	global_load_lds_dwordx4 v[206:207], off
	v_lshl_add_u64 v[206:207], v[242:243], 0, s[38:39]
	s_mov_b32 m0, s70
	s_nop 0
	global_load_lds_dwordx4 v[206:207], off
	s_waitcnt vmcnt(8)
	s_waitcnt lgkmcnt(0)
	s_barrier
	s_setprio 1
	s_waitcnt lgkmcnt(0)
	v_mfma_f32_16x16x32_bf16 v[60:63], v[202:205], v[146:149], v[60:63]
	v_mfma_f32_16x16x32_bf16 v[56:59], v[202:205], v[178:181], v[56:59]
	v_mfma_f32_16x16x32_bf16 v[48:51], v[214:217], v[146:149], v[48:51]
	v_mfma_f32_16x16x32_bf16 v[40:43], v[214:217], v[178:181], v[40:43]
	v_mfma_f32_16x16x32_bf16 v[32:35], v[222:225], v[146:149], v[32:35]
	v_mfma_f32_16x16x32_bf16 v[24:27], v[222:225], v[178:181], v[24:27]
	v_mfma_f32_16x16x32_bf16 v[16:19], v[230:233], v[146:149], v[16:19]
	v_mfma_f32_16x16x32_bf16 v[8:11], v[230:233], v[178:181], v[8:11]
	v_mfma_f32_16x16x32_bf16 v[60:63], v[210:213], v[150:153], v[60:63]
	v_mfma_f32_16x16x32_bf16 v[56:59], v[210:213], v[182:185], v[56:59]
	v_mfma_f32_16x16x32_bf16 v[48:51], v[218:221], v[150:153], v[48:51]
	v_mfma_f32_16x16x32_bf16 v[40:43], v[218:221], v[182:185], v[40:43]
	v_mfma_f32_16x16x32_bf16 v[32:35], v[226:229], v[150:153], v[32:35]
	v_mfma_f32_16x16x32_bf16 v[24:27], v[226:229], v[182:185], v[24:27]
	v_mfma_f32_16x16x32_bf16 v[16:19], v[234:237], v[150:153], v[16:19]
	v_mfma_f32_16x16x32_bf16 v[8:11], v[234:237], v[182:185], v[8:11]
	s_setprio 0
	s_setprio 1
	v_mfma_f32_16x16x32_bf16 v[52:55], v[202:205], v[186:189], v[52:55]
	v_mfma_f32_16x16x32_bf16 v[44:47], v[202:205], v[194:197], v[44:47]
	v_mfma_f32_16x16x32_bf16 v[36:39], v[214:217], v[186:189], v[36:39]
	v_mfma_f32_16x16x32_bf16 v[28:31], v[214:217], v[194:197], v[28:31]
	v_mfma_f32_16x16x32_bf16 v[20:23], v[222:225], v[186:189], v[20:23]
	v_mfma_f32_16x16x32_bf16 v[12:15], v[222:225], v[194:197], v[12:15]
	v_mfma_f32_16x16x32_bf16 v[4:7], v[230:233], v[186:189], v[4:7]
	v_mfma_f32_16x16x32_bf16 v[0:3], v[230:233], v[194:197], v[0:3]
	v_mfma_f32_16x16x32_bf16 v[52:55], v[210:213], v[190:193], v[52:55]
	v_mfma_f32_16x16x32_bf16 v[44:47], v[210:213], v[198:201], v[44:47]
	v_mfma_f32_16x16x32_bf16 v[36:39], v[218:221], v[190:193], v[36:39]
	v_mfma_f32_16x16x32_bf16 v[28:31], v[218:221], v[198:201], v[28:31]
	v_mfma_f32_16x16x32_bf16 v[20:23], v[226:229], v[190:193], v[20:23]
	v_mfma_f32_16x16x32_bf16 v[12:15], v[226:229], v[198:201], v[12:15]
	v_mfma_f32_16x16x32_bf16 v[4:7], v[234:237], v[190:193], v[4:7]
	v_mfma_f32_16x16x32_bf16 v[0:3], v[234:237], v[198:201], v[0:3]
	s_setprio 0
	s_barrier
	s_add_i32 s93, s93, 2
	s_add_u32 s14, s14, 0x100
	s_addc_u32 s15, s15, 0
	s_add_u32 s91, s91, 0x100
	s_addc_u32 s92, s92, 0
	s_cmp_gt_u32 s93, 13
	s_cbranch_scc0 .Lp2_vloop
	s_branch .Lp2_kexit

; __device__ __forceinline__ unsigned f2bf(float f) { unsigned u = __builtin_bit_cast(unsigned, f); return (u + 0x7fffu + ((u >> 16) & 1u)) >> 16; }
;     __device__ __forceinline__ void operator()(const f32x4 (&acc)[2][2][4][2], const pg8::Unit& u, int wr, int wc, int fr, int fq) const {
;     ...
;         } else if (pn < 6) {
;             const int head = 4 * (pn & 1) + wc, b = u.pm >> 3;
;             bf16_t* vb = Vt + (size_t)((b * 8 + head) * 64) * S_;
; #pragma unroll
;             for (int ai = 0; ai < 2; ++ai)
; #pragma unroll
;                 for (int m = 0; m < 4; ++m) { const int t = (row0 + ai * 128 + m * 16) & (S_ - 1);
;                     const int tp = (t & ~15) | (((t >> 2) & 1) << 3) | (((t >> 3) & 1) << 2) | (t & 3);
; #pragma unroll
;                     for (int bj = 0; bj < 2; ++bj)
; #pragma unroll
;                         for (int n = 0; n < 2; ++n) { const f32x4 a = acc[ai][bj][m][n]; const int d = 32 * bj + 8 * fq + 4 * n;
;                             vb[(unsigned)((d + 0) * S_ + tp)] = (bf16_t)f2bf(a.x); vb[(unsigned)((d + 1) * S_ + tp)] = (bf16_t)f2bf(a.y);
;                             vb[(unsigned)((d + 2) * S_ + tp)] = (bf16_t)f2bf(a.z); vb[(unsigned)((d + 3) * S_ + tp)] = (bf16_t)f2bf(a.w); }
;                 }
.LBB0_286:
	s_andn2_b64 vcc, exec, s[14:15]
	s_cbranch_vccnz .LBB0_288
	s_lshl_b32 s0, s21, 2
	s_and_b32 s0, s0, 4
	s_and_b32 s1, s20, 0x3fffff8
	s_or_b32 s0, s1, s0
	s_or_b32 s0, s0, s67
	s_lshl_b32 s14, s0, 6
	s_ashr_i32 s15, s14, 31
	s_lshl_b64 s[14:15], s[14:15], 12
	s_add_u32 s14, s65, s14
	s_addc_u32 s15, s66, s15
	s_and_b32 s0, s43, 0x7c0
	s_lshl_b32 s0, s0, 1
	v_and_b32_e32 v136, 12, v208
	v_and_b32_e32 v147, 3, v208
	v_lshlrev_b32_e32 v136, 13, v136
	v_lshl_or_b32 v136, v147, 12, v136
	v_bfe_u32 v147, v208, 4, 1
	v_lshl_or_b32 v136, v147, 4, v136
	v_bfe_u32 v147, v208, 5, 1
	v_lshl_or_b32 v136, v147, 3, v136
	v_add_u32_e32 v136, s0, v136
	v_add_u32_e32 v148, 0x4000, v136
	v_add_u32_e32 v149, 0x20000, v136
	v_add_u32_e32 v150, 0x24000, v136
	v_cvt_pk_bf16_f32 v178, v124, v125
	v_cvt_pk_bf16_f32 v179, v126, v127
	global_store_dwordx2 v136, v[178:179], s[14:15]
	v_cvt_pk_bf16_f32 v180, v120, v121
	v_cvt_pk_bf16_f32 v181, v122, v123
	global_store_dwordx2 v148, v[180:181], s[14:15]
	v_cvt_pk_bf16_f32 v182, v116, v117
	v_cvt_pk_bf16_f32 v183, v118, v119
	global_store_dwordx2 v149, v[182:183], s[14:15]
	v_cvt_pk_bf16_f32 v184, v108, v109
	v_cvt_pk_bf16_f32 v185, v110, v111
	global_store_dwordx2 v150, v[184:185], s[14:15]
	v_cvt_pk_bf16_f32 v186, v112, v113
	v_cvt_pk_bf16_f32 v187, v114, v115
	global_store_dwordx2 v136, v[186:187], s[14:15] offset:32
	v_cvt_pk_bf16_f32 v188, v104, v105
	v_cvt_pk_bf16_f32 v189, v106, v107
	global_store_dwordx2 v148, v[188:189], s[14:15] offset:32
	v_cvt_pk_bf16_f32 v190, v100, v101
	v_cvt_pk_bf16_f32 v191, v102, v103
	global_store_dwordx2 v149, v[190:191], s[14:15] offset:32
	v_cvt_pk_bf16_f32 v192, v92, v93
	v_cvt_pk_bf16_f32 v193, v94, v95
	global_store_dwordx2 v150, v[192:193], s[14:15] offset:32
	v_cvt_pk_bf16_f32 v194, v96, v97
	v_cvt_pk_bf16_f32 v195, v98, v99
	global_store_dwordx2 v136, v[194:195], s[14:15] offset:64
	v_cvt_pk_bf16_f32 v198, v88, v89
	v_cvt_pk_bf16_f32 v199, v90, v91
	global_store_dwordx2 v148, v[198:199], s[14:15] offset:64
	v_cvt_pk_bf16_f32 v200, v84, v85
	v_cvt_pk_bf16_f32 v201, v86, v87
	global_store_dwordx2 v149, v[200:201], s[14:15] offset:64
	v_cvt_pk_bf16_f32 v178, v76, v77
	v_cvt_pk_bf16_f32 v179, v78, v79
	global_store_dwordx2 v150, v[178:179], s[14:15] offset:64
	v_cvt_pk_bf16_f32 v180, v80, v81
	v_cvt_pk_bf16_f32 v181, v82, v83
	global_store_dwordx2 v136, v[180:181], s[14:15] offset:96
	v_cvt_pk_bf16_f32 v182, v72, v73
	v_cvt_pk_bf16_f32 v183, v74, v75
	global_store_dwordx2 v148, v[182:183], s[14:15] offset:96
	v_cvt_pk_bf16_f32 v184, v68, v69
	v_cvt_pk_bf16_f32 v185, v70, v71
	global_store_dwordx2 v149, v[184:185], s[14:15] offset:96
	v_cvt_pk_bf16_f32 v186, v64, v65
	v_cvt_pk_bf16_f32 v187, v66, v67
	global_store_dwordx2 v150, v[186:187], s[14:15] offset:96
	v_cvt_pk_bf16_f32 v188, v60, v61
	v_cvt_pk_bf16_f32 v189, v62, v63
	global_store_dwordx2 v136, v[188:189], s[14:15] offset:256
	v_cvt_pk_bf16_f32 v190, v56, v57
	v_cvt_pk_bf16_f32 v191, v58, v59
	global_store_dwordx2 v148, v[190:191], s[14:15] offset:256
	v_cvt_pk_bf16_f32 v192, v52, v53
	v_cvt_pk_bf16_f32 v193, v54, v55
	global_store_dwordx2 v149, v[192:193], s[14:15] offset:256
	v_cvt_pk_bf16_f32 v194, v44, v45
	v_cvt_pk_bf16_f32 v195, v46, v47
	global_store_dwordx2 v150, v[194:195], s[14:15] offset:256
	v_cvt_pk_bf16_f32 v198, v48, v49
	v_cvt_pk_bf16_f32 v199, v50, v51
	global_store_dwordx2 v136, v[198:199], s[14:15] offset:288
	v_cvt_pk_bf16_f32 v200, v40, v41
	v_cvt_pk_bf16_f32 v201, v42, v43
	global_store_dwordx2 v148, v[200:201], s[14:15] offset:288
	v_cvt_pk_bf16_f32 v178, v36, v37
	v_cvt_pk_bf16_f32 v179, v38, v39
	global_store_dwordx2 v149, v[178:179], s[14:15] offset:288
	v_cvt_pk_bf16_f32 v180, v28, v29
	v_cvt_pk_bf16_f32 v181, v30, v31
	global_store_dwordx2 v150, v[180:181], s[14:15] offset:288
	v_cvt_pk_bf16_f32 v182, v32, v33
	v_cvt_pk_bf16_f32 v183, v34, v35
	global_store_dwordx2 v136, v[182:183], s[14:15] offset:320
	v_cvt_pk_bf16_f32 v184, v24, v25
	v_cvt_pk_bf16_f32 v185, v26, v27
	global_store_dwordx2 v148, v[184:185], s[14:15] offset:320
	v_cvt_pk_bf16_f32 v186, v20, v21
	v_cvt_pk_bf16_f32 v187, v22, v23
	global_store_dwordx2 v149, v[186:187], s[14:15] offset:320
	v_cvt_pk_bf16_f32 v188, v12, v13
	v_cvt_pk_bf16_f32 v189, v14, v15
	global_store_dwordx2 v150, v[188:189], s[14:15] offset:320
	v_cvt_pk_bf16_f32 v190, v16, v17
	v_cvt_pk_bf16_f32 v191, v18, v19
	global_store_dwordx2 v136, v[190:191], s[14:15] offset:352
	v_cvt_pk_bf16_f32 v192, v8, v9
	v_cvt_pk_bf16_f32 v193, v10, v11
	global_store_dwordx2 v148, v[192:193], s[14:15] offset:352
	v_cvt_pk_bf16_f32 v194, v4, v5
	v_cvt_pk_bf16_f32 v195, v6, v7
	global_store_dwordx2 v149, v[194:195], s[14:15] offset:352
	v_cvt_pk_bf16_f32 v198, v0, v1
	v_cvt_pk_bf16_f32 v199, v2, v3
	global_store_dwordx2 v150, v[198:199], s[14:15] offset:352

; #define LAS __attribute__((address_space(3)))
;     template <bool tail> __device__ __forceinline__ void run(f32x4 (&acc)[2][2][4][2], const pg8::Unit& u, int wr, int wc, int fr_in, int fq_in) const {
;     ...
;             for (int e = 0; e < 4; ++e) { ag[e] = fr == 0 ? wg1[e] : 0.f; bgm[e] = fr < 2 ? wg0[e] : 0.f; av[e] = fr == 0 ? wv1[e] : 0.f; bvm[e] = fr < 2 ? wv0[e] : 0.f; }
; #pragma unroll
;             for (int ai = 0; ai < 2; ++ai) {
;                 const int slot = 2 * ai + wr - 1;
;                 f32x4 g14 = (f32x4){0.f, 0.f, 0.f, 0.f}, g15 = g14, v14 = g14, v15 = g14;
;                 if (slot >= 0) { const LAS float* xp = xch + (slot * 2) * 256 + colg + 4 * n;
;                     g14 = *(const LAS f32x4*)(xp); g15 = *(const LAS f32x4*)(xp + 256); v14 = *(const LAS f32x4*)(xp + 128); v15 = *(const LAS f32x4*)(xp + 256 + 128); }
;                 f32x4 pg = g14, pv = g14;
; #pragma unroll
;                 for (int m = 0; m < 4; ++m) {
;                     const int r = rbase + 128 * ai + 16 * m;
;                     if (tail) { const float* bp = bias2 + (4 * ai + 2 * wr + (m >> 1)) * (2 * DFF) + chan0 + 4 * n; bg = *(const f32x4*)(bp); bvl = *(const f32x4*)(bp + DFF); }
;                     f32x4 cg_ = acc[ai][0][m][n] * rstd[ai][m] + bg, cv_ = acc[ai][1][m][n] * rstd[ai][m] + bvl;
;                     if (ai == 0 && m == 0) { if (zfirst) { cg_ = (f32x4){0.f, 0.f, 0.f, 0.f}; cv_ = cg_; } }
;                     float o[4];
; #pragma unroll
;                     for (int e = 0; e < 4; ++e) {
;                         float G = wg2[e] * cg_[e], V = wv2[e] * cv_[e];
;                         FMAC_DPP4(G, V, cg_[e], cv_[e], wg1[e], wg0[e], wv1[e], wv0[e], "row_shr:1", "row_shr:2");
;                         if (m == 0) { const float x2g = (fr == 0) ? g14[e] : g15[e], x2v = (fr == 0) ? v14[e] : v15[e];
;                             G = __builtin_fmaf(g15[e], ag[e], G); G = __builtin_fmaf(x2g, bgm[e], G); V = __builtin_fmaf(v15[e], av[e], V); V = __builtin_fmaf(x2v, bvm[e], V); }
;                         else { FMAC_DPP4(G, V, pg[e], pv[e], ag[e], bgm[e], av[e], bvm[e], "row_ror:1", "row_ror:2"); }
;                         o[e] = G * __builtin_amdgcn_rcpf(1.f + __expf(-G)) * V;
;                     }
;                     pg = cg_; pv = cv_;
;                     bool outv; int tg;
.LBB0_584:
	s_waitcnt lgkmcnt(2)
	v_pk_add_f32 v[206:207], v[206:207], v[212:213]
	v_mov_b32_e32 v184, 0x358637bd
	v_pk_fma_f32 v[206:207], v[206:207], s[56:57], v[184:185] op_sel_hi:[1,0,0]
	s_or_b32 s0, s14, s74
	v_mul_f32_e32 v184, 0x4b800000, v207
	v_cmp_gt_f32_e64 s[14:15], s6, v207
	s_cmp_eq_u32 s0, 0
	v_cmp_gt_u32_e64 s[12:13], 2, v214
	v_cndmask_b32_e64 v184, v207, v184, s[14:15]
	v_rsq_f32_e32 v184, v184
	v_cmp_eq_u32_e64 s[10:11], 0, v214
	s_cselect_b64 s[22:23], -1, 0
	s_and_b64 s[70:71], s[22:23], s[12:13]
	v_mul_f32_e32 v190, 0x45800000, v184
	v_cndmask_b32_e64 v214, v184, v190, s[14:15]
	s_waitcnt vmcnt(1)
	v_pk_fma_f32 v[212:213], v[92:93], v[214:215], v[152:153] op_sel_hi:[1,0,1]
	v_pk_fma_f32 v[230:231], v[94:95], v[214:215], v[154:155] op_sel_hi:[1,0,1]
	s_waitcnt vmcnt(0)
	v_pk_fma_f32 v[236:237], v[88:89], v[214:215], v[156:157] op_sel_hi:[1,0,1]
	v_pk_fma_f32 v[238:239], v[90:91], v[214:215], v[158:159] op_sel_hi:[1,0,1]
	v_cndmask_b32_e64 v228, v231, 0, s[70:71]
	v_cndmask_b32_e64 v230, v230, 0, s[70:71]
	v_cndmask_b32_e64 v232, v213, 0, s[70:71]
	v_cndmask_b32_e64 v234, v212, 0, s[70:71]
	v_cndmask_b32_e64 v229, v239, 0, s[70:71]
	v_cndmask_b32_e64 v231, v238, 0, s[70:71]
	v_cndmask_b32_e64 v233, v237, 0, s[70:71]
	v_cndmask_b32_e64 v247, v236, 0, s[70:71]
	v_cmp_gt_f32_e32 vcc, s6, v206
	v_mul_f32_e32 v184, v136, v234
	v_mul_f32_e32 v212, v148, v247
	v_mul_f32_e32 v251, v137, v232
	v_mul_f32_e32 v250, v149, v233
	v_mul_f32_e32 v252, v138, v230
	v_mul_f32_e32 v253, v150, v231
	v_mul_f32_e32 v248, v139, v228
	v_mul_f32_e32 v249, v151, v229
	v_cmp_lt_u32_e64 s[14:15], 1, v221
	v_cmp_gt_u32_e64 s[22:23], 2, v221
	v_mul_lo_u32 v205, v220, s7
	s_nop 1
	v_fmac_f32_dpp v184, v234, v132 row_shr:1 row_mask:0xf bank_mask:0xf bound_ctrl:1
	v_fmac_f32_dpp v184, v234, v128 row_shr:2 row_mask:0xf bank_mask:0xf bound_ctrl:1
	v_fmac_f32_dpp v212, v247, v144 row_shr:1 row_mask:0xf bank_mask:0xf bound_ctrl:1
	v_fmac_f32_dpp v212, v247, v140 row_shr:2 row_mask:0xf bank_mask:0xf bound_ctrl:1
	v_fmac_f32_dpp v251, v232, v133 row_shr:1 row_mask:0xf bank_mask:0xf bound_ctrl:1
	v_fmac_f32_dpp v251, v232, v129 row_shr:2 row_mask:0xf bank_mask:0xf bound_ctrl:1
	v_fmac_f32_dpp v250, v233, v145 row_shr:1 row_mask:0xf bank_mask:0xf bound_ctrl:1
	v_fmac_f32_dpp v250, v233, v141 row_shr:2 row_mask:0xf bank_mask:0xf bound_ctrl:1
	v_fmac_f32_dpp v252, v230, v134 row_shr:1 row_mask:0xf bank_mask:0xf bound_ctrl:1
	v_fmac_f32_dpp v252, v230, v130 row_shr:2 row_mask:0xf bank_mask:0xf bound_ctrl:1
	v_fmac_f32_dpp v253, v231, v146 row_shr:1 row_mask:0xf bank_mask:0xf bound_ctrl:1
	v_fmac_f32_dpp v253, v231, v142 row_shr:2 row_mask:0xf bank_mask:0xf bound_ctrl:1
	v_fmac_f32_dpp v248, v228, v135 row_shr:1 row_mask:0xf bank_mask:0xf bound_ctrl:1
	v_fmac_f32_dpp v248, v228, v131 row_shr:2 row_mask:0xf bank_mask:0xf bound_ctrl:1
	v_fmac_f32_dpp v249, v229, v147 row_shr:1 row_mask:0xf bank_mask:0xf bound_ctrl:1
	v_fmac_f32_dpp v249, v229, v143 row_shr:2 row_mask:0xf bank_mask:0xf bound_ctrl:1
	s_and_saveexec_b64 s[48:49], s[22:23]
	s_xor_b64 s[22:23], exec, s[48:49]
	v_mul_lo_u32 v205, v220, s7
	s_or_saveexec_b64 s[22:23], s[22:23]
	v_cndmask_b32_e64 v243, 0, v132, s[10:11]
	v_cndmask_b32_e64 v244, 0, v128, s[12:13]
	v_cndmask_b32_e64 v245, 0, v144, s[10:11]
	v_cndmask_b32_e64 v246, 0, v140, s[12:13]
	v_cndmask_b32_e64 v239, 0, v133, s[10:11]
	v_cndmask_b32_e64 v240, 0, v129, s[12:13]
	v_cndmask_b32_e64 v241, 0, v145, s[10:11]
	v_cndmask_b32_e64 v242, 0, v141, s[12:13]
	v_cndmask_b32_e64 v235, 0, v134, s[10:11]
	v_cndmask_b32_e64 v236, 0, v130, s[12:13]
	v_cndmask_b32_e64 v237, 0, v146, s[10:11]
	v_cndmask_b32_e64 v238, 0, v142, s[12:13]
	v_cndmask_b32_e64 v207, 0, v135, s[10:11]
	v_cndmask_b32_e64 v213, 0, v131, s[12:13]
	v_cndmask_b32_e64 v221, 0, v147, s[10:11]
	v_cndmask_b32_e64 v227, 0, v143, s[12:13]
	s_xor_b64 exec, exec, s[22:23]
	s_cbranch_execz .LBB0_588
	s_waitcnt lgkmcnt(1)
	v_cndmask_b32_e64 v162, v170, v162, s[10:11]
	v_fmac_f32_e32 v252, v170, v235
	v_cndmask_b32_e64 v161, v169, v161, s[10:11]
	v_fmac_f32_e32 v251, v169, v239
	v_cndmask_b32_e64 v160, v168, v160, s[10:11]
	v_fmac_f32_e32 v184, v168, v243
	v_cndmask_b32_e64 v163, v171, v163, s[10:11]
	v_fmac_f32_e32 v248, v171, v207
	v_fmac_f32_e32 v252, v162, v236
	v_fmac_f32_e32 v251, v161, v240
	v_fmac_f32_e32 v184, v160, v244
	v_fmac_f32_e32 v248, v163, v213
	v_mul_f32_e32 v162, 0xbfb8aa3b, v252
	v_mul_f32_e32 v161, 0xbfb8aa3b, v251
	v_mul_f32_e32 v160, 0xbfb8aa3b, v184
	v_mul_f32_e32 v163, 0xbfb8aa3b, v248
	v_exp_f32_e32 v162, v162
	v_exp_f32_e32 v161, v161
	v_exp_f32_e32 v160, v160
	v_exp_f32_e32 v163, v163
	v_add_f32_e32 v162, 1.0, v162
	v_add_f32_e32 v161, 1.0, v161
	v_add_f32_e32 v160, 1.0, v160
	v_add_f32_e32 v163, 1.0, v163
	v_rcp_f32_e32 v162, v162
	v_rcp_f32_e32 v161, v161
	v_rcp_f32_e32 v160, v160
	v_rcp_f32_e32 v163, v163
	s_waitcnt lgkmcnt(0)
	v_cndmask_b32_e64 v164, v172, v164, s[10:11]
	v_fmac_f32_e32 v212, v172, v245
	v_cndmask_b32_e64 v166, v174, v166, s[10:11]
	v_fmac_f32_e32 v253, v174, v237
	v_cndmask_b32_e64 v165, v173, v165, s[10:11]
	v_fmac_f32_e32 v250, v173, v241
	v_fmac_f32_e32 v212, v164, v246
	v_cndmask_b32_e64 v164, v175, v167, s[10:11]
	v_fmac_f32_e32 v249, v175, v221
	v_fmac_f32_e32 v253, v166, v238
	v_mul_f32_e32 v162, v252, v162
	v_fmac_f32_e32 v250, v165, v242
	v_mul_f32_e32 v161, v251, v161
	v_mul_f32_e32 v160, v184, v160
	v_fmac_f32_e32 v249, v164, v227
	v_mul_f32_e32 v163, v248, v163
	v_mul_f32_e32 v162, v253, v162
	v_mul_f32_e32 v161, v250, v161
	v_mul_f32_e32 v160, v212, v160
	v_mul_f32_e32 v163, v249, v163
	v_add_u32_e32 v184, v205, v204
	v_cvt_pk_bf16_f32 v160, v160, v161
	v_cvt_pk_bf16_f32 v161, v162, v163
	v_lshl_add_u64 v[162:163], v[184:185], 1, s[38:39]
	global_store_dwordx2 v[162:163], v[160:161], off
; __device__ __forceinline__ unsigned pk2(float lo, float hi) { return pg8::cvt_pk_bf16(lo, hi); }
;     template <bool tail> __device__ __forceinline__ void run(f32x4 (&acc)[2][2][4][2], const pg8::Unit& u, int wr, int wc, int fr_in, int fq_in) const {
;     ...
; #pragma unroll
;                 for (int m = 0; m < 4; ++m) {
;                     const int r = rbase + 128 * ai + 16 * m;
;                     if (tail) { const float* bp = bias2 + (4 * ai + 2 * wr + (m >> 1)) * (2 * DFF) + chan0 + 4 * n; bg = *(const f32x4*)(bp); bvl = *(const f32x4*)(bp + DFF); }
;                     f32x4 cg_ = acc[ai][0][m][n] * rstd[ai][m] + bg, cv_ = acc[ai][1][m][n] * rstd[ai][m] + bvl;
;                     if (ai == 0 && m == 0) { if (zfirst) { cg_ = (f32x4){0.f, 0.f, 0.f, 0.f}; cv_ = cg_; } }
;                     float o[4];
; #pragma unroll
;                     for (int e = 0; e < 4; ++e) {
;                         float G = wg2[e] * cg_[e], V = wv2[e] * cv_[e];
;                         FMAC_DPP4(G, V, cg_[e], cv_[e], wg1[e], wg0[e], wv1[e], wv0[e], "row_shr:1", "row_shr:2");
;                         if (m == 0) { const float x2g = (fr == 0) ? g14[e] : g15[e], x2v = (fr == 0) ? v14[e] : v15[e];
;                             G = __builtin_fmaf(g15[e], ag[e], G); G = __builtin_fmaf(x2g, bgm[e], G); V = __builtin_fmaf(v15[e], av[e], V); V = __builtin_fmaf(x2v, bvm[e], V); }
;                         else { FMAC_DPP4(G, V, pg[e], pv[e], ag[e], bgm[e], av[e], bvm[e], "row_ror:1", "row_ror:2"); }
;                         o[e] = G * __builtin_amdgcn_rcpf(1.f + __expf(-G)) * V;
;                     }
;                     pg = cg_; pv = cv_;
;                     bool outv; int tg;
;                     if (tail) { outv = (m & 1) != 0; tg = (r >> 5) * S_ + 2016 + (r & 31); } else { outv = r >= 2; tg = tok0 + r; }
;                     if (outv) { u32x2 w; w.x = pk2(o[0], o[1]); w.y = pk2(o[2], o[3]); *(u32x2*)(act + ((unsigned)tg * DFF + chan0 + 4 * n)) = w; }
.LBB0_588:
	s_or_b64 exec, exec, s[22:23]
	v_mul_f32_e32 v160, 0x4b800000, v206
	v_cndmask_b32_e32 v160, v206, v160, vcc
	v_rsq_f32_e32 v160, v160
	v_mul_f32_e32 v161, 0x4b800000, v199
	v_cndmask_b32_e64 v161, v199, v161, s[20:21]
	v_rsq_f32_e32 v162, v161
	v_mul_f32_e32 v161, 0x45800000, v160
	v_cndmask_b32_e32 v220, v160, v161, vcc
	s_waitcnt lgkmcnt(0)
	v_pk_add_f32 v[160:161], v[200:201], v[202:203]
	v_mov_b32_e32 v164, 0x358637bd
	v_pk_fma_f32 v[160:161], v[160:161], s[56:57], v[164:165] op_sel_hi:[1,0,0]
	s_nop 0
	v_mul_f32_e32 v163, 0x4b800000, v161
	v_cmp_gt_f32_e32 vcc, s6, v161
	s_nop 1
	v_cndmask_b32_e32 v161, v161, v163, vcc
	v_mul_f32_e32 v163, 0x45800000, v162
	v_cndmask_b32_e64 v212, v162, v163, s[20:21]
	v_cmp_gt_f32_e64 s[20:21], s6, v160
	v_mul_f32_e32 v163, 0x4b800000, v160
	v_rsq_f32_e32 v161, v161
	v_cndmask_b32_e64 v160, v160, v163, s[20:21]
	v_mul_f32_e32 v163, 0x4b800000, v197
	v_rsq_f32_e32 v160, v160
	v_cndmask_b32_e64 v163, v197, v163, s[18:19]
	v_rsq_f32_e32 v163, v163
	v_mul_f32_e32 v162, 0x45800000, v161
	v_cndmask_b32_e32 v206, v161, v162, vcc
	v_mul_f32_e32 v161, 0x45800000, v160
	v_cndmask_b32_e64 v202, v160, v161, s[20:21]
	v_mul_f32_e32 v160, 0x45800000, v163
	v_cndmask_b32_e64 v200, v163, v160, s[18:19]
	v_pk_fma_f32 v[160:161], v[86:87], v[220:221], v[154:155] op_sel_hi:[1,0,1]
	v_pk_fma_f32 v[164:165], v[82:83], v[220:221], v[158:159] op_sel_hi:[1,0,1]
	v_mul_f32_e32 v172, v138, v160
	v_mul_f32_e32 v173, v150, v164
	s_nop 0
	v_fmac_f32_dpp v172, v160, v134 row_shr:1 row_mask:0xf bank_mask:0xf bound_ctrl:1
	v_fmac_f32_dpp v172, v160, v130 row_shr:2 row_mask:0xf bank_mask:0xf bound_ctrl:1
	v_fmac_f32_dpp v173, v164, v146 row_shr:1 row_mask:0xf bank_mask:0xf bound_ctrl:1
	v_fmac_f32_dpp v173, v164, v142 row_shr:2 row_mask:0xf bank_mask:0xf bound_ctrl:1
	v_pk_fma_f32 v[162:163], v[84:85], v[220:221], v[152:153] op_sel_hi:[1,0,1]
	v_fmac_f32_dpp v172, v230, v235 row_ror:1 row_mask:0xf bank_mask:0xf bound_ctrl:1
	v_fmac_f32_dpp v172, v230, v236 row_ror:2 row_mask:0xf bank_mask:0xf bound_ctrl:1
	v_fmac_f32_dpp v173, v231, v237 row_ror:1 row_mask:0xf bank_mask:0xf bound_ctrl:1
	v_fmac_f32_dpp v173, v231, v238 row_ror:2 row_mask:0xf bank_mask:0xf bound_ctrl:1
	v_pk_fma_f32 v[166:167], v[80:81], v[220:221], v[156:157] op_sel_hi:[1,0,1]
	v_mul_f32_e32 v174, 0xbfb8aa3b, v172
	v_exp_f32_e32 v174, v174
	v_mul_f32_e32 v170, v137, v163
	v_mul_f32_e32 v171, v149, v167
	s_nop 0
	v_fmac_f32_dpp v170, v163, v133 row_shr:1 row_mask:0xf bank_mask:0xf bound_ctrl:1
	v_fmac_f32_dpp v170, v163, v129 row_shr:2 row_mask:0xf bank_mask:0xf bound_ctrl:1
	v_fmac_f32_dpp v171, v167, v145 row_shr:1 row_mask:0xf bank_mask:0xf bound_ctrl:1
	v_fmac_f32_dpp v171, v167, v141 row_shr:2 row_mask:0xf bank_mask:0xf bound_ctrl:1
	v_add_f32_e32 v174, 1.0, v174
	v_fmac_f32_dpp v170, v232, v239 row_ror:1 row_mask:0xf bank_mask:0xf bound_ctrl:1
	v_fmac_f32_dpp v170, v232, v240 row_ror:2 row_mask:0xf bank_mask:0xf bound_ctrl:1
	v_fmac_f32_dpp v171, v233, v241 row_ror:1 row_mask:0xf bank_mask:0xf bound_ctrl:1
	v_fmac_f32_dpp v171, v233, v242 row_ror:2 row_mask:0xf bank_mask:0xf bound_ctrl:1
	v_rcp_f32_e32 v174, v174
	v_mul_f32_e32 v190, 0xbfb8aa3b, v170
	v_exp_f32_e32 v190, v190
	v_mul_f32_e32 v168, v136, v162
	v_mul_f32_e32 v169, v148, v166
	s_nop 0
	v_fmac_f32_dpp v168, v162, v132 row_shr:1 row_mask:0xf bank_mask:0xf bound_ctrl:1
	v_fmac_f32_dpp v168, v162, v128 row_shr:2 row_mask:0xf bank_mask:0xf bound_ctrl:1
	v_fmac_f32_dpp v169, v166, v144 row_shr:1 row_mask:0xf bank_mask:0xf bound_ctrl:1
	v_fmac_f32_dpp v169, v166, v140 row_shr:2 row_mask:0xf bank_mask:0xf bound_ctrl:1
	v_mul_f32_e32 v175, v139, v161
	v_mul_f32_e32 v184, v151, v165
	v_mul_f32_e32 v172, v172, v174
	v_fmac_f32_dpp v168, v234, v243 row_ror:1 row_mask:0xf bank_mask:0xf bound_ctrl:1
	v_fmac_f32_dpp v168, v234, v244 row_ror:2 row_mask:0xf bank_mask:0xf bound_ctrl:1
	v_fmac_f32_dpp v169, v247, v245 row_ror:1 row_mask:0xf bank_mask:0xf bound_ctrl:1
	v_fmac_f32_dpp v169, v247, v246 row_ror:2 row_mask:0xf bank_mask:0xf bound_ctrl:1
	v_fmac_f32_dpp v175, v161, v135 row_shr:1 row_mask:0xf bank_mask:0xf bound_ctrl:1
	v_fmac_f32_dpp v175, v161, v131 row_shr:2 row_mask:0xf bank_mask:0xf bound_ctrl:1
	v_fmac_f32_dpp v184, v165, v147 row_shr:1 row_mask:0xf bank_mask:0xf bound_ctrl:1
	v_fmac_f32_dpp v184, v165, v143 row_shr:2 row_mask:0xf bank_mask:0xf bound_ctrl:1
	v_mul_f32_e32 v172, v173, v172
	v_add_f32_e32 v173, 1.0, v190
	v_mul_f32_e32 v174, 0xbfb8aa3b, v168
	v_fmac_f32_dpp v175, v228, v207 row_ror:1 row_mask:0xf bank_mask:0xf bound_ctrl:1
	v_fmac_f32_dpp v175, v228, v213 row_ror:2 row_mask:0xf bank_mask:0xf bound_ctrl:1
	v_fmac_f32_dpp v184, v229, v221 row_ror:1 row_mask:0xf bank_mask:0xf bound_ctrl:1
	v_fmac_f32_dpp v184, v229, v227 row_ror:2 row_mask:0xf bank_mask:0xf bound_ctrl:1
	v_rcp_f32_e32 v173, v173
	v_exp_f32_e32 v174, v174
	v_mul_f32_e32 v190, 0xbfb8aa3b, v175
	v_exp_f32_e32 v190, v190
	v_mul_f32_e32 v170, v170, v173
	v_add_f32_e32 v173, 1.0, v174
	v_rcp_f32_e32 v173, v173
	v_add_f32_e32 v174, 1.0, v190
	v_rcp_f32_e32 v174, v174
	v_add_u32_e32 v234, 0xb000, v205
	v_mul_f32_e32 v168, v168, v173
	v_mul_f32_e32 v168, v169, v168
	v_mul_f32_e32 v169, v175, v174
	v_mul_f32_e32 v170, v171, v170
	v_mul_f32_e32 v169, v184, v169
	v_add_u32_e32 v184, v204, v234
	v_cvt_pk_bf16_f32 v168, v168, v170
	v_lshl_add_u64 v[170:171], v[184:185], 1, s[38:39]
	v_cvt_pk_bf16_f32 v169, v172, v169
	global_store_dwordx2 v[170:171], v[168:169], off
	v_pk_fma_f32 v[170:171], v[76:77], v[212:213], v[152:153] op_sel_hi:[1,0,1]
	v_pk_fma_f32 v[174:175], v[72:73], v[212:213], v[156:157] op_sel_hi:[1,0,1]
; __device__ __forceinline__ unsigned pk2(float lo, float hi) { return pg8::cvt_pk_bf16(lo, hi); }
;     template <bool tail> __device__ __forceinline__ void run(f32x4 (&acc)[2][2][4][2], const pg8::Unit& u, int wr, int wc, int fr_in, int fq_in) const {
;     ...
; #pragma unroll
;                 for (int m = 0; m < 4; ++m) {
;                     const int r = rbase + 128 * ai + 16 * m;
;                     if (tail) { const float* bp = bias2 + (4 * ai + 2 * wr + (m >> 1)) * (2 * DFF) + chan0 + 4 * n; bg = *(const f32x4*)(bp); bvl = *(const f32x4*)(bp + DFF); }
;                     f32x4 cg_ = acc[ai][0][m][n] * rstd[ai][m] + bg, cv_ = acc[ai][1][m][n] * rstd[ai][m] + bvl;
;                     if (ai == 0 && m == 0) { if (zfirst) { cg_ = (f32x4){0.f, 0.f, 0.f, 0.f}; cv_ = cg_; } }
;                     float o[4];
; #pragma unroll
;                     for (int e = 0; e < 4; ++e) {
;                         float G = wg2[e] * cg_[e], V = wv2[e] * cv_[e];
;                         FMAC_DPP4(G, V, cg_[e], cv_[e], wg1[e], wg0[e], wv1[e], wv0[e], "row_shr:1", "row_shr:2");
;                         if (m == 0) { const float x2g = (fr == 0) ? g14[e] : g15[e], x2v = (fr == 0) ? v14[e] : v15[e];
;                             G = __builtin_fmaf(g15[e], ag[e], G); G = __builtin_fmaf(x2g, bgm[e], G); V = __builtin_fmaf(v15[e], av[e], V); V = __builtin_fmaf(x2v, bvm[e], V); }
;                         else { FMAC_DPP4(G, V, pg[e], pv[e], ag[e], bgm[e], av[e], bvm[e], "row_ror:1", "row_ror:2"); }
;                         o[e] = G * __builtin_amdgcn_rcpf(1.f + __expf(-G)) * V;
;                     }
;                     pg = cg_; pv = cv_;
;                     bool outv; int tg;
;                     if (tail) { outv = (m & 1) != 0; tg = (r >> 5) * S_ + 2016 + (r & 31); } else { outv = r >= 2; tg = tok0 + r; }
;                     if (outv) { u32x2 w; w.x = pk2(o[0], o[1]); w.y = pk2(o[2], o[3]); *(u32x2*)(act + ((unsigned)tg * DFF + chan0 + 4 * n)) = w; }
	v_mul_f32_e32 v184, v136, v170
	v_mul_f32_e32 v190, v148, v174
	s_nop 0
	v_fmac_f32_dpp v184, v170, v132 row_shr:1 row_mask:0xf bank_mask:0xf bound_ctrl:1
	v_fmac_f32_dpp v184, v170, v128 row_shr:2 row_mask:0xf bank_mask:0xf bound_ctrl:1
	v_fmac_f32_dpp v190, v174, v144 row_shr:1 row_mask:0xf bank_mask:0xf bound_ctrl:1
	v_fmac_f32_dpp v190, v174, v140 row_shr:2 row_mask:0xf bank_mask:0xf bound_ctrl:1
	v_pk_fma_f32 v[168:169], v[78:79], v[212:213], v[154:155] op_sel_hi:[1,0,1]
	v_fmac_f32_dpp v184, v162, v243 row_ror:1 row_mask:0xf bank_mask:0xf bound_ctrl:1
	v_fmac_f32_dpp v184, v162, v244 row_ror:2 row_mask:0xf bank_mask:0xf bound_ctrl:1
	v_fmac_f32_dpp v190, v166, v245 row_ror:1 row_mask:0xf bank_mask:0xf bound_ctrl:1
	v_fmac_f32_dpp v190, v166, v246 row_ror:2 row_mask:0xf bank_mask:0xf bound_ctrl:1
	v_mul_f32_e32 v162, v137, v171
	v_mul_f32_e32 v166, v149, v175
	v_pk_fma_f32 v[172:173], v[74:75], v[212:213], v[158:159] op_sel_hi:[1,0,1]
	v_fmac_f32_dpp v162, v171, v133 row_shr:1 row_mask:0xf bank_mask:0xf bound_ctrl:1
	v_fmac_f32_dpp v162, v171, v129 row_shr:2 row_mask:0xf bank_mask:0xf bound_ctrl:1
	v_fmac_f32_dpp v166, v175, v145 row_shr:1 row_mask:0xf bank_mask:0xf bound_ctrl:1
	v_fmac_f32_dpp v166, v175, v141 row_shr:2 row_mask:0xf bank_mask:0xf bound_ctrl:1
	v_add_u32_e32 v233, 0x16000, v205
	v_fmac_f32_dpp v162, v163, v239 row_ror:1 row_mask:0xf bank_mask:0xf bound_ctrl:1
	v_fmac_f32_dpp v162, v163, v240 row_ror:2 row_mask:0xf bank_mask:0xf bound_ctrl:1
	v_fmac_f32_dpp v166, v167, v241 row_ror:1 row_mask:0xf bank_mask:0xf bound_ctrl:1
	v_fmac_f32_dpp v166, v167, v242 row_ror:2 row_mask:0xf bank_mask:0xf bound_ctrl:1
	v_mul_f32_e32 v163, v138, v168
	v_mul_f32_e32 v167, v150, v172
	s_nop 0
	v_fmac_f32_dpp v163, v168, v134 row_shr:1 row_mask:0xf bank_mask:0xf bound_ctrl:1
	v_fmac_f32_dpp v163, v168, v130 row_shr:2 row_mask:0xf bank_mask:0xf bound_ctrl:1
	v_fmac_f32_dpp v167, v172, v146 row_shr:1 row_mask:0xf bank_mask:0xf bound_ctrl:1
	v_fmac_f32_dpp v167, v172, v142 row_shr:2 row_mask:0xf bank_mask:0xf bound_ctrl:1
	v_mul_f32_e32 v197, 0xbfb8aa3b, v162
	v_fmac_f32_dpp v163, v160, v235 row_ror:1 row_mask:0xf bank_mask:0xf bound_ctrl:1
	v_fmac_f32_dpp v163, v160, v236 row_ror:2 row_mask:0xf bank_mask:0xf bound_ctrl:1
	v_fmac_f32_dpp v167, v164, v237 row_ror:1 row_mask:0xf bank_mask:0xf bound_ctrl:1
	v_fmac_f32_dpp v167, v164, v238 row_ror:2 row_mask:0xf bank_mask:0xf bound_ctrl:1
	v_exp_f32_e32 v197, v197
	v_mul_f32_e32 v160, 0xbfb8aa3b, v163
	v_exp_f32_e32 v160, v160
	v_mul_f32_e32 v164, v139, v169
	v_mul_f32_e32 v191, v151, v173
	s_nop 0
	v_fmac_f32_dpp v164, v169, v135 row_shr:1 row_mask:0xf bank_mask:0xf bound_ctrl:1
	v_fmac_f32_dpp v164, v169, v131 row_shr:2 row_mask:0xf bank_mask:0xf bound_ctrl:1
	v_fmac_f32_dpp v191, v173, v147 row_shr:1 row_mask:0xf bank_mask:0xf bound_ctrl:1
	v_fmac_f32_dpp v191, v173, v143 row_shr:2 row_mask:0xf bank_mask:0xf bound_ctrl:1
	v_add_f32_e32 v160, 1.0, v160
	v_rcp_f32_e32 v160, v160
	v_fmac_f32_dpp v164, v161, v207 row_ror:1 row_mask:0xf bank_mask:0xf bound_ctrl:1
	v_fmac_f32_dpp v164, v161, v213 row_ror:2 row_mask:0xf bank_mask:0xf bound_ctrl:1
	v_fmac_f32_dpp v191, v165, v221 row_ror:1 row_mask:0xf bank_mask:0xf bound_ctrl:1
	v_fmac_f32_dpp v191, v165, v227 row_ror:2 row_mask:0xf bank_mask:0xf bound_ctrl:1
	s_nop 0
	v_mul_f32_e32 v165, 0xbfb8aa3b, v164
	v_mul_f32_e32 v160, v163, v160
	v_mul_f32_e32 v161, v167, v160
	v_add_f32_e32 v160, 1.0, v197
	v_mul_f32_e32 v163, 0xbfb8aa3b, v184
	v_rcp_f32_e32 v160, v160
	v_exp_f32_e32 v163, v163
	v_exp_f32_e32 v165, v165
	v_mul_f32_e32 v160, v162, v160
	v_add_f32_e32 v162, 1.0, v163
	v_add_f32_e32 v163, 1.0, v165
	v_rcp_f32_e32 v162, v162
	v_rcp_f32_e32 v163, v163
	v_mul_f32_e32 v160, v166, v160
	v_mul_f32_e32 v162, v184, v162
	v_mul_f32_e32 v163, v164, v163
	v_mul_f32_e32 v162, v190, v162
	v_mul_f32_e32 v163, v191, v163
	v_add_u32_e32 v184, v204, v233
	v_cvt_pk_bf16_f32 v160, v162, v160
	v_cvt_pk_bf16_f32 v161, v161, v163
	v_lshl_add_u64 v[162:163], v[184:185], 1, s[38:39]
	global_store_dwordx2 v[162:163], v[160:161], off
	v_pk_fma_f32 v[162:163], v[124:125], v[198:199], v[152:153] op_sel_hi:[1,0,1]
	v_pk_fma_f32 v[166:167], v[116:117], v[198:199], v[156:157] op_sel_hi:[1,0,1]
	v_mul_f32_e32 v184, v136, v162
	v_mul_f32_e32 v190, v148, v166
	v_pk_fma_f32 v[160:161], v[126:127], v[198:199], v[154:155] op_sel_hi:[1,0,1]
	v_pk_fma_f32 v[164:165], v[118:119], v[198:199], v[158:159] op_sel_hi:[1,0,1]
	v_fmac_f32_dpp v184, v162, v132 row_shr:1 row_mask:0xf bank_mask:0xf bound_ctrl:1
	v_fmac_f32_dpp v184, v162, v128 row_shr:2 row_mask:0xf bank_mask:0xf bound_ctrl:1
	v_fmac_f32_dpp v190, v166, v144 row_shr:1 row_mask:0xf bank_mask:0xf bound_ctrl:1
	v_fmac_f32_dpp v190, v166, v140 row_shr:2 row_mask:0xf bank_mask:0xf bound_ctrl:1
	v_mul_f32_e32 v162, v137, v163
	v_mul_f32_e32 v166, v149, v167
	s_nop 0
	v_fmac_f32_dpp v162, v163, v133 row_shr:1 row_mask:0xf bank_mask:0xf bound_ctrl:1
	v_fmac_f32_dpp v162, v163, v129 row_shr:2 row_mask:0xf bank_mask:0xf bound_ctrl:1
	v_fmac_f32_dpp v166, v167, v145 row_shr:1 row_mask:0xf bank_mask:0xf bound_ctrl:1
	v_fmac_f32_dpp v166, v167, v141 row_shr:2 row_mask:0xf bank_mask:0xf bound_ctrl:1
	v_mul_f32_e32 v163, v138, v160
	v_mul_f32_e32 v167, v150, v164
	s_nop 0
	v_fmac_f32_dpp v163, v160, v134 row_shr:1 row_mask:0xf bank_mask:0xf bound_ctrl:1
	v_fmac_f32_dpp v163, v160, v130 row_shr:2 row_mask:0xf bank_mask:0xf bound_ctrl:1
	v_fmac_f32_dpp v167, v164, v146 row_shr:1 row_mask:0xf bank_mask:0xf bound_ctrl:1
	v_fmac_f32_dpp v167, v164, v142 row_shr:2 row_mask:0xf bank_mask:0xf bound_ctrl:1
	v_mul_f32_e32 v164, v139, v161
; #define LAS __attribute__((address_space(3)))
; __device__ __forceinline__ unsigned pk2(float lo, float hi) { return pg8::cvt_pk_bf16(lo, hi); }
;     template <bool tail> __device__ __forceinline__ void run(f32x4 (&acc)[2][2][4][2], const pg8::Unit& u, int wr, int wc, int fr_in, int fq_in) const {
;     ...
;                 if (slot >= 0) { const LAS float* xp = xch + (slot * 2) * 256 + colg + 4 * n;
;                     g14 = *(const LAS f32x4*)(xp); g15 = *(const LAS f32x4*)(xp + 256); v14 = *(const LAS f32x4*)(xp + 128); v15 = *(const LAS f32x4*)(xp + 256 + 128); }
;                 f32x4 pg = g14, pv = g14;
; #pragma unroll
;                 for (int m = 0; m < 4; ++m) {
;                     const int r = rbase + 128 * ai + 16 * m;
;                     if (tail) { const float* bp = bias2 + (4 * ai + 2 * wr + (m >> 1)) * (2 * DFF) + chan0 + 4 * n; bg = *(const f32x4*)(bp); bvl = *(const f32x4*)(bp + DFF); }
;                     f32x4 cg_ = acc[ai][0][m][n] * rstd[ai][m] + bg, cv_ = acc[ai][1][m][n] * rstd[ai][m] + bvl;
;                     if (ai == 0 && m == 0) { if (zfirst) { cg_ = (f32x4){0.f, 0.f, 0.f, 0.f}; cv_ = cg_; } }
;                     float o[4];
; #pragma unroll
;                     for (int e = 0; e < 4; ++e) {
;                         float G = wg2[e] * cg_[e], V = wv2[e] * cv_[e];
;                         FMAC_DPP4(G, V, cg_[e], cv_[e], wg1[e], wg0[e], wv1[e], wv0[e], "row_shr:1", "row_shr:2");
;                         if (m == 0) { const float x2g = (fr == 0) ? g14[e] : g15[e], x2v = (fr == 0) ? v14[e] : v15[e];
;                             G = __builtin_fmaf(g15[e], ag[e], G); G = __builtin_fmaf(x2g, bgm[e], G); V = __builtin_fmaf(v15[e], av[e], V); V = __builtin_fmaf(x2v, bvm[e], V); }
;                         else { FMAC_DPP4(G, V, pg[e], pv[e], ag[e], bgm[e], av[e], bvm[e], "row_ror:1", "row_ror:2"); }
;                         o[e] = G * __builtin_amdgcn_rcpf(1.f + __expf(-G)) * V;
;                     }
;                     pg = cg_; pv = cv_;
;                     bool outv; int tg;
;                     if (tail) { outv = (m & 1) != 0; tg = (r >> 5) * S_ + 2016 + (r & 31); } else { outv = r >= 2; tg = tok0 + r; }
;                     if (outv) { u32x2 w; w.x = pk2(o[0], o[1]); w.y = pk2(o[2], o[3]); *(u32x2*)(act + ((unsigned)tg * DFF + chan0 + 4 * n)) = w; }
	v_fmac_f32_dpp v163, v168, v235 row_ror:1 row_mask:0xf bank_mask:0xf bound_ctrl:1
	v_fmac_f32_dpp v163, v168, v236 row_ror:2 row_mask:0xf bank_mask:0xf bound_ctrl:1
	v_fmac_f32_dpp v167, v172, v237 row_ror:1 row_mask:0xf bank_mask:0xf bound_ctrl:1
	v_fmac_f32_dpp v167, v172, v238 row_ror:2 row_mask:0xf bank_mask:0xf bound_ctrl:1
	v_mul_f32_e32 v168, v151, v165
	v_mul_f32_e32 v160, 0xbfb8aa3b, v163
	v_exp_f32_e32 v160, v160
	v_fmac_f32_dpp v162, v171, v239 row_ror:1 row_mask:0xf bank_mask:0xf bound_ctrl:1
	v_fmac_f32_dpp v162, v171, v240 row_ror:2 row_mask:0xf bank_mask:0xf bound_ctrl:1
	v_fmac_f32_dpp v166, v175, v241 row_ror:1 row_mask:0xf bank_mask:0xf bound_ctrl:1
	v_fmac_f32_dpp v166, v175, v242 row_ror:2 row_mask:0xf bank_mask:0xf bound_ctrl:1
	v_fmac_f32_dpp v164, v161, v135 row_shr:1 row_mask:0xf bank_mask:0xf bound_ctrl:1
	v_fmac_f32_dpp v164, v161, v131 row_shr:2 row_mask:0xf bank_mask:0xf bound_ctrl:1
	v_fmac_f32_dpp v168, v165, v147 row_shr:1 row_mask:0xf bank_mask:0xf bound_ctrl:1
	v_fmac_f32_dpp v168, v165, v143 row_shr:2 row_mask:0xf bank_mask:0xf bound_ctrl:1
	v_fmac_f32_dpp v184, v170, v243 row_ror:1 row_mask:0xf bank_mask:0xf bound_ctrl:1
	v_fmac_f32_dpp v184, v170, v244 row_ror:2 row_mask:0xf bank_mask:0xf bound_ctrl:1
	v_fmac_f32_dpp v190, v174, v245 row_ror:1 row_mask:0xf bank_mask:0xf bound_ctrl:1
	v_fmac_f32_dpp v190, v174, v246 row_ror:2 row_mask:0xf bank_mask:0xf bound_ctrl:1
	v_add_u32_e32 v231, 0x21000, v205
	v_add_f32_e32 v160, 1.0, v160
	v_rcp_f32_e32 v160, v160
	v_mul_f32_e32 v161, 0xbfb8aa3b, v162
	v_exp_f32_e32 v161, v161
	v_fmac_f32_dpp v164, v169, v207 row_ror:1 row_mask:0xf bank_mask:0xf bound_ctrl:1
	v_fmac_f32_dpp v164, v169, v213 row_ror:2 row_mask:0xf bank_mask:0xf bound_ctrl:1
	v_fmac_f32_dpp v168, v173, v221 row_ror:1 row_mask:0xf bank_mask:0xf bound_ctrl:1
	v_fmac_f32_dpp v168, v173, v227 row_ror:2 row_mask:0xf bank_mask:0xf bound_ctrl:1
	v_mul_f32_e32 v160, v163, v160
	v_mul_f32_e32 v163, v167, v160
	v_add_f32_e32 v160, 1.0, v161
	v_mul_f32_e32 v161, 0xbfb8aa3b, v184
	v_mul_f32_e32 v165, 0xbfb8aa3b, v164
	v_rcp_f32_e32 v160, v160
	v_exp_f32_e32 v161, v161
	v_exp_f32_e32 v165, v165
	v_mul_f32_e32 v160, v162, v160
	v_add_f32_e32 v161, 1.0, v161
	v_add_f32_e32 v162, 1.0, v165
	v_rcp_f32_e32 v161, v161
	v_rcp_f32_e32 v162, v162
	v_mul_f32_e32 v160, v166, v160
	v_mul_f32_e32 v161, v184, v161
	v_mul_f32_e32 v162, v164, v162
	v_mul_f32_e32 v161, v190, v161
	v_mul_f32_e32 v162, v168, v162
	v_add_u32_e32 v184, v204, v231
	v_cvt_pk_bf16_f32 v160, v161, v160
	v_cvt_pk_bf16_f32 v161, v163, v162
	v_lshl_add_u64 v[162:163], v[184:185], 1, s[38:39]
	global_store_dwordx2 v[162:163], v[160:161], off
	v_lshl_add_u32 v230, v215, 2, s95
	ds_read_b128 v[160:163], v230 offset:3584
	ds_read_b128 v[164:167], v230 offset:3072
	ds_read_b128 v[168:171], v230 offset:2560
	ds_read_b128 v[172:175], v230 offset:2048
	v_pk_fma_f32 v[228:229], v[70:71], v[206:207], v[154:155] op_sel_hi:[1,0,1]
	v_pk_fma_f32 v[250:251], v[66:67], v[206:207], v[158:159] op_sel_hi:[1,0,1]
	v_mul_f32_e32 v199, v138, v228
	v_mul_f32_e32 v201, v150, v250
	s_nop 0
	v_fmac_f32_dpp v199, v228, v134 row_shr:1 row_mask:0xf bank_mask:0xf bound_ctrl:1
	v_fmac_f32_dpp v199, v228, v130 row_shr:2 row_mask:0xf bank_mask:0xf bound_ctrl:1
	v_fmac_f32_dpp v201, v250, v146 row_shr:1 row_mask:0xf bank_mask:0xf bound_ctrl:1
	v_fmac_f32_dpp v201, v250, v142 row_shr:2 row_mask:0xf bank_mask:0xf bound_ctrl:1
	s_waitcnt lgkmcnt(0)
	v_cndmask_b32_e64 v174, v166, v174, s[10:11]
	v_fmac_f32_e32 v199, v166, v235
	v_fmac_f32_e32 v199, v174, v236
	v_mul_f32_e32 v166, 0xbfb8aa3b, v199
	v_exp_f32_e32 v166, v166
	v_pk_fma_f32 v[248:249], v[68:69], v[206:207], v[152:153] op_sel_hi:[1,0,1]
	v_pk_fma_f32 v[252:253], v[64:65], v[206:207], v[156:157] op_sel_hi:[1,0,1]
	v_mul_f32_e32 v191, v137, v249
	v_mul_f32_e32 v197, v149, v253
	s_nop 0
	v_fmac_f32_dpp v191, v249, v133 row_shr:1 row_mask:0xf bank_mask:0xf bound_ctrl:1
	v_fmac_f32_dpp v191, v249, v129 row_shr:2 row_mask:0xf bank_mask:0xf bound_ctrl:1
	v_fmac_f32_dpp v197, v253, v145 row_shr:1 row_mask:0xf bank_mask:0xf bound_ctrl:1
	v_fmac_f32_dpp v197, v253, v141 row_shr:2 row_mask:0xf bank_mask:0xf bound_ctrl:1
	v_cndmask_b32_e64 v170, v162, v170, s[10:11]
	v_fmac_f32_e32 v201, v162, v237
	v_add_f32_e32 v162, 1.0, v166
	v_cndmask_b32_e64 v166, v165, v173, s[10:11]
	v_fmac_f32_e32 v191, v165, v239
	v_fmac_f32_e32 v191, v166, v240
	v_mul_f32_e32 v165, 0xbfb8aa3b, v191
	v_exp_f32_e32 v165, v165
	v_mul_f32_e32 v184, v136, v248
	v_mul_f32_e32 v190, v148, v252
	s_nop 0
	v_fmac_f32_dpp v184, v248, v132 row_shr:1 row_mask:0xf bank_mask:0xf bound_ctrl:1
	v_fmac_f32_dpp v184, v248, v128 row_shr:2 row_mask:0xf bank_mask:0xf bound_ctrl:1
	v_fmac_f32_dpp v190, v252, v144 row_shr:1 row_mask:0xf bank_mask:0xf bound_ctrl:1
	v_fmac_f32_dpp v190, v252, v140 row_shr:2 row_mask:0xf bank_mask:0xf bound_ctrl:1
	v_add_f32_e32 v165, 1.0, v165
	v_rcp_f32_e32 v165, v165
	v_cndmask_b32_e64 v166, v161, v169, s[10:11]
	v_fmac_f32_e32 v197, v161, v241
	v_fmac_f32_e32 v184, v164, v243
	v_mul_f32_e32 v161, v191, v165
	v_cndmask_b32_e64 v165, v164, v172, s[10:11]
	v_fmac_f32_e32 v184, v165, v244
	v_mul_f32_e32 v164, 0xbfb8aa3b, v184
	v_exp_f32_e32 v164, v164
	v_mul_f32_e32 v203, v139, v229
	v_mul_f32_e32 v215, v151, v251
	s_nop 0
	v_fmac_f32_dpp v203, v229, v135 row_shr:1 row_mask:0xf bank_mask:0xf bound_ctrl:1
	v_fmac_f32_dpp v203, v229, v131 row_shr:2 row_mask:0xf bank_mask:0xf bound_ctrl:1
	v_fmac_f32_dpp v215, v251, v147 row_shr:1 row_mask:0xf bank_mask:0xf bound_ctrl:1
	v_fmac_f32_dpp v215, v251, v143 row_shr:2 row_mask:0xf bank_mask:0xf bound_ctrl:1
; __device__ __forceinline__ unsigned pk2(float lo, float hi) { return pg8::cvt_pk_bf16(lo, hi); }
;     template <bool tail> __device__ __forceinline__ void run(f32x4 (&acc)[2][2][4][2], const pg8::Unit& u, int wr, int wc, int fr_in, int fq_in) const {
;     ...
; #pragma unroll
;                 for (int m = 0; m < 4; ++m) {
;                     const int r = rbase + 128 * ai + 16 * m;
;                     if (tail) { const float* bp = bias2 + (4 * ai + 2 * wr + (m >> 1)) * (2 * DFF) + chan0 + 4 * n; bg = *(const f32x4*)(bp); bvl = *(const f32x4*)(bp + DFF); }
;                     f32x4 cg_ = acc[ai][0][m][n] * rstd[ai][m] + bg, cv_ = acc[ai][1][m][n] * rstd[ai][m] + bvl;
;                     if (ai == 0 && m == 0) { if (zfirst) { cg_ = (f32x4){0.f, 0.f, 0.f, 0.f}; cv_ = cg_; } }
;                     float o[4];
; #pragma unroll
;                     for (int e = 0; e < 4; ++e) {
;                         float G = wg2[e] * cg_[e], V = wv2[e] * cv_[e];
;                         FMAC_DPP4(G, V, cg_[e], cv_[e], wg1[e], wg0[e], wv1[e], wv0[e], "row_shr:1", "row_shr:2");
;                         if (m == 0) { const float x2g = (fr == 0) ? g14[e] : g15[e], x2v = (fr == 0) ? v14[e] : v15[e];
;                             G = __builtin_fmaf(g15[e], ag[e], G); G = __builtin_fmaf(x2g, bgm[e], G); V = __builtin_fmaf(v15[e], av[e], V); V = __builtin_fmaf(x2v, bvm[e], V); }
;                         else { FMAC_DPP4(G, V, pg[e], pv[e], ag[e], bgm[e], av[e], bvm[e], "row_ror:1", "row_ror:2"); }
;                         o[e] = G * __builtin_amdgcn_rcpf(1.f + __expf(-G)) * V;
;                     }
;                     pg = cg_; pv = cv_;
;                     bool outv; int tg;
;                     if (tail) { outv = (m & 1) != 0; tg = (r >> 5) * S_ + 2016 + (r & 31); } else { outv = r >= 2; tg = tok0 + r; }
;                     if (outv) { u32x2 w; w.x = pk2(o[0], o[1]); w.y = pk2(o[2], o[3]); *(u32x2*)(act + ((unsigned)tg * DFF + chan0 + 4 * n)) = w; }
	v_cndmask_b32_e64 v165, v160, v168, s[10:11]
	v_fmac_f32_e32 v190, v160, v245
	v_add_f32_e32 v160, 1.0, v164
	v_cndmask_b32_e64 v164, v167, v175, s[10:11]
	v_fmac_f32_e32 v203, v167, v207
	v_fmac_f32_e32 v203, v164, v213
	v_mul_f32_e32 v164, 0xbfb8aa3b, v203
	v_exp_f32_e32 v164, v164
	v_rcp_f32_e32 v162, v162
	v_rcp_f32_e32 v160, v160
	v_fmac_f32_e32 v190, v165, v246
	v_add_f32_e32 v164, 1.0, v164
	v_rcp_f32_e32 v164, v164
	v_cndmask_b32_e64 v165, v163, v171, s[10:11]
	v_fmac_f32_e32 v215, v163, v221
	v_fmac_f32_e32 v201, v170, v238
	v_mul_f32_e32 v162, v199, v162
	v_fmac_f32_e32 v197, v166, v242
	v_mul_f32_e32 v160, v184, v160
	v_fmac_f32_e32 v215, v165, v227
	v_mul_f32_e32 v163, v203, v164
	v_add_u32_e32 v232, 0x58000, v205
	v_mul_f32_e32 v162, v201, v162
	v_mul_f32_e32 v161, v197, v161
	v_mul_f32_e32 v160, v190, v160
	v_mul_f32_e32 v163, v215, v163
	v_add_u32_e32 v184, v232, v204
	v_cvt_pk_bf16_f32 v160, v160, v161
	v_cvt_pk_bf16_f32 v161, v162, v163
	v_lshl_add_u64 v[162:163], v[184:185], 1, s[38:39]
	global_store_dwordx2 v[162:163], v[160:161], off
	v_pk_fma_f32 v[160:161], v[62:63], v[202:203], v[154:155] op_sel_hi:[1,0,1]
	v_pk_fma_f32 v[164:165], v[58:59], v[202:203], v[158:159] op_sel_hi:[1,0,1]
	v_mul_f32_e32 v172, v138, v160
	v_mul_f32_e32 v173, v150, v164
	s_nop 0
	v_fmac_f32_dpp v172, v160, v134 row_shr:1 row_mask:0xf bank_mask:0xf bound_ctrl:1
	v_fmac_f32_dpp v172, v160, v130 row_shr:2 row_mask:0xf bank_mask:0xf bound_ctrl:1
	v_fmac_f32_dpp v173, v164, v146 row_shr:1 row_mask:0xf bank_mask:0xf bound_ctrl:1
	v_fmac_f32_dpp v173, v164, v142 row_shr:2 row_mask:0xf bank_mask:0xf bound_ctrl:1
	v_pk_fma_f32 v[162:163], v[60:61], v[202:203], v[152:153] op_sel_hi:[1,0,1]
	v_fmac_f32_dpp v172, v228, v235 row_ror:1 row_mask:0xf bank_mask:0xf bound_ctrl:1
	v_fmac_f32_dpp v172, v228, v236 row_ror:2 row_mask:0xf bank_mask:0xf bound_ctrl:1
	v_fmac_f32_dpp v173, v250, v237 row_ror:1 row_mask:0xf bank_mask:0xf bound_ctrl:1
	v_fmac_f32_dpp v173, v250, v238 row_ror:2 row_mask:0xf bank_mask:0xf bound_ctrl:1
	v_pk_fma_f32 v[166:167], v[56:57], v[202:203], v[156:157] op_sel_hi:[1,0,1]
	v_mul_f32_e32 v174, 0xbfb8aa3b, v172
	v_exp_f32_e32 v174, v174
	v_mul_f32_e32 v170, v137, v163
	v_mul_f32_e32 v171, v149, v167
	s_nop 0
	v_fmac_f32_dpp v170, v163, v133 row_shr:1 row_mask:0xf bank_mask:0xf bound_ctrl:1
	v_fmac_f32_dpp v170, v163, v129 row_shr:2 row_mask:0xf bank_mask:0xf bound_ctrl:1
	v_fmac_f32_dpp v171, v167, v145 row_shr:1 row_mask:0xf bank_mask:0xf bound_ctrl:1
	v_fmac_f32_dpp v171, v167, v141 row_shr:2 row_mask:0xf bank_mask:0xf bound_ctrl:1
	v_add_f32_e32 v174, 1.0, v174
	v_fmac_f32_dpp v170, v249, v239 row_ror:1 row_mask:0xf bank_mask:0xf bound_ctrl:1
	v_fmac_f32_dpp v170, v249, v240 row_ror:2 row_mask:0xf bank_mask:0xf bound_ctrl:1
	v_fmac_f32_dpp v171, v253, v241 row_ror:1 row_mask:0xf bank_mask:0xf bound_ctrl:1
	v_fmac_f32_dpp v171, v253, v242 row_ror:2 row_mask:0xf bank_mask:0xf bound_ctrl:1
	v_rcp_f32_e32 v174, v174
	v_mul_f32_e32 v190, 0xbfb8aa3b, v170
	v_exp_f32_e32 v190, v190
	v_mul_f32_e32 v168, v136, v162
	v_mul_f32_e32 v169, v148, v166
	s_nop 0
	v_fmac_f32_dpp v168, v162, v132 row_shr:1 row_mask:0xf bank_mask:0xf bound_ctrl:1
	v_fmac_f32_dpp v168, v162, v128 row_shr:2 row_mask:0xf bank_mask:0xf bound_ctrl:1
	v_fmac_f32_dpp v169, v166, v144 row_shr:1 row_mask:0xf bank_mask:0xf bound_ctrl:1
	v_fmac_f32_dpp v169, v166, v140 row_shr:2 row_mask:0xf bank_mask:0xf bound_ctrl:1
	v_mul_f32_e32 v175, v139, v161
	v_mul_f32_e32 v184, v151, v165
	v_mul_f32_e32 v172, v172, v174
	v_fmac_f32_dpp v168, v248, v243 row_ror:1 row_mask:0xf bank_mask:0xf bound_ctrl:1
	v_fmac_f32_dpp v168, v248, v244 row_ror:2 row_mask:0xf bank_mask:0xf bound_ctrl:1
	v_fmac_f32_dpp v169, v252, v245 row_ror:1 row_mask:0xf bank_mask:0xf bound_ctrl:1
	v_fmac_f32_dpp v169, v252, v246 row_ror:2 row_mask:0xf bank_mask:0xf bound_ctrl:1
	v_fmac_f32_dpp v175, v161, v135 row_shr:1 row_mask:0xf bank_mask:0xf bound_ctrl:1
	v_fmac_f32_dpp v175, v161, v131 row_shr:2 row_mask:0xf bank_mask:0xf bound_ctrl:1
	v_fmac_f32_dpp v184, v165, v147 row_shr:1 row_mask:0xf bank_mask:0xf bound_ctrl:1
	v_fmac_f32_dpp v184, v165, v143 row_shr:2 row_mask:0xf bank_mask:0xf bound_ctrl:1
	v_mul_f32_e32 v172, v173, v172
	v_add_f32_e32 v173, 1.0, v190
	v_mul_f32_e32 v174, 0xbfb8aa3b, v168
	v_fmac_f32_dpp v175, v229, v207 row_ror:1 row_mask:0xf bank_mask:0xf bound_ctrl:1
	v_fmac_f32_dpp v175, v229, v213 row_ror:2 row_mask:0xf bank_mask:0xf bound_ctrl:1
	v_fmac_f32_dpp v184, v251, v221 row_ror:1 row_mask:0xf bank_mask:0xf bound_ctrl:1
	v_fmac_f32_dpp v184, v251, v227 row_ror:2 row_mask:0xf bank_mask:0xf bound_ctrl:1
	v_rcp_f32_e32 v173, v173
	v_exp_f32_e32 v174, v174
	v_mul_f32_e32 v190, 0xbfb8aa3b, v175
	v_exp_f32_e32 v190, v190
	v_mul_f32_e32 v170, v170, v173
	v_add_f32_e32 v173, 1.0, v174
	v_rcp_f32_e32 v173, v173
	v_add_f32_e32 v174, 1.0, v190
	v_rcp_f32_e32 v174, v174
	v_add_u32_e32 v229, 0x63000, v205
	v_mul_f32_e32 v168, v168, v173
	v_mul_f32_e32 v168, v169, v168
	v_mul_f32_e32 v169, v175, v174
	v_mul_f32_e32 v170, v171, v170
	v_mul_f32_e32 v169, v184, v169
	v_add_u32_e32 v184, v229, v204
	v_cvt_pk_bf16_f32 v168, v168, v170
	v_lshl_add_u64 v[170:171], v[184:185], 1, s[38:39]
	v_cvt_pk_bf16_f32 v169, v172, v169
	global_store_dwordx2 v[170:171], v[168:169], off
	v_pk_fma_f32 v[170:171], v[52:53], v[200:201], v[152:153] op_sel_hi:[1,0,1]
	v_pk_fma_f32 v[174:175], v[48:49], v[200:201], v[156:157] op_sel_hi:[1,0,1]
	v_mul_f32_e32 v184, v136, v170
	v_mul_f32_e32 v190, v148, v174
	s_nop 0
	v_fmac_f32_dpp v184, v170, v132 row_shr:1 row_mask:0xf bank_mask:0xf bound_ctrl:1
; __device__ __forceinline__ unsigned pk2(float lo, float hi) { return pg8::cvt_pk_bf16(lo, hi); }
;     template <bool tail> __device__ __forceinline__ void run(f32x4 (&acc)[2][2][4][2], const pg8::Unit& u, int wr, int wc, int fr_in, int fq_in) const {
;     ...
; #pragma unroll
;                 for (int m = 0; m < 4; ++m) {
;                     const int r = rbase + 128 * ai + 16 * m;
;                     if (tail) { const float* bp = bias2 + (4 * ai + 2 * wr + (m >> 1)) * (2 * DFF) + chan0 + 4 * n; bg = *(const f32x4*)(bp); bvl = *(const f32x4*)(bp + DFF); }
;                     f32x4 cg_ = acc[ai][0][m][n] * rstd[ai][m] + bg, cv_ = acc[ai][1][m][n] * rstd[ai][m] + bvl;
;                     if (ai == 0 && m == 0) { if (zfirst) { cg_ = (f32x4){0.f, 0.f, 0.f, 0.f}; cv_ = cg_; } }
;                     float o[4];
; #pragma unroll
;                     for (int e = 0; e < 4; ++e) {
;                         float G = wg2[e] * cg_[e], V = wv2[e] * cv_[e];
;                         FMAC_DPP4(G, V, cg_[e], cv_[e], wg1[e], wg0[e], wv1[e], wv0[e], "row_shr:1", "row_shr:2");
;                         if (m == 0) { const float x2g = (fr == 0) ? g14[e] : g15[e], x2v = (fr == 0) ? v14[e] : v15[e];
;                             G = __builtin_fmaf(g15[e], ag[e], G); G = __builtin_fmaf(x2g, bgm[e], G); V = __builtin_fmaf(v15[e], av[e], V); V = __builtin_fmaf(x2v, bvm[e], V); }
;                         else { FMAC_DPP4(G, V, pg[e], pv[e], ag[e], bgm[e], av[e], bvm[e], "row_ror:1", "row_ror:2"); }
;                         o[e] = G * __builtin_amdgcn_rcpf(1.f + __expf(-G)) * V;
;                     }
;                     pg = cg_; pv = cv_;
;                     bool outv; int tg;
;                     if (tail) { outv = (m & 1) != 0; tg = (r >> 5) * S_ + 2016 + (r & 31); } else { outv = r >= 2; tg = tok0 + r; }
;                     if (outv) { u32x2 w; w.x = pk2(o[0], o[1]); w.y = pk2(o[2], o[3]); *(u32x2*)(act + ((unsigned)tg * DFF + chan0 + 4 * n)) = w; }
	v_fmac_f32_dpp v184, v170, v128 row_shr:2 row_mask:0xf bank_mask:0xf bound_ctrl:1
	v_fmac_f32_dpp v190, v174, v144 row_shr:1 row_mask:0xf bank_mask:0xf bound_ctrl:1
	v_fmac_f32_dpp v190, v174, v140 row_shr:2 row_mask:0xf bank_mask:0xf bound_ctrl:1
	v_pk_fma_f32 v[168:169], v[54:55], v[200:201], v[154:155] op_sel_hi:[1,0,1]
	v_fmac_f32_dpp v184, v162, v243 row_ror:1 row_mask:0xf bank_mask:0xf bound_ctrl:1
	v_fmac_f32_dpp v184, v162, v244 row_ror:2 row_mask:0xf bank_mask:0xf bound_ctrl:1
	v_fmac_f32_dpp v190, v166, v245 row_ror:1 row_mask:0xf bank_mask:0xf bound_ctrl:1
	v_fmac_f32_dpp v190, v166, v246 row_ror:2 row_mask:0xf bank_mask:0xf bound_ctrl:1
	v_mul_f32_e32 v162, v137, v171
	v_mul_f32_e32 v166, v149, v175
	v_pk_fma_f32 v[172:173], v[50:51], v[200:201], v[158:159] op_sel_hi:[1,0,1]
	v_fmac_f32_dpp v162, v171, v133 row_shr:1 row_mask:0xf bank_mask:0xf bound_ctrl:1
	v_fmac_f32_dpp v162, v171, v129 row_shr:2 row_mask:0xf bank_mask:0xf bound_ctrl:1
	v_fmac_f32_dpp v166, v175, v145 row_shr:1 row_mask:0xf bank_mask:0xf bound_ctrl:1
	v_fmac_f32_dpp v166, v175, v141 row_shr:2 row_mask:0xf bank_mask:0xf bound_ctrl:1
	v_add_u32_e32 v228, 0x6e000, v205
	v_fmac_f32_dpp v162, v163, v239 row_ror:1 row_mask:0xf bank_mask:0xf bound_ctrl:1
	v_fmac_f32_dpp v162, v163, v240 row_ror:2 row_mask:0xf bank_mask:0xf bound_ctrl:1
	v_fmac_f32_dpp v166, v167, v241 row_ror:1 row_mask:0xf bank_mask:0xf bound_ctrl:1
	v_fmac_f32_dpp v166, v167, v242 row_ror:2 row_mask:0xf bank_mask:0xf bound_ctrl:1
	v_mul_f32_e32 v163, v138, v168
	v_mul_f32_e32 v167, v150, v172
	s_nop 0
	v_fmac_f32_dpp v163, v168, v134 row_shr:1 row_mask:0xf bank_mask:0xf bound_ctrl:1
	v_fmac_f32_dpp v163, v168, v130 row_shr:2 row_mask:0xf bank_mask:0xf bound_ctrl:1
	v_fmac_f32_dpp v167, v172, v146 row_shr:1 row_mask:0xf bank_mask:0xf bound_ctrl:1
	v_fmac_f32_dpp v167, v172, v142 row_shr:2 row_mask:0xf bank_mask:0xf bound_ctrl:1
	v_mul_f32_e32 v197, 0xbfb8aa3b, v162
	v_fmac_f32_dpp v163, v160, v235 row_ror:1 row_mask:0xf bank_mask:0xf bound_ctrl:1
	v_fmac_f32_dpp v163, v160, v236 row_ror:2 row_mask:0xf bank_mask:0xf bound_ctrl:1
	v_fmac_f32_dpp v167, v164, v237 row_ror:1 row_mask:0xf bank_mask:0xf bound_ctrl:1
	v_fmac_f32_dpp v167, v164, v238 row_ror:2 row_mask:0xf bank_mask:0xf bound_ctrl:1
	v_exp_f32_e32 v197, v197
	v_mul_f32_e32 v160, 0xbfb8aa3b, v163
	v_exp_f32_e32 v160, v160
	v_mul_f32_e32 v164, v139, v169
	v_mul_f32_e32 v191, v151, v173
	s_nop 0
	v_fmac_f32_dpp v164, v169, v135 row_shr:1 row_mask:0xf bank_mask:0xf bound_ctrl:1
	v_fmac_f32_dpp v164, v169, v131 row_shr:2 row_mask:0xf bank_mask:0xf bound_ctrl:1
	v_fmac_f32_dpp v191, v173, v147 row_shr:1 row_mask:0xf bank_mask:0xf bound_ctrl:1
	v_fmac_f32_dpp v191, v173, v143 row_shr:2 row_mask:0xf bank_mask:0xf bound_ctrl:1
	v_add_f32_e32 v160, 1.0, v160
	v_rcp_f32_e32 v160, v160
	v_fmac_f32_dpp v164, v161, v207 row_ror:1 row_mask:0xf bank_mask:0xf bound_ctrl:1
	v_fmac_f32_dpp v164, v161, v213 row_ror:2 row_mask:0xf bank_mask:0xf bound_ctrl:1
	v_fmac_f32_dpp v191, v165, v221 row_ror:1 row_mask:0xf bank_mask:0xf bound_ctrl:1
	v_fmac_f32_dpp v191, v165, v227 row_ror:2 row_mask:0xf bank_mask:0xf bound_ctrl:1
	s_nop 0
	v_mul_f32_e32 v165, 0xbfb8aa3b, v164
	v_mul_f32_e32 v160, v163, v160
	v_mul_f32_e32 v161, v167, v160
	v_add_f32_e32 v160, 1.0, v197
	v_mul_f32_e32 v163, 0xbfb8aa3b, v184
	v_rcp_f32_e32 v160, v160
	v_exp_f32_e32 v163, v163
	v_exp_f32_e32 v165, v165
	v_mul_f32_e32 v160, v162, v160
	v_add_f32_e32 v162, 1.0, v163
	v_add_f32_e32 v163, 1.0, v165
	v_rcp_f32_e32 v162, v162
	v_rcp_f32_e32 v163, v163
	v_mul_f32_e32 v160, v166, v160
	v_mul_f32_e32 v162, v184, v162
	v_mul_f32_e32 v163, v164, v163
	v_mul_f32_e32 v162, v190, v162
	v_mul_f32_e32 v163, v191, v163
	v_add_u32_e32 v184, v228, v204
	v_cvt_pk_bf16_f32 v160, v162, v160
	v_cvt_pk_bf16_f32 v161, v161, v163
	v_lshl_add_u64 v[162:163], v[184:185], 1, s[38:39]
	global_store_dwordx2 v[162:163], v[160:161], off
	v_pk_fma_f32 v[152:153], v[108:109], v[196:197], v[152:153] op_sel_hi:[1,0,1]
	v_pk_fma_f32 v[156:157], v[100:101], v[196:197], v[156:157] op_sel_hi:[1,0,1]
	v_mul_f32_e32 v136, v136, v152
	v_mul_f32_e32 v148, v148, v156
	v_pk_fma_f32 v[154:155], v[110:111], v[196:197], v[154:155] op_sel_hi:[1,0,1]
	v_pk_fma_f32 v[158:159], v[102:103], v[196:197], v[158:159] op_sel_hi:[1,0,1]
	v_fmac_f32_dpp v136, v152, v132 row_shr:1 row_mask:0xf bank_mask:0xf bound_ctrl:1
	v_fmac_f32_dpp v136, v152, v128 row_shr:2 row_mask:0xf bank_mask:0xf bound_ctrl:1
	v_fmac_f32_dpp v148, v156, v144 row_shr:1 row_mask:0xf bank_mask:0xf bound_ctrl:1
	v_fmac_f32_dpp v148, v156, v140 row_shr:2 row_mask:0xf bank_mask:0xf bound_ctrl:1
	v_mul_f32_e32 v128, v137, v153
	v_mul_f32_e32 v132, v149, v157
	s_nop 0
	v_fmac_f32_dpp v128, v153, v133 row_shr:1 row_mask:0xf bank_mask:0xf bound_ctrl:1
	v_fmac_f32_dpp v128, v153, v129 row_shr:2 row_mask:0xf bank_mask:0xf bound_ctrl:1
	v_fmac_f32_dpp v132, v157, v145 row_shr:1 row_mask:0xf bank_mask:0xf bound_ctrl:1
	v_fmac_f32_dpp v132, v157, v141 row_shr:2 row_mask:0xf bank_mask:0xf bound_ctrl:1
	v_mul_f32_e32 v129, v138, v154
	v_mul_f32_e32 v133, v150, v158
	s_nop 0
	v_fmac_f32_dpp v129, v154, v134 row_shr:1 row_mask:0xf bank_mask:0xf bound_ctrl:1
	v_fmac_f32_dpp v129, v154, v130 row_shr:2 row_mask:0xf bank_mask:0xf bound_ctrl:1
	v_fmac_f32_dpp v133, v158, v146 row_shr:1 row_mask:0xf bank_mask:0xf bound_ctrl:1
	v_fmac_f32_dpp v133, v158, v142 row_shr:2 row_mask:0xf bank_mask:0xf bound_ctrl:1
	v_mul_f32_e32 v134, v139, v155
	v_fmac_f32_dpp v129, v168, v235 row_ror:1 row_mask:0xf bank_mask:0xf bound_ctrl:1
	v_fmac_f32_dpp v129, v168, v236 row_ror:2 row_mask:0xf bank_mask:0xf bound_ctrl:1
; #define LAS __attribute__((address_space(3)))
;     template <bool tail> __device__ __forceinline__ void run(f32x4 (&acc)[2][2][4][2], const pg8::Unit& u, int wr, int wc, int fr_in, int fq_in) const {
;     ...
;         for (int n = 0; n < 2; ++n) {
;             const float* wp = fcw + chan0 + 4 * n;
;             const f32x4 wg0 = *(const f32x4*)(wp), wg1 = *(const f32x4*)(wp + 2 * DFF), wg2 = *(const f32x4*)(wp + 4 * DFF);
;             const f32x4 wv0 = *(const f32x4*)(wp + DFF), wv1 = *(const f32x4*)(wp + 3 * DFF), wv2 = *(const f32x4*)(wp + 5 * DFF);
;             f32x4 bg = (f32x4){0.f, 0.f, 0.f, 0.f}, bvl = bg;
;             if (!tail) { bg = *(const f32x4*)(bias2 + breg * (2 * DFF) + chan0 + 4 * n); bvl = *(const f32x4*)(bias2 + breg * (2 * DFF) + DFF + chan0 + 4 * n); }
;             f32x4 ag, bgm, av, bvm;
; #pragma unroll
;             for (int e = 0; e < 4; ++e) { ag[e] = fr == 0 ? wg1[e] : 0.f; bgm[e] = fr < 2 ? wg0[e] : 0.f; av[e] = fr == 0 ? wv1[e] : 0.f; bvm[e] = fr < 2 ? wv0[e] : 0.f; }
; #pragma unroll
;             for (int ai = 0; ai < 2; ++ai) {
;                 const int slot = 2 * ai + wr - 1;
;                 f32x4 g14 = (f32x4){0.f, 0.f, 0.f, 0.f}, g15 = g14, v14 = g14, v15 = g14;
;                 if (slot >= 0) { const LAS float* xp = xch + (slot * 2) * 256 + colg + 4 * n;
;                     g14 = *(const LAS f32x4*)(xp); g15 = *(const LAS f32x4*)(xp + 256); v14 = *(const LAS f32x4*)(xp + 128); v15 = *(const LAS f32x4*)(xp + 256 + 128); }
;                 f32x4 pg = g14, pv = g14;
;     ...
;                             G = __builtin_fmaf(g15[e], ag[e], G); G = __builtin_fmaf(x2g, bgm[e], G); V = __builtin_fmaf(v15[e], av[e], V); V = __builtin_fmaf(x2v, bvm[e], V); }
;                         else { FMAC_DPP4(G, V, pg[e], pv[e], ag[e], bgm[e], av[e], bvm[e], "row_ror:1", "row_ror:2"); }
;                         o[e] = G * __builtin_amdgcn_rcpf(1.f + __expf(-G)) * V;
;                     }
;                     pg = cg_; pv = cv_;
;                     bool outv; int tg;
;                     if (tail) { outv = (m & 1) != 0; tg = (r >> 5) * S_ + 2016 + (r & 31); } else { outv = r >= 2; tg = tok0 + r; }
;                     if (outv) { u32x2 w; w.x = pk2(o[0], o[1]); w.y = pk2(o[2], o[3]); *(u32x2*)(act + ((unsigned)tg * DFF + chan0 + 4 * n)) = w; }
	v_fmac_f32_dpp v133, v172, v237 row_ror:1 row_mask:0xf bank_mask:0xf bound_ctrl:1
	v_fmac_f32_dpp v133, v172, v238 row_ror:2 row_mask:0xf bank_mask:0xf bound_ctrl:1
	v_mul_f32_e32 v137, v151, v159
	v_mul_f32_e32 v130, 0xbfb8aa3b, v129
	v_exp_f32_e32 v130, v130
	v_fmac_f32_dpp v128, v171, v239 row_ror:1 row_mask:0xf bank_mask:0xf bound_ctrl:1
	v_fmac_f32_dpp v128, v171, v240 row_ror:2 row_mask:0xf bank_mask:0xf bound_ctrl:1
	v_fmac_f32_dpp v132, v175, v241 row_ror:1 row_mask:0xf bank_mask:0xf bound_ctrl:1
	v_fmac_f32_dpp v132, v175, v242 row_ror:2 row_mask:0xf bank_mask:0xf bound_ctrl:1
	v_fmac_f32_dpp v134, v155, v135 row_shr:1 row_mask:0xf bank_mask:0xf bound_ctrl:1
	v_fmac_f32_dpp v134, v155, v131 row_shr:2 row_mask:0xf bank_mask:0xf bound_ctrl:1
	v_fmac_f32_dpp v137, v159, v147 row_shr:1 row_mask:0xf bank_mask:0xf bound_ctrl:1
	v_fmac_f32_dpp v137, v159, v143 row_shr:2 row_mask:0xf bank_mask:0xf bound_ctrl:1
	v_fmac_f32_dpp v136, v170, v243 row_ror:1 row_mask:0xf bank_mask:0xf bound_ctrl:1
	v_fmac_f32_dpp v136, v170, v244 row_ror:2 row_mask:0xf bank_mask:0xf bound_ctrl:1
	v_fmac_f32_dpp v148, v174, v245 row_ror:1 row_mask:0xf bank_mask:0xf bound_ctrl:1
	v_fmac_f32_dpp v148, v174, v246 row_ror:2 row_mask:0xf bank_mask:0xf bound_ctrl:1
	s_nop 0
	v_add_f32_e32 v130, 1.0, v130
	v_rcp_f32_e32 v130, v130
	v_mul_f32_e32 v131, 0xbfb8aa3b, v128
	v_exp_f32_e32 v131, v131
	v_fmac_f32_dpp v134, v169, v207 row_ror:1 row_mask:0xf bank_mask:0xf bound_ctrl:1
	v_fmac_f32_dpp v134, v169, v213 row_ror:2 row_mask:0xf bank_mask:0xf bound_ctrl:1
	v_fmac_f32_dpp v137, v173, v221 row_ror:1 row_mask:0xf bank_mask:0xf bound_ctrl:1
	v_fmac_f32_dpp v137, v173, v227 row_ror:2 row_mask:0xf bank_mask:0xf bound_ctrl:1
	v_mul_f32_e32 v129, v129, v130
	v_mul_f32_e32 v129, v133, v129
	v_add_f32_e32 v130, 1.0, v131
	v_mul_f32_e32 v131, 0xbfb8aa3b, v136
	v_mul_f32_e32 v133, 0xbfb8aa3b, v134
	v_rcp_f32_e32 v130, v130
	v_exp_f32_e32 v131, v131
	v_exp_f32_e32 v133, v133
	v_add_u32_e32 v227, 0x79000, v205
	v_mul_f32_e32 v128, v128, v130
	v_add_f32_e32 v130, 1.0, v131
	v_add_f32_e32 v131, 1.0, v133
	v_rcp_f32_e32 v130, v130
	v_rcp_f32_e32 v131, v131
	v_mul_f32_e32 v128, v132, v128
	v_add_u32_e32 v184, v227, v204
	v_mul_f32_e32 v130, v136, v130
	v_mul_f32_e32 v131, v134, v131
	v_mul_f32_e32 v130, v148, v130
	v_mul_f32_e32 v131, v137, v131
	v_cvt_pk_bf16_f32 v128, v130, v128
	v_cvt_pk_bf16_f32 v129, v129, v131
	v_lshl_add_u64 v[130:131], v[184:185], 1, s[38:39]
	global_store_dwordx2 v[130:131], v[128:129], off
	v_add_co_u32_e32 v132, vcc, 0x5000, v210
	global_load_dwordx4 v[128:131], v[210:211], off offset:16
	s_nop 0
	v_addc_co_u32_e32 v133, vcc, 0, v211, vcc
	v_add_co_u32_e32 v136, vcc, 0xb000, v210
	v_mov_b32_e32 v160, 0
	s_nop 0
	v_addc_co_u32_e32 v137, vcc, 0, v211, vcc
	v_add_co_u32_e32 v144, vcc, 0x8000, v210
	global_load_dwordx4 v[132:135], v[132:133], off offset:2064
	s_nop 0
	global_load_dwordx4 v[136:139], v[136:137], off offset:16
	v_addc_co_u32_e32 v145, vcc, 0, v211, vcc
	v_add_co_u32_e32 v148, vcc, 0xd000, v210
	global_load_dwordx4 v[140:143], v[216:217], off offset:3088
	s_nop 0
	global_load_dwordx4 v[144:147], v[144:145], off offset:1040
	v_addc_co_u32_e32 v149, vcc, 0, v211, vcc
	v_add_co_u32_e32 v156, vcc, 0x2000, v218
	global_load_dwordx4 v[148:151], v[148:149], off offset:3088
	s_nop 0
	global_load_dwordx4 v[152:155], v[218:219], off offset:16
	v_addc_co_u32_e32 v157, vcc, 0, v219, vcc
	global_load_dwordx4 v[156:159], v[156:157], off offset:3088
	s_and_b64 vcc, exec, s[16:17]
	v_mov_b32_e32 v161, 0
	v_mov_b32_e32 v162, 0
	v_mov_b32_e32 v163, 0
	v_mov_b32_e32 v172, 0
	v_mov_b32_e32 v173, 0
	v_mov_b32_e32 v174, 0
	v_mov_b32_e32 v175, 0
	v_mov_b32_e32 v164, 0
	v_mov_b32_e32 v165, 0
	v_mov_b32_e32 v166, 0
	v_mov_b32_e32 v167, 0
	v_mov_b32_e32 v168, 0
	v_mov_b32_e32 v169, 0
	v_mov_b32_e32 v170, 0
	v_mov_b32_e32 v171, 0
	s_cbranch_vccnz .LBB0_590
	v_add_u32_e32 v168, 0xfffffe10, v230
	v_add_u32_e32 v164, 0xfffffa10, v230
	v_add_u32_e32 v165, 0xfffffc10, v230
	v_add_u32_e32 v160, 0xfffff810, v230
	ds_read_b128 v[160:163], v160
	ds_read_b128 v[172:175], v165
	ds_read_b128 v[164:167], v164
	ds_read_b128 v[168:171], v168
.LBB0_590:
	v_mov_b32_e32 v215, v214
	v_mov_b32_e32 v246, v214
	v_mov_b32_e32 v247, v214
	s_waitcnt vmcnt(1)
	v_pk_fma_f32 v[248:249], v[46:47], v[246:247], v[154:155]
	v_pk_fma_f32 v[250:251], v[44:45], v[214:215], v[152:153]
	s_waitcnt vmcnt(0)
; #define LAS __attribute__((address_space(3)))
;     template <bool tail> __device__ __forceinline__ void run(f32x4 (&acc)[2][2][4][2], const pg8::Unit& u, int wr, int wc, int fr_in, int fq_in) const {
;     ...
;             for (int e = 0; e < 4; ++e) { ag[e] = fr == 0 ? wg1[e] : 0.f; bgm[e] = fr < 2 ? wg0[e] : 0.f; av[e] = fr == 0 ? wv1[e] : 0.f; bvm[e] = fr < 2 ? wv0[e] : 0.f; }
; #pragma unroll
;             for (int ai = 0; ai < 2; ++ai) {
;                 const int slot = 2 * ai + wr - 1;
;                 f32x4 g14 = (f32x4){0.f, 0.f, 0.f, 0.f}, g15 = g14, v14 = g14, v15 = g14;
;                 if (slot >= 0) { const LAS float* xp = xch + (slot * 2) * 256 + colg + 4 * n;
;                     g14 = *(const LAS f32x4*)(xp); g15 = *(const LAS f32x4*)(xp + 256); v14 = *(const LAS f32x4*)(xp + 128); v15 = *(const LAS f32x4*)(xp + 256 + 128); }
;                 f32x4 pg = g14, pv = g14;
; #pragma unroll
;                 for (int m = 0; m < 4; ++m) {
;                     const int r = rbase + 128 * ai + 16 * m;
;                     if (tail) { const float* bp = bias2 + (4 * ai + 2 * wr + (m >> 1)) * (2 * DFF) + chan0 + 4 * n; bg = *(const f32x4*)(bp); bvl = *(const f32x4*)(bp + DFF); }
;                     f32x4 cg_ = acc[ai][0][m][n] * rstd[ai][m] + bg, cv_ = acc[ai][1][m][n] * rstd[ai][m] + bvl;
;                     if (ai == 0 && m == 0) { if (zfirst) { cg_ = (f32x4){0.f, 0.f, 0.f, 0.f}; cv_ = cg_; } }
;                     float o[4];
; #pragma unroll
;                     for (int e = 0; e < 4; ++e) {
;                         float G = wg2[e] * cg_[e], V = wv2[e] * cv_[e];
;                         FMAC_DPP4(G, V, cg_[e], cv_[e], wg1[e], wg0[e], wv1[e], wv0[e], "row_shr:1", "row_shr:2");
;                         if (m == 0) { const float x2g = (fr == 0) ? g14[e] : g15[e], x2v = (fr == 0) ? v14[e] : v15[e];
;                             G = __builtin_fmaf(g15[e], ag[e], G); G = __builtin_fmaf(x2g, bgm[e], G); V = __builtin_fmaf(v15[e], av[e], V); V = __builtin_fmaf(x2v, bvm[e], V); }
;                         else { FMAC_DPP4(G, V, pg[e], pv[e], ag[e], bgm[e], av[e], bvm[e], "row_ror:1", "row_ror:2"); }
;                         o[e] = G * __builtin_amdgcn_rcpf(1.f + __expf(-G)) * V;
	v_pk_fma_f32 v[252:253], v[42:43], v[246:247], v[158:159]
	v_pk_fma_f32 v[190:191], v[40:41], v[214:215], v[156:157]
	v_cndmask_b32_e64 v214, v249, 0, s[70:71]
	v_cndmask_b32_e64 v245, v248, 0, s[70:71]
	v_cndmask_b32_e64 v247, v251, 0, s[70:71]
	v_cndmask_b32_e64 v249, v250, 0, s[70:71]
	v_cndmask_b32_e64 v215, v253, 0, s[70:71]
	v_cndmask_b32_e64 v246, v252, 0, s[70:71]
	v_cndmask_b32_e64 v248, v191, 0, s[70:71]
	v_cndmask_b32_e64 v250, v190, 0, s[70:71]
	v_cndmask_b32_e64 v241, 0, v132, s[10:11]
	v_cndmask_b32_e64 v242, 0, v128, s[12:13]
	v_cndmask_b32_e64 v243, 0, v144, s[10:11]
	v_cndmask_b32_e64 v244, 0, v140, s[12:13]
	v_cndmask_b32_e64 v237, 0, v133, s[10:11]
	v_cndmask_b32_e64 v238, 0, v129, s[12:13]
	v_cndmask_b32_e64 v239, 0, v145, s[10:11]
	v_cndmask_b32_e64 v240, 0, v141, s[12:13]
	v_cndmask_b32_e64 v218, 0, v134, s[10:11]
	v_cndmask_b32_e64 v219, 0, v130, s[12:13]
	v_cndmask_b32_e64 v235, 0, v146, s[10:11]
	v_cndmask_b32_e64 v236, 0, v142, s[12:13]
	v_cndmask_b32_e64 v210, 0, v135, s[10:11]
	v_cndmask_b32_e64 v211, 0, v131, s[12:13]
	v_cndmask_b32_e64 v216, 0, v147, s[10:11]
	v_cndmask_b32_e64 v217, 0, v143, s[12:13]
	v_or_b32_e32 v204, 4, v204
	v_mul_f32_e32 v197, v136, v249
	v_mul_f32_e32 v184, v148, v250
	v_mul_f32_e32 v207, v137, v247
	v_mul_f32_e32 v203, v149, v248
	v_mul_f32_e32 v221, v138, v245
	v_mul_f32_e32 v213, v150, v246
	v_mul_f32_e32 v201, v139, v214
	v_mul_f32_e32 v199, v151, v215
	v_fmac_f32_dpp v197, v249, v132 row_shr:1 row_mask:0xf bank_mask:0xf bound_ctrl:1
	v_fmac_f32_dpp v197, v249, v128 row_shr:2 row_mask:0xf bank_mask:0xf bound_ctrl:1
	v_fmac_f32_dpp v184, v250, v144 row_shr:1 row_mask:0xf bank_mask:0xf bound_ctrl:1
	v_fmac_f32_dpp v184, v250, v140 row_shr:2 row_mask:0xf bank_mask:0xf bound_ctrl:1
	v_fmac_f32_dpp v207, v247, v133 row_shr:1 row_mask:0xf bank_mask:0xf bound_ctrl:1
	v_fmac_f32_dpp v207, v247, v129 row_shr:2 row_mask:0xf bank_mask:0xf bound_ctrl:1
	v_fmac_f32_dpp v203, v248, v145 row_shr:1 row_mask:0xf bank_mask:0xf bound_ctrl:1
	v_fmac_f32_dpp v203, v248, v141 row_shr:2 row_mask:0xf bank_mask:0xf bound_ctrl:1
	v_fmac_f32_dpp v221, v245, v134 row_shr:1 row_mask:0xf bank_mask:0xf bound_ctrl:1
	v_fmac_f32_dpp v221, v245, v130 row_shr:2 row_mask:0xf bank_mask:0xf bound_ctrl:1
	v_fmac_f32_dpp v213, v246, v146 row_shr:1 row_mask:0xf bank_mask:0xf bound_ctrl:1
	v_fmac_f32_dpp v213, v246, v142 row_shr:2 row_mask:0xf bank_mask:0xf bound_ctrl:1
	v_fmac_f32_dpp v201, v214, v135 row_shr:1 row_mask:0xf bank_mask:0xf bound_ctrl:1
	v_fmac_f32_dpp v201, v214, v131 row_shr:2 row_mask:0xf bank_mask:0xf bound_ctrl:1
	v_fmac_f32_dpp v199, v215, v147 row_shr:1 row_mask:0xf bank_mask:0xf bound_ctrl:1
	v_fmac_f32_dpp v199, v215, v143 row_shr:2 row_mask:0xf bank_mask:0xf bound_ctrl:1
	s_and_saveexec_b64 s[12:13], s[14:15]
	s_cbranch_execz .LBB0_592
	s_waitcnt lgkmcnt(2)
	v_cndmask_b32_e64 v162, v174, v162, s[10:11]
	v_fmac_f32_e32 v221, v174, v218
	v_cndmask_b32_e64 v161, v173, v161, s[10:11]
	v_fmac_f32_e32 v207, v173, v237
	v_cndmask_b32_e64 v160, v172, v160, s[10:11]
	v_fmac_f32_e32 v197, v172, v241
	v_cndmask_b32_e64 v163, v175, v163, s[10:11]
	v_fmac_f32_e32 v201, v175, v210
	v_fmac_f32_e32 v221, v162, v219
	v_fmac_f32_e32 v207, v161, v238
	v_fmac_f32_e32 v197, v160, v242
	v_fmac_f32_e32 v201, v163, v211
	v_mul_f32_e32 v162, 0xbfb8aa3b, v221
	v_mul_f32_e32 v161, 0xbfb8aa3b, v207
	v_mul_f32_e32 v160, 0xbfb8aa3b, v197
	v_mul_f32_e32 v163, 0xbfb8aa3b, v201
	v_exp_f32_e32 v162, v162
	v_exp_f32_e32 v161, v161
	v_exp_f32_e32 v160, v160
	v_exp_f32_e32 v163, v163
	v_add_f32_e32 v162, 1.0, v162
	v_add_f32_e32 v161, 1.0, v161
	v_add_f32_e32 v160, 1.0, v160
	v_add_f32_e32 v163, 1.0, v163
	v_rcp_f32_e32 v162, v162
	v_rcp_f32_e32 v161, v161
	v_rcp_f32_e32 v160, v160
	v_rcp_f32_e32 v163, v163
	s_waitcnt lgkmcnt(0)
	v_cndmask_b32_e64 v164, v168, v164, s[10:11]
	v_fmac_f32_e32 v184, v168, v243
	v_cndmask_b32_e64 v166, v170, v166, s[10:11]
	v_fmac_f32_e32 v213, v170, v235
	v_cndmask_b32_e64 v165, v169, v165, s[10:11]
	v_fmac_f32_e32 v203, v169, v239
	v_fmac_f32_e32 v184, v164, v244
	v_cndmask_b32_e64 v164, v171, v167, s[10:11]
	v_fmac_f32_e32 v199, v171, v216
	v_fmac_f32_e32 v213, v166, v236
	v_mul_f32_e32 v162, v221, v162
	v_fmac_f32_e32 v203, v165, v240
	v_mul_f32_e32 v161, v207, v161
	v_mul_f32_e32 v160, v197, v160
	v_fmac_f32_e32 v199, v164, v217
	v_mul_f32_e32 v163, v201, v163
	v_mul_f32_e32 v162, v213, v162
	v_mul_f32_e32 v161, v203, v161
	v_mul_f32_e32 v160, v184, v160
	v_mul_f32_e32 v163, v199, v163
	v_add_u32_e32 v184, v204, v205
	v_cvt_pk_bf16_f32 v160, v160, v161
	v_cvt_pk_bf16_f32 v161, v162, v163
	v_lshl_add_u64 v[162:163], v[184:185], 1, s[38:39]
	global_store_dwordx2 v[162:163], v[160:161], off
; __device__ __forceinline__ unsigned pk2(float lo, float hi) { return pg8::cvt_pk_bf16(lo, hi); }
;     template <bool tail> __device__ __forceinline__ void run(f32x4 (&acc)[2][2][4][2], const pg8::Unit& u, int wr, int wc, int fr_in, int fq_in) const {
;     ...
; #pragma unroll
;                 for (int m = 0; m < 4; ++m) {
;                     const int r = rbase + 128 * ai + 16 * m;
;                     if (tail) { const float* bp = bias2 + (4 * ai + 2 * wr + (m >> 1)) * (2 * DFF) + chan0 + 4 * n; bg = *(const f32x4*)(bp); bvl = *(const f32x4*)(bp + DFF); }
;                     f32x4 cg_ = acc[ai][0][m][n] * rstd[ai][m] + bg, cv_ = acc[ai][1][m][n] * rstd[ai][m] + bvl;
;                     if (ai == 0 && m == 0) { if (zfirst) { cg_ = (f32x4){0.f, 0.f, 0.f, 0.f}; cv_ = cg_; } }
;                     float o[4];
; #pragma unroll
;                     for (int e = 0; e < 4; ++e) {
;                         float G = wg2[e] * cg_[e], V = wv2[e] * cv_[e];
;                         FMAC_DPP4(G, V, cg_[e], cv_[e], wg1[e], wg0[e], wv1[e], wv0[e], "row_shr:1", "row_shr:2");
;                         if (m == 0) { const float x2g = (fr == 0) ? g14[e] : g15[e], x2v = (fr == 0) ? v14[e] : v15[e];
;                             G = __builtin_fmaf(g15[e], ag[e], G); G = __builtin_fmaf(x2g, bgm[e], G); V = __builtin_fmaf(v15[e], av[e], V); V = __builtin_fmaf(x2v, bvm[e], V); }
;                         else { FMAC_DPP4(G, V, pg[e], pv[e], ag[e], bgm[e], av[e], bvm[e], "row_ror:1", "row_ror:2"); }
;                         o[e] = G * __builtin_amdgcn_rcpf(1.f + __expf(-G)) * V;
;                     }
;                     pg = cg_; pv = cv_;
;                     bool outv; int tg;
;                     if (tail) { outv = (m & 1) != 0; tg = (r >> 5) * S_ + 2016 + (r & 31); } else { outv = r >= 2; tg = tok0 + r; }
;                     if (outv) { u32x2 w; w.x = pk2(o[0], o[1]); w.y = pk2(o[2], o[3]); *(u32x2*)(act + ((unsigned)tg * DFF + chan0 + 4 * n)) = w; }
.LBB0_592:
	s_or_b64 exec, exec, s[12:13]
	v_mov_b32_e32 v221, v220
	v_mov_b32_e32 v213, v212
	v_mov_b32_e32 v199, v198
	v_mov_b32_e32 v207, v206
	v_mov_b32_e32 v203, v202
	v_mov_b32_e32 v201, v200
	v_mov_b32_e32 v197, v196
	s_waitcnt lgkmcnt(3)
	v_mov_b32_e32 v160, v220
	v_mov_b32_e32 v161, v220
	v_pk_fma_f32 v[162:163], v[38:39], v[160:161], v[154:155]
	v_pk_fma_f32 v[160:161], v[34:35], v[160:161], v[158:159]
	s_waitcnt lgkmcnt(2)
	v_mul_f32_e32 v172, v138, v162
	v_mul_f32_e32 v173, v150, v160
	s_nop 0
	v_fmac_f32_dpp v172, v162, v134 row_shr:1 row_mask:0xf bank_mask:0xf bound_ctrl:1
	v_fmac_f32_dpp v172, v162, v130 row_shr:2 row_mask:0xf bank_mask:0xf bound_ctrl:1
	v_fmac_f32_dpp v173, v160, v146 row_shr:1 row_mask:0xf bank_mask:0xf bound_ctrl:1
	v_fmac_f32_dpp v173, v160, v142 row_shr:2 row_mask:0xf bank_mask:0xf bound_ctrl:1
	s_waitcnt lgkmcnt(1)
	v_pk_fma_f32 v[164:165], v[36:37], v[220:221], v[152:153]
	v_fmac_f32_dpp v172, v245, v218 row_ror:1 row_mask:0xf bank_mask:0xf bound_ctrl:1
	v_fmac_f32_dpp v172, v245, v219 row_ror:2 row_mask:0xf bank_mask:0xf bound_ctrl:1
	v_fmac_f32_dpp v173, v246, v235 row_ror:1 row_mask:0xf bank_mask:0xf bound_ctrl:1
	v_fmac_f32_dpp v173, v246, v236 row_ror:2 row_mask:0xf bank_mask:0xf bound_ctrl:1
	v_pk_fma_f32 v[166:167], v[32:33], v[220:221], v[156:157]
	v_mul_f32_e32 v174, 0xbfb8aa3b, v172
	v_exp_f32_e32 v174, v174
	s_waitcnt lgkmcnt(0)
	v_mul_f32_e32 v170, v137, v165
	v_mul_f32_e32 v171, v149, v167
	s_nop 0
	v_fmac_f32_dpp v170, v165, v133 row_shr:1 row_mask:0xf bank_mask:0xf bound_ctrl:1
	v_fmac_f32_dpp v170, v165, v129 row_shr:2 row_mask:0xf bank_mask:0xf bound_ctrl:1
	v_fmac_f32_dpp v171, v167, v145 row_shr:1 row_mask:0xf bank_mask:0xf bound_ctrl:1
	v_fmac_f32_dpp v171, v167, v141 row_shr:2 row_mask:0xf bank_mask:0xf bound_ctrl:1
	v_add_f32_e32 v174, 1.0, v174
	v_fmac_f32_dpp v170, v247, v237 row_ror:1 row_mask:0xf bank_mask:0xf bound_ctrl:1
	v_fmac_f32_dpp v170, v247, v238 row_ror:2 row_mask:0xf bank_mask:0xf bound_ctrl:1
	v_fmac_f32_dpp v171, v248, v239 row_ror:1 row_mask:0xf bank_mask:0xf bound_ctrl:1
	v_fmac_f32_dpp v171, v248, v240 row_ror:2 row_mask:0xf bank_mask:0xf bound_ctrl:1
	v_rcp_f32_e32 v174, v174
	v_mul_f32_e32 v190, 0xbfb8aa3b, v170
	v_exp_f32_e32 v190, v190
	v_mul_f32_e32 v168, v136, v164
	v_mul_f32_e32 v169, v148, v166
	s_nop 0
	v_fmac_f32_dpp v168, v164, v132 row_shr:1 row_mask:0xf bank_mask:0xf bound_ctrl:1
	v_fmac_f32_dpp v168, v164, v128 row_shr:2 row_mask:0xf bank_mask:0xf bound_ctrl:1
	v_fmac_f32_dpp v169, v166, v144 row_shr:1 row_mask:0xf bank_mask:0xf bound_ctrl:1
	v_fmac_f32_dpp v169, v166, v140 row_shr:2 row_mask:0xf bank_mask:0xf bound_ctrl:1
	v_mul_f32_e32 v175, v139, v163
	v_mul_f32_e32 v184, v151, v161
	v_mul_f32_e32 v172, v172, v174
	v_fmac_f32_dpp v168, v249, v241 row_ror:1 row_mask:0xf bank_mask:0xf bound_ctrl:1
	v_fmac_f32_dpp v168, v249, v242 row_ror:2 row_mask:0xf bank_mask:0xf bound_ctrl:1
	v_fmac_f32_dpp v169, v250, v243 row_ror:1 row_mask:0xf bank_mask:0xf bound_ctrl:1
	v_fmac_f32_dpp v169, v250, v244 row_ror:2 row_mask:0xf bank_mask:0xf bound_ctrl:1
	v_fmac_f32_dpp v175, v163, v135 row_shr:1 row_mask:0xf bank_mask:0xf bound_ctrl:1
	v_fmac_f32_dpp v175, v163, v131 row_shr:2 row_mask:0xf bank_mask:0xf bound_ctrl:1
	v_fmac_f32_dpp v184, v161, v147 row_shr:1 row_mask:0xf bank_mask:0xf bound_ctrl:1
	v_fmac_f32_dpp v184, v161, v143 row_shr:2 row_mask:0xf bank_mask:0xf bound_ctrl:1
	v_mul_f32_e32 v172, v173, v172
	v_add_f32_e32 v173, 1.0, v190
	v_mul_f32_e32 v174, 0xbfb8aa3b, v168
	v_fmac_f32_dpp v175, v214, v210 row_ror:1 row_mask:0xf bank_mask:0xf bound_ctrl:1
	v_fmac_f32_dpp v175, v214, v211 row_ror:2 row_mask:0xf bank_mask:0xf bound_ctrl:1
	v_fmac_f32_dpp v184, v215, v216 row_ror:1 row_mask:0xf bank_mask:0xf bound_ctrl:1
	v_fmac_f32_dpp v184, v215, v217 row_ror:2 row_mask:0xf bank_mask:0xf bound_ctrl:1
	v_rcp_f32_e32 v173, v173
	v_exp_f32_e32 v174, v174
	v_mul_f32_e32 v190, 0xbfb8aa3b, v175
	v_exp_f32_e32 v190, v190
	v_mul_f32_e32 v170, v170, v173
	v_add_f32_e32 v173, 1.0, v174
	v_rcp_f32_e32 v173, v173
	v_add_f32_e32 v174, 1.0, v190
	v_rcp_f32_e32 v174, v174
	v_mul_f32_e32 v170, v171, v170
	v_mul_f32_e32 v168, v168, v173
	v_mul_f32_e32 v168, v169, v168
	v_mul_f32_e32 v169, v175, v174
	v_mul_f32_e32 v169, v184, v169
	v_add_u32_e32 v184, v204, v234
	v_cvt_pk_bf16_f32 v168, v168, v170
	v_lshl_add_u64 v[170:171], v[184:185], 1, s[38:39]
	v_cvt_pk_bf16_f32 v169, v172, v169
	global_store_dwordx2 v[170:171], v[168:169], off
	v_pk_fma_f32 v[172:173], v[28:29], v[212:213], v[152:153]
	v_pk_fma_f32 v[174:175], v[24:25], v[212:213], v[156:157]
	v_mul_f32_e32 v184, v136, v172
	v_mul_f32_e32 v190, v148, v174
	s_nop 0
	v_fmac_f32_dpp v184, v172, v132 row_shr:1 row_mask:0xf bank_mask:0xf bound_ctrl:1
	v_fmac_f32_dpp v184, v172, v128 row_shr:2 row_mask:0xf bank_mask:0xf bound_ctrl:1
	v_fmac_f32_dpp v190, v174, v144 row_shr:1 row_mask:0xf bank_mask:0xf bound_ctrl:1
	v_fmac_f32_dpp v190, v174, v140 row_shr:2 row_mask:0xf bank_mask:0xf bound_ctrl:1
	v_mov_b32_e32 v168, v212
	v_mov_b32_e32 v169, v212
	v_fmac_f32_dpp v184, v164, v241 row_ror:1 row_mask:0xf bank_mask:0xf bound_ctrl:1
	v_fmac_f32_dpp v184, v164, v242 row_ror:2 row_mask:0xf bank_mask:0xf bound_ctrl:1
	v_fmac_f32_dpp v190, v166, v243 row_ror:1 row_mask:0xf bank_mask:0xf bound_ctrl:1
	v_fmac_f32_dpp v190, v166, v244 row_ror:2 row_mask:0xf bank_mask:0xf bound_ctrl:1
	v_mul_f32_e32 v164, v137, v173
	v_mul_f32_e32 v166, v149, v175
	v_pk_fma_f32 v[170:171], v[30:31], v[168:169], v[154:155]
	v_pk_fma_f32 v[168:169], v[26:27], v[168:169], v[158:159]
	v_fmac_f32_dpp v164, v173, v133 row_shr:1 row_mask:0xf bank_mask:0xf bound_ctrl:1
; __device__ __forceinline__ unsigned pk2(float lo, float hi) { return pg8::cvt_pk_bf16(lo, hi); }
;     template <bool tail> __device__ __forceinline__ void run(f32x4 (&acc)[2][2][4][2], const pg8::Unit& u, int wr, int wc, int fr_in, int fq_in) const {
;     ...
; #pragma unroll
;                 for (int m = 0; m < 4; ++m) {
;                     const int r = rbase + 128 * ai + 16 * m;
;                     if (tail) { const float* bp = bias2 + (4 * ai + 2 * wr + (m >> 1)) * (2 * DFF) + chan0 + 4 * n; bg = *(const f32x4*)(bp); bvl = *(const f32x4*)(bp + DFF); }
;                     f32x4 cg_ = acc[ai][0][m][n] * rstd[ai][m] + bg, cv_ = acc[ai][1][m][n] * rstd[ai][m] + bvl;
;                     if (ai == 0 && m == 0) { if (zfirst) { cg_ = (f32x4){0.f, 0.f, 0.f, 0.f}; cv_ = cg_; } }
;                     float o[4];
; #pragma unroll
;                     for (int e = 0; e < 4; ++e) {
;                         float G = wg2[e] * cg_[e], V = wv2[e] * cv_[e];
;                         FMAC_DPP4(G, V, cg_[e], cv_[e], wg1[e], wg0[e], wv1[e], wv0[e], "row_shr:1", "row_shr:2");
;                         if (m == 0) { const float x2g = (fr == 0) ? g14[e] : g15[e], x2v = (fr == 0) ? v14[e] : v15[e];
;                             G = __builtin_fmaf(g15[e], ag[e], G); G = __builtin_fmaf(x2g, bgm[e], G); V = __builtin_fmaf(v15[e], av[e], V); V = __builtin_fmaf(x2v, bvm[e], V); }
;                         else { FMAC_DPP4(G, V, pg[e], pv[e], ag[e], bgm[e], av[e], bvm[e], "row_ror:1", "row_ror:2"); }
;                         o[e] = G * __builtin_amdgcn_rcpf(1.f + __expf(-G)) * V;
;                     }
;                     pg = cg_; pv = cv_;
;                     bool outv; int tg;
;                     if (tail) { outv = (m & 1) != 0; tg = (r >> 5) * S_ + 2016 + (r & 31); } else { outv = r >= 2; tg = tok0 + r; }
;                     if (outv) { u32x2 w; w.x = pk2(o[0], o[1]); w.y = pk2(o[2], o[3]); *(u32x2*)(act + ((unsigned)tg * DFF + chan0 + 4 * n)) = w; }
	v_fmac_f32_dpp v164, v173, v129 row_shr:2 row_mask:0xf bank_mask:0xf bound_ctrl:1
	v_fmac_f32_dpp v166, v175, v145 row_shr:1 row_mask:0xf bank_mask:0xf bound_ctrl:1
	v_fmac_f32_dpp v166, v175, v141 row_shr:2 row_mask:0xf bank_mask:0xf bound_ctrl:1
	s_nop 0
	v_fmac_f32_dpp v164, v165, v237 row_ror:1 row_mask:0xf bank_mask:0xf bound_ctrl:1
	v_fmac_f32_dpp v164, v165, v238 row_ror:2 row_mask:0xf bank_mask:0xf bound_ctrl:1
	v_fmac_f32_dpp v166, v167, v239 row_ror:1 row_mask:0xf bank_mask:0xf bound_ctrl:1
	v_fmac_f32_dpp v166, v167, v240 row_ror:2 row_mask:0xf bank_mask:0xf bound_ctrl:1
	v_mul_f32_e32 v165, v138, v170
	v_mul_f32_e32 v167, v150, v168
	s_nop 0
	v_fmac_f32_dpp v165, v170, v134 row_shr:1 row_mask:0xf bank_mask:0xf bound_ctrl:1
	v_fmac_f32_dpp v165, v170, v130 row_shr:2 row_mask:0xf bank_mask:0xf bound_ctrl:1
	v_fmac_f32_dpp v167, v168, v146 row_shr:1 row_mask:0xf bank_mask:0xf bound_ctrl:1
	v_fmac_f32_dpp v167, v168, v142 row_shr:2 row_mask:0xf bank_mask:0xf bound_ctrl:1
	v_mul_f32_e32 v205, 0xbfb8aa3b, v164
	v_fmac_f32_dpp v165, v162, v218 row_ror:1 row_mask:0xf bank_mask:0xf bound_ctrl:1
	v_fmac_f32_dpp v165, v162, v219 row_ror:2 row_mask:0xf bank_mask:0xf bound_ctrl:1
	v_fmac_f32_dpp v167, v160, v235 row_ror:1 row_mask:0xf bank_mask:0xf bound_ctrl:1
	v_fmac_f32_dpp v167, v160, v236 row_ror:2 row_mask:0xf bank_mask:0xf bound_ctrl:1
	v_exp_f32_e32 v205, v205
	v_mul_f32_e32 v160, 0xbfb8aa3b, v165
	v_exp_f32_e32 v160, v160
	v_mul_f32_e32 v162, v139, v171
	v_mul_f32_e32 v191, v151, v169
	s_nop 0
	v_fmac_f32_dpp v162, v171, v135 row_shr:1 row_mask:0xf bank_mask:0xf bound_ctrl:1
	v_fmac_f32_dpp v162, v171, v131 row_shr:2 row_mask:0xf bank_mask:0xf bound_ctrl:1
	v_fmac_f32_dpp v191, v169, v147 row_shr:1 row_mask:0xf bank_mask:0xf bound_ctrl:1
	v_fmac_f32_dpp v191, v169, v143 row_shr:2 row_mask:0xf bank_mask:0xf bound_ctrl:1
	v_add_f32_e32 v160, 1.0, v160
	v_rcp_f32_e32 v160, v160
	v_fmac_f32_dpp v162, v163, v210 row_ror:1 row_mask:0xf bank_mask:0xf bound_ctrl:1
	v_fmac_f32_dpp v162, v163, v211 row_ror:2 row_mask:0xf bank_mask:0xf bound_ctrl:1
	v_fmac_f32_dpp v191, v161, v216 row_ror:1 row_mask:0xf bank_mask:0xf bound_ctrl:1
	v_fmac_f32_dpp v191, v161, v217 row_ror:2 row_mask:0xf bank_mask:0xf bound_ctrl:1
	v_mul_f32_e32 v163, 0xbfb8aa3b, v184
	v_exp_f32_e32 v163, v163
	v_mul_f32_e32 v160, v165, v160
	v_mul_f32_e32 v161, v167, v160
	v_add_f32_e32 v160, 1.0, v205
	v_mul_f32_e32 v165, 0xbfb8aa3b, v162
	v_rcp_f32_e32 v160, v160
	v_exp_f32_e32 v165, v165
	v_add_f32_e32 v163, 1.0, v163
	v_rcp_f32_e32 v163, v163
	v_mul_f32_e32 v160, v164, v160
	v_add_f32_e32 v164, 1.0, v165
	v_rcp_f32_e32 v164, v164
	v_mul_f32_e32 v163, v184, v163
	v_mul_f32_e32 v160, v166, v160
	v_mul_f32_e32 v163, v190, v163
	v_mul_f32_e32 v162, v162, v164
	v_mul_f32_e32 v162, v191, v162
	v_add_u32_e32 v184, v204, v233
	v_cvt_pk_bf16_f32 v160, v163, v160
	v_cvt_pk_bf16_f32 v161, v161, v162
	v_lshl_add_u64 v[162:163], v[184:185], 1, s[38:39]
	global_store_dwordx2 v[162:163], v[160:161], off
	v_pk_fma_f32 v[164:165], v[120:121], v[198:199], v[152:153]
	v_pk_fma_f32 v[166:167], v[112:113], v[198:199], v[156:157]
	v_mov_b32_e32 v160, v198
	v_mov_b32_e32 v161, v198
	v_mul_f32_e32 v184, v136, v164
	v_mul_f32_e32 v190, v148, v166
	v_pk_fma_f32 v[162:163], v[122:123], v[160:161], v[154:155]
	v_pk_fma_f32 v[160:161], v[114:115], v[160:161], v[158:159]
	v_fmac_f32_dpp v184, v164, v132 row_shr:1 row_mask:0xf bank_mask:0xf bound_ctrl:1
	v_fmac_f32_dpp v184, v164, v128 row_shr:2 row_mask:0xf bank_mask:0xf bound_ctrl:1
	v_fmac_f32_dpp v190, v166, v144 row_shr:1 row_mask:0xf bank_mask:0xf bound_ctrl:1
	v_fmac_f32_dpp v190, v166, v140 row_shr:2 row_mask:0xf bank_mask:0xf bound_ctrl:1
	v_mul_f32_e32 v164, v137, v165
	v_mul_f32_e32 v166, v149, v167
	s_nop 0
	v_fmac_f32_dpp v164, v165, v133 row_shr:1 row_mask:0xf bank_mask:0xf bound_ctrl:1
	v_fmac_f32_dpp v164, v165, v129 row_shr:2 row_mask:0xf bank_mask:0xf bound_ctrl:1
	v_fmac_f32_dpp v166, v167, v145 row_shr:1 row_mask:0xf bank_mask:0xf bound_ctrl:1
	v_fmac_f32_dpp v166, v167, v141 row_shr:2 row_mask:0xf bank_mask:0xf bound_ctrl:1
	v_mul_f32_e32 v165, v138, v162
	v_mul_f32_e32 v167, v150, v160
	s_nop 0
	v_fmac_f32_dpp v165, v162, v134 row_shr:1 row_mask:0xf bank_mask:0xf bound_ctrl:1
	v_fmac_f32_dpp v165, v162, v130 row_shr:2 row_mask:0xf bank_mask:0xf bound_ctrl:1
	v_fmac_f32_dpp v167, v160, v146 row_shr:1 row_mask:0xf bank_mask:0xf bound_ctrl:1
	v_fmac_f32_dpp v167, v160, v142 row_shr:2 row_mask:0xf bank_mask:0xf bound_ctrl:1
	v_mul_f32_e32 v162, v139, v163
	v_fmac_f32_dpp v165, v170, v218 row_ror:1 row_mask:0xf bank_mask:0xf bound_ctrl:1
	v_fmac_f32_dpp v165, v170, v219 row_ror:2 row_mask:0xf bank_mask:0xf bound_ctrl:1
	v_fmac_f32_dpp v167, v168, v235 row_ror:1 row_mask:0xf bank_mask:0xf bound_ctrl:1
	v_fmac_f32_dpp v167, v168, v236 row_ror:2 row_mask:0xf bank_mask:0xf bound_ctrl:1
	v_mul_f32_e32 v168, v151, v161
	v_mul_f32_e32 v160, 0xbfb8aa3b, v165
	v_exp_f32_e32 v160, v160
	v_fmac_f32_dpp v164, v173, v237 row_ror:1 row_mask:0xf bank_mask:0xf bound_ctrl:1
	v_fmac_f32_dpp v164, v173, v238 row_ror:2 row_mask:0xf bank_mask:0xf bound_ctrl:1
	v_fmac_f32_dpp v166, v175, v239 row_ror:1 row_mask:0xf bank_mask:0xf bound_ctrl:1
	v_fmac_f32_dpp v166, v175, v240 row_ror:2 row_mask:0xf bank_mask:0xf bound_ctrl:1
	v_fmac_f32_dpp v162, v163, v135 row_shr:1 row_mask:0xf bank_mask:0xf bound_ctrl:1
	v_fmac_f32_dpp v162, v163, v131 row_shr:2 row_mask:0xf bank_mask:0xf bound_ctrl:1
	v_fmac_f32_dpp v168, v161, v147 row_shr:1 row_mask:0xf bank_mask:0xf bound_ctrl:1
	v_fmac_f32_dpp v168, v161, v143 row_shr:2 row_mask:0xf bank_mask:0xf bound_ctrl:1
; #define LAS __attribute__((address_space(3)))
; __device__ __forceinline__ unsigned pk2(float lo, float hi) { return pg8::cvt_pk_bf16(lo, hi); }
;     template <bool tail> __device__ __forceinline__ void run(f32x4 (&acc)[2][2][4][2], const pg8::Unit& u, int wr, int wc, int fr_in, int fq_in) const {
;     ...
;                 if (slot >= 0) { const LAS float* xp = xch + (slot * 2) * 256 + colg + 4 * n;
;                     g14 = *(const LAS f32x4*)(xp); g15 = *(const LAS f32x4*)(xp + 256); v14 = *(const LAS f32x4*)(xp + 128); v15 = *(const LAS f32x4*)(xp + 256 + 128); }
;                 f32x4 pg = g14, pv = g14;
; #pragma unroll
;                 for (int m = 0; m < 4; ++m) {
;                     const int r = rbase + 128 * ai + 16 * m;
;                     if (tail) { const float* bp = bias2 + (4 * ai + 2 * wr + (m >> 1)) * (2 * DFF) + chan0 + 4 * n; bg = *(const f32x4*)(bp); bvl = *(const f32x4*)(bp + DFF); }
;                     f32x4 cg_ = acc[ai][0][m][n] * rstd[ai][m] + bg, cv_ = acc[ai][1][m][n] * rstd[ai][m] + bvl;
;                     if (ai == 0 && m == 0) { if (zfirst) { cg_ = (f32x4){0.f, 0.f, 0.f, 0.f}; cv_ = cg_; } }
;                     float o[4];
; #pragma unroll
;                     for (int e = 0; e < 4; ++e) {
;                         float G = wg2[e] * cg_[e], V = wv2[e] * cv_[e];
;                         FMAC_DPP4(G, V, cg_[e], cv_[e], wg1[e], wg0[e], wv1[e], wv0[e], "row_shr:1", "row_shr:2");
;                         if (m == 0) { const float x2g = (fr == 0) ? g14[e] : g15[e], x2v = (fr == 0) ? v14[e] : v15[e];
;                             G = __builtin_fmaf(g15[e], ag[e], G); G = __builtin_fmaf(x2g, bgm[e], G); V = __builtin_fmaf(v15[e], av[e], V); V = __builtin_fmaf(x2v, bvm[e], V); }
;                         else { FMAC_DPP4(G, V, pg[e], pv[e], ag[e], bgm[e], av[e], bvm[e], "row_ror:1", "row_ror:2"); }
;                         o[e] = G * __builtin_amdgcn_rcpf(1.f + __expf(-G)) * V;
;                     }
;                     pg = cg_; pv = cv_;
;                     bool outv; int tg;
;                     if (tail) { outv = (m & 1) != 0; tg = (r >> 5) * S_ + 2016 + (r & 31); } else { outv = r >= 2; tg = tok0 + r; }
;                     if (outv) { u32x2 w; w.x = pk2(o[0], o[1]); w.y = pk2(o[2], o[3]); *(u32x2*)(act + ((unsigned)tg * DFF + chan0 + 4 * n)) = w; }
	v_fmac_f32_dpp v184, v172, v241 row_ror:1 row_mask:0xf bank_mask:0xf bound_ctrl:1
	v_fmac_f32_dpp v184, v172, v242 row_ror:2 row_mask:0xf bank_mask:0xf bound_ctrl:1
	v_fmac_f32_dpp v190, v174, v243 row_ror:1 row_mask:0xf bank_mask:0xf bound_ctrl:1
	v_fmac_f32_dpp v190, v174, v244 row_ror:2 row_mask:0xf bank_mask:0xf bound_ctrl:1
	s_nop 0
	v_add_f32_e32 v160, 1.0, v160
	v_rcp_f32_e32 v160, v160
	v_mul_f32_e32 v161, 0xbfb8aa3b, v164
	v_exp_f32_e32 v161, v161
	v_fmac_f32_dpp v162, v171, v210 row_ror:1 row_mask:0xf bank_mask:0xf bound_ctrl:1
	v_fmac_f32_dpp v162, v171, v211 row_ror:2 row_mask:0xf bank_mask:0xf bound_ctrl:1
	v_fmac_f32_dpp v168, v169, v216 row_ror:1 row_mask:0xf bank_mask:0xf bound_ctrl:1
	v_fmac_f32_dpp v168, v169, v217 row_ror:2 row_mask:0xf bank_mask:0xf bound_ctrl:1
	v_mul_f32_e32 v160, v165, v160
	v_mul_f32_e32 v163, v167, v160
	v_add_f32_e32 v160, 1.0, v161
	v_mul_f32_e32 v161, 0xbfb8aa3b, v184
	v_mul_f32_e32 v165, 0xbfb8aa3b, v162
	v_rcp_f32_e32 v160, v160
	v_exp_f32_e32 v161, v161
	v_exp_f32_e32 v165, v165
	v_mul_f32_e32 v160, v164, v160
	v_add_f32_e32 v161, 1.0, v161
	v_add_f32_e32 v164, 1.0, v165
	v_rcp_f32_e32 v161, v161
	v_rcp_f32_e32 v164, v164
	v_mul_f32_e32 v160, v166, v160
	v_mul_f32_e32 v161, v184, v161
	v_mul_f32_e32 v162, v162, v164
	v_mul_f32_e32 v161, v190, v161
	v_mul_f32_e32 v162, v168, v162
	v_add_u32_e32 v184, v204, v231
	v_cvt_pk_bf16_f32 v160, v161, v160
	v_cvt_pk_bf16_f32 v161, v163, v162
	v_lshl_add_u64 v[162:163], v[184:185], 1, s[38:39]
	global_store_dwordx2 v[162:163], v[160:161], off
	v_mov_b32_e32 v160, v206
	v_mov_b32_e32 v161, v206
	v_pk_fma_f32 v[190:191], v[22:23], v[160:161], v[154:155]
	v_pk_fma_f32 v[212:213], v[18:19], v[160:161], v[158:159]
	ds_read_b128 v[160:163], v230 offset:3600
	ds_read_b128 v[164:167], v230 offset:3088
	ds_read_b128 v[168:171], v230 offset:2576
	ds_read_b128 v[172:175], v230 offset:2064
	v_mul_f32_e32 v220, v138, v190
	v_mul_f32_e32 v221, v150, v212
	s_nop 0
	v_fmac_f32_dpp v220, v190, v134 row_shr:1 row_mask:0xf bank_mask:0xf bound_ctrl:1
	v_fmac_f32_dpp v220, v190, v130 row_shr:2 row_mask:0xf bank_mask:0xf bound_ctrl:1
	v_fmac_f32_dpp v221, v212, v146 row_shr:1 row_mask:0xf bank_mask:0xf bound_ctrl:1
	v_fmac_f32_dpp v221, v212, v142 row_shr:2 row_mask:0xf bank_mask:0xf bound_ctrl:1
	v_pk_fma_f32 v[198:199], v[20:21], v[206:207], v[152:153]
	s_waitcnt lgkmcnt(0)
	v_cndmask_b32_e64 v174, v166, v174, s[10:11]
	v_fmac_f32_e32 v220, v166, v218
	v_fmac_f32_e32 v220, v174, v219
	v_mul_f32_e32 v166, 0xbfb8aa3b, v220
	v_exp_f32_e32 v166, v166
	v_pk_fma_f32 v[206:207], v[16:17], v[206:207], v[156:157]
	v_mul_f32_e32 v214, v137, v199
	v_mul_f32_e32 v215, v149, v207
	s_nop 0
	v_fmac_f32_dpp v214, v199, v133 row_shr:1 row_mask:0xf bank_mask:0xf bound_ctrl:1
	v_fmac_f32_dpp v214, v199, v129 row_shr:2 row_mask:0xf bank_mask:0xf bound_ctrl:1
	v_fmac_f32_dpp v215, v207, v145 row_shr:1 row_mask:0xf bank_mask:0xf bound_ctrl:1
	v_fmac_f32_dpp v215, v207, v141 row_shr:2 row_mask:0xf bank_mask:0xf bound_ctrl:1
	v_cndmask_b32_e64 v170, v162, v170, s[10:11]
	v_fmac_f32_e32 v221, v162, v235
	v_add_f32_e32 v162, 1.0, v166
	v_cndmask_b32_e64 v166, v165, v173, s[10:11]
	v_fmac_f32_e32 v214, v165, v237
	v_fmac_f32_e32 v214, v166, v238
	v_mul_f32_e32 v165, 0xbfb8aa3b, v214
	v_exp_f32_e32 v165, v165
	v_mul_f32_e32 v184, v136, v198
	v_mul_f32_e32 v205, v148, v206
	s_nop 0
	v_fmac_f32_dpp v184, v198, v132 row_shr:1 row_mask:0xf bank_mask:0xf bound_ctrl:1
	v_fmac_f32_dpp v184, v198, v128 row_shr:2 row_mask:0xf bank_mask:0xf bound_ctrl:1
	v_fmac_f32_dpp v205, v206, v144 row_shr:1 row_mask:0xf bank_mask:0xf bound_ctrl:1
	v_fmac_f32_dpp v205, v206, v140 row_shr:2 row_mask:0xf bank_mask:0xf bound_ctrl:1
	v_add_f32_e32 v165, 1.0, v165
	v_rcp_f32_e32 v165, v165
	v_cndmask_b32_e64 v166, v161, v169, s[10:11]
	v_fmac_f32_e32 v215, v161, v239
	v_fmac_f32_e32 v184, v164, v241
	v_mul_f32_e32 v161, v214, v165
	v_cndmask_b32_e64 v165, v164, v172, s[10:11]
	v_fmac_f32_e32 v184, v165, v242
	v_mul_f32_e32 v164, 0xbfb8aa3b, v184
	v_exp_f32_e32 v164, v164
	v_mul_f32_e32 v230, v139, v191
	v_mul_f32_e32 v231, v151, v213
	s_nop 0
	v_fmac_f32_dpp v230, v191, v135 row_shr:1 row_mask:0xf bank_mask:0xf bound_ctrl:1
	v_fmac_f32_dpp v230, v191, v131 row_shr:2 row_mask:0xf bank_mask:0xf bound_ctrl:1
	v_fmac_f32_dpp v231, v213, v147 row_shr:1 row_mask:0xf bank_mask:0xf bound_ctrl:1
	v_fmac_f32_dpp v231, v213, v143 row_shr:2 row_mask:0xf bank_mask:0xf bound_ctrl:1
	v_cndmask_b32_e64 v165, v160, v168, s[10:11]
	v_fmac_f32_e32 v205, v160, v243
	v_add_f32_e32 v160, 1.0, v164
	v_cndmask_b32_e64 v164, v167, v175, s[10:11]
	v_fmac_f32_e32 v230, v167, v210
	v_fmac_f32_e32 v230, v164, v211
	v_mul_f32_e32 v164, 0xbfb8aa3b, v230
	v_exp_f32_e32 v164, v164
	v_rcp_f32_e32 v162, v162
	v_rcp_f32_e32 v160, v160
	v_fmac_f32_e32 v205, v165, v244
	v_add_f32_e32 v164, 1.0, v164
	v_rcp_f32_e32 v164, v164
	v_cndmask_b32_e64 v165, v163, v171, s[10:11]
	v_fmac_f32_e32 v231, v163, v216
	v_fmac_f32_e32 v221, v170, v236
	v_mul_f32_e32 v162, v220, v162
	v_fmac_f32_e32 v215, v166, v240
	v_mul_f32_e32 v160, v184, v160
	v_fmac_f32_e32 v231, v165, v217
	v_mul_f32_e32 v163, v230, v164
	v_mul_f32_e32 v162, v221, v162
	v_mul_f32_e32 v161, v215, v161
	v_mul_f32_e32 v160, v205, v160
	v_mul_f32_e32 v163, v231, v163
	v_add_u32_e32 v184, v232, v204
	v_cvt_pk_bf16_f32 v160, v160, v161
	v_cvt_pk_bf16_f32 v161, v162, v163
	v_lshl_add_u64 v[162:163], v[184:185], 1, s[38:39]
	global_store_dwordx2 v[162:163], v[160:161], off
	v_mov_b32_e32 v160, v202
	v_mov_b32_e32 v161, v202
	v_pk_fma_f32 v[162:163], v[14:15], v[160:161], v[154:155]
	v_pk_fma_f32 v[160:161], v[10:11], v[160:161], v[158:159]
; __device__ __forceinline__ unsigned pk2(float lo, float hi) { return pg8::cvt_pk_bf16(lo, hi); }
;     template <bool tail> __device__ __forceinline__ void run(f32x4 (&acc)[2][2][4][2], const pg8::Unit& u, int wr, int wc, int fr_in, int fq_in) const {
;     ...
; #pragma unroll
;                 for (int m = 0; m < 4; ++m) {
;                     const int r = rbase + 128 * ai + 16 * m;
;                     if (tail) { const float* bp = bias2 + (4 * ai + 2 * wr + (m >> 1)) * (2 * DFF) + chan0 + 4 * n; bg = *(const f32x4*)(bp); bvl = *(const f32x4*)(bp + DFF); }
;                     f32x4 cg_ = acc[ai][0][m][n] * rstd[ai][m] + bg, cv_ = acc[ai][1][m][n] * rstd[ai][m] + bvl;
;                     if (ai == 0 && m == 0) { if (zfirst) { cg_ = (f32x4){0.f, 0.f, 0.f, 0.f}; cv_ = cg_; } }
;                     float o[4];
; #pragma unroll
;                     for (int e = 0; e < 4; ++e) {
;                         float G = wg2[e] * cg_[e], V = wv2[e] * cv_[e];
;                         FMAC_DPP4(G, V, cg_[e], cv_[e], wg1[e], wg0[e], wv1[e], wv0[e], "row_shr:1", "row_shr:2");
;                         if (m == 0) { const float x2g = (fr == 0) ? g14[e] : g15[e], x2v = (fr == 0) ? v14[e] : v15[e];
;                             G = __builtin_fmaf(g15[e], ag[e], G); G = __builtin_fmaf(x2g, bgm[e], G); V = __builtin_fmaf(v15[e], av[e], V); V = __builtin_fmaf(x2v, bvm[e], V); }
;                         else { FMAC_DPP4(G, V, pg[e], pv[e], ag[e], bgm[e], av[e], bvm[e], "row_ror:1", "row_ror:2"); }
;                         o[e] = G * __builtin_amdgcn_rcpf(1.f + __expf(-G)) * V;
;                     }
;                     pg = cg_; pv = cv_;
;                     bool outv; int tg;
;                     if (tail) { outv = (m & 1) != 0; tg = (r >> 5) * S_ + 2016 + (r & 31); } else { outv = r >= 2; tg = tok0 + r; }
;                     if (outv) { u32x2 w; w.x = pk2(o[0], o[1]); w.y = pk2(o[2], o[3]); *(u32x2*)(act + ((unsigned)tg * DFF + chan0 + 4 * n)) = w; }
	v_mul_f32_e32 v172, v138, v162
	v_mul_f32_e32 v173, v150, v160
	s_nop 0
	v_fmac_f32_dpp v172, v162, v134 row_shr:1 row_mask:0xf bank_mask:0xf bound_ctrl:1
	v_fmac_f32_dpp v172, v162, v130 row_shr:2 row_mask:0xf bank_mask:0xf bound_ctrl:1
	v_fmac_f32_dpp v173, v160, v146 row_shr:1 row_mask:0xf bank_mask:0xf bound_ctrl:1
	v_fmac_f32_dpp v173, v160, v142 row_shr:2 row_mask:0xf bank_mask:0xf bound_ctrl:1
	v_pk_fma_f32 v[164:165], v[12:13], v[202:203], v[152:153]
	v_fmac_f32_dpp v172, v190, v218 row_ror:1 row_mask:0xf bank_mask:0xf bound_ctrl:1
	v_fmac_f32_dpp v172, v190, v219 row_ror:2 row_mask:0xf bank_mask:0xf bound_ctrl:1
	v_fmac_f32_dpp v173, v212, v235 row_ror:1 row_mask:0xf bank_mask:0xf bound_ctrl:1
	v_fmac_f32_dpp v173, v212, v236 row_ror:2 row_mask:0xf bank_mask:0xf bound_ctrl:1
	v_pk_fma_f32 v[166:167], v[8:9], v[202:203], v[156:157]
	v_mul_f32_e32 v174, 0xbfb8aa3b, v172
	v_exp_f32_e32 v174, v174
	v_mul_f32_e32 v170, v137, v165
	v_mul_f32_e32 v171, v149, v167
	s_nop 0
	v_fmac_f32_dpp v170, v165, v133 row_shr:1 row_mask:0xf bank_mask:0xf bound_ctrl:1
	v_fmac_f32_dpp v170, v165, v129 row_shr:2 row_mask:0xf bank_mask:0xf bound_ctrl:1
	v_fmac_f32_dpp v171, v167, v145 row_shr:1 row_mask:0xf bank_mask:0xf bound_ctrl:1
	v_fmac_f32_dpp v171, v167, v141 row_shr:2 row_mask:0xf bank_mask:0xf bound_ctrl:1
	v_add_f32_e32 v174, 1.0, v174
	v_fmac_f32_dpp v170, v199, v237 row_ror:1 row_mask:0xf bank_mask:0xf bound_ctrl:1
	v_fmac_f32_dpp v170, v199, v238 row_ror:2 row_mask:0xf bank_mask:0xf bound_ctrl:1
	v_fmac_f32_dpp v171, v207, v239 row_ror:1 row_mask:0xf bank_mask:0xf bound_ctrl:1
	v_fmac_f32_dpp v171, v207, v240 row_ror:2 row_mask:0xf bank_mask:0xf bound_ctrl:1
	v_rcp_f32_e32 v174, v174
	v_mul_f32_e32 v190, 0xbfb8aa3b, v170
	v_exp_f32_e32 v190, v190
	v_mul_f32_e32 v168, v136, v164
	v_mul_f32_e32 v169, v148, v166
	s_nop 0
	v_fmac_f32_dpp v168, v164, v132 row_shr:1 row_mask:0xf bank_mask:0xf bound_ctrl:1
	v_fmac_f32_dpp v168, v164, v128 row_shr:2 row_mask:0xf bank_mask:0xf bound_ctrl:1
	v_fmac_f32_dpp v169, v166, v144 row_shr:1 row_mask:0xf bank_mask:0xf bound_ctrl:1
	v_fmac_f32_dpp v169, v166, v140 row_shr:2 row_mask:0xf bank_mask:0xf bound_ctrl:1
	v_mul_f32_e32 v175, v139, v163
	v_mul_f32_e32 v184, v151, v161
	v_mul_f32_e32 v172, v172, v174
	v_fmac_f32_dpp v168, v198, v241 row_ror:1 row_mask:0xf bank_mask:0xf bound_ctrl:1
	v_fmac_f32_dpp v168, v198, v242 row_ror:2 row_mask:0xf bank_mask:0xf bound_ctrl:1
	v_fmac_f32_dpp v169, v206, v243 row_ror:1 row_mask:0xf bank_mask:0xf bound_ctrl:1
	v_fmac_f32_dpp v169, v206, v244 row_ror:2 row_mask:0xf bank_mask:0xf bound_ctrl:1
	v_fmac_f32_dpp v175, v163, v135 row_shr:1 row_mask:0xf bank_mask:0xf bound_ctrl:1
	v_fmac_f32_dpp v175, v163, v131 row_shr:2 row_mask:0xf bank_mask:0xf bound_ctrl:1
	v_fmac_f32_dpp v184, v161, v147 row_shr:1 row_mask:0xf bank_mask:0xf bound_ctrl:1
	v_fmac_f32_dpp v184, v161, v143 row_shr:2 row_mask:0xf bank_mask:0xf bound_ctrl:1
	v_mul_f32_e32 v172, v173, v172
	v_add_f32_e32 v173, 1.0, v190
	v_mul_f32_e32 v174, 0xbfb8aa3b, v168
	v_fmac_f32_dpp v175, v191, v210 row_ror:1 row_mask:0xf bank_mask:0xf bound_ctrl:1
	v_fmac_f32_dpp v175, v191, v211 row_ror:2 row_mask:0xf bank_mask:0xf bound_ctrl:1
	v_fmac_f32_dpp v184, v213, v216 row_ror:1 row_mask:0xf bank_mask:0xf bound_ctrl:1
	v_fmac_f32_dpp v184, v213, v217 row_ror:2 row_mask:0xf bank_mask:0xf bound_ctrl:1
	v_rcp_f32_e32 v173, v173
	v_exp_f32_e32 v174, v174
	v_mul_f32_e32 v190, 0xbfb8aa3b, v175
	v_exp_f32_e32 v190, v190
	v_mul_f32_e32 v170, v170, v173
	v_add_f32_e32 v173, 1.0, v174
	v_rcp_f32_e32 v173, v173
	v_add_f32_e32 v174, 1.0, v190
	v_rcp_f32_e32 v174, v174
	v_mul_f32_e32 v170, v171, v170
	v_mul_f32_e32 v168, v168, v173
	v_mul_f32_e32 v168, v169, v168
	v_mul_f32_e32 v169, v175, v174
	v_mul_f32_e32 v169, v184, v169
	v_add_u32_e32 v184, v229, v204
	v_cvt_pk_bf16_f32 v168, v168, v170
	v_lshl_add_u64 v[170:171], v[184:185], 1, s[38:39]
	v_cvt_pk_bf16_f32 v169, v172, v169
	global_store_dwordx2 v[170:171], v[168:169], off
	v_pk_fma_f32 v[172:173], v[4:5], v[200:201], v[152:153]
	v_pk_fma_f32 v[174:175], v[0:1], v[200:201], v[156:157]
	v_mul_f32_e32 v184, v136, v172
	v_mul_f32_e32 v190, v148, v174
	s_nop 0
	v_fmac_f32_dpp v184, v172, v132 row_shr:1 row_mask:0xf bank_mask:0xf bound_ctrl:1
	v_fmac_f32_dpp v184, v172, v128 row_shr:2 row_mask:0xf bank_mask:0xf bound_ctrl:1
	v_fmac_f32_dpp v190, v174, v144 row_shr:1 row_mask:0xf bank_mask:0xf bound_ctrl:1
	v_fmac_f32_dpp v190, v174, v140 row_shr:2 row_mask:0xf bank_mask:0xf bound_ctrl:1
	v_mov_b32_e32 v168, v200
	v_mov_b32_e32 v169, v200
	v_fmac_f32_dpp v184, v164, v241 row_ror:1 row_mask:0xf bank_mask:0xf bound_ctrl:1
	v_fmac_f32_dpp v184, v164, v242 row_ror:2 row_mask:0xf bank_mask:0xf bound_ctrl:1
	v_fmac_f32_dpp v190, v166, v243 row_ror:1 row_mask:0xf bank_mask:0xf bound_ctrl:1
	v_fmac_f32_dpp v190, v166, v244 row_ror:2 row_mask:0xf bank_mask:0xf bound_ctrl:1
	v_mul_f32_e32 v164, v137, v173
	v_mul_f32_e32 v166, v149, v175
	v_pk_fma_f32 v[170:171], v[6:7], v[168:169], v[154:155]
	v_pk_fma_f32 v[168:169], v[2:3], v[168:169], v[158:159]
	v_fmac_f32_dpp v164, v173, v133 row_shr:1 row_mask:0xf bank_mask:0xf bound_ctrl:1
	v_fmac_f32_dpp v164, v173, v129 row_shr:2 row_mask:0xf bank_mask:0xf bound_ctrl:1
	v_fmac_f32_dpp v166, v175, v145 row_shr:1 row_mask:0xf bank_mask:0xf bound_ctrl:1
	v_fmac_f32_dpp v166, v175, v141 row_shr:2 row_mask:0xf bank_mask:0xf bound_ctrl:1
	s_nop 0
	v_fmac_f32_dpp v164, v165, v237 row_ror:1 row_mask:0xf bank_mask:0xf bound_ctrl:1
	v_fmac_f32_dpp v164, v165, v238 row_ror:2 row_mask:0xf bank_mask:0xf bound_ctrl:1
	v_fmac_f32_dpp v166, v167, v239 row_ror:1 row_mask:0xf bank_mask:0xf bound_ctrl:1
; __device__ __forceinline__ unsigned pk2(float lo, float hi) { return pg8::cvt_pk_bf16(lo, hi); }
;     template <bool tail> __device__ __forceinline__ void run(f32x4 (&acc)[2][2][4][2], const pg8::Unit& u, int wr, int wc, int fr_in, int fq_in) const {
;     ...
; #pragma unroll
;                 for (int m = 0; m < 4; ++m) {
;                     const int r = rbase + 128 * ai + 16 * m;
;                     if (tail) { const float* bp = bias2 + (4 * ai + 2 * wr + (m >> 1)) * (2 * DFF) + chan0 + 4 * n; bg = *(const f32x4*)(bp); bvl = *(const f32x4*)(bp + DFF); }
;                     f32x4 cg_ = acc[ai][0][m][n] * rstd[ai][m] + bg, cv_ = acc[ai][1][m][n] * rstd[ai][m] + bvl;
;                     if (ai == 0 && m == 0) { if (zfirst) { cg_ = (f32x4){0.f, 0.f, 0.f, 0.f}; cv_ = cg_; } }
;                     float o[4];
; #pragma unroll
;                     for (int e = 0; e < 4; ++e) {
;                         float G = wg2[e] * cg_[e], V = wv2[e] * cv_[e];
;                         FMAC_DPP4(G, V, cg_[e], cv_[e], wg1[e], wg0[e], wv1[e], wv0[e], "row_shr:1", "row_shr:2");
;                         if (m == 0) { const float x2g = (fr == 0) ? g14[e] : g15[e], x2v = (fr == 0) ? v14[e] : v15[e];
;                             G = __builtin_fmaf(g15[e], ag[e], G); G = __builtin_fmaf(x2g, bgm[e], G); V = __builtin_fmaf(v15[e], av[e], V); V = __builtin_fmaf(x2v, bvm[e], V); }
;                         else { FMAC_DPP4(G, V, pg[e], pv[e], ag[e], bgm[e], av[e], bvm[e], "row_ror:1", "row_ror:2"); }
;                         o[e] = G * __builtin_amdgcn_rcpf(1.f + __expf(-G)) * V;
;                     }
;                     pg = cg_; pv = cv_;
;                     bool outv; int tg;
;                     if (tail) { outv = (m & 1) != 0; tg = (r >> 5) * S_ + 2016 + (r & 31); } else { outv = r >= 2; tg = tok0 + r; }
;                     if (outv) { u32x2 w; w.x = pk2(o[0], o[1]); w.y = pk2(o[2], o[3]); *(u32x2*)(act + ((unsigned)tg * DFF + chan0 + 4 * n)) = w; }
;                     __builtin_amdgcn_sched_barrier(0);
;                 }
	v_fmac_f32_dpp v166, v167, v240 row_ror:2 row_mask:0xf bank_mask:0xf bound_ctrl:1
	v_mul_f32_e32 v165, v138, v170
	v_mul_f32_e32 v167, v150, v168
	s_nop 0
	v_fmac_f32_dpp v165, v170, v134 row_shr:1 row_mask:0xf bank_mask:0xf bound_ctrl:1
	v_fmac_f32_dpp v165, v170, v130 row_shr:2 row_mask:0xf bank_mask:0xf bound_ctrl:1
	v_fmac_f32_dpp v167, v168, v146 row_shr:1 row_mask:0xf bank_mask:0xf bound_ctrl:1
	v_fmac_f32_dpp v167, v168, v142 row_shr:2 row_mask:0xf bank_mask:0xf bound_ctrl:1
	v_mul_f32_e32 v198, 0xbfb8aa3b, v164
	v_fmac_f32_dpp v165, v162, v218 row_ror:1 row_mask:0xf bank_mask:0xf bound_ctrl:1
	v_fmac_f32_dpp v165, v162, v219 row_ror:2 row_mask:0xf bank_mask:0xf bound_ctrl:1
	v_fmac_f32_dpp v167, v160, v235 row_ror:1 row_mask:0xf bank_mask:0xf bound_ctrl:1
	v_fmac_f32_dpp v167, v160, v236 row_ror:2 row_mask:0xf bank_mask:0xf bound_ctrl:1
	v_exp_f32_e32 v198, v198
	v_mul_f32_e32 v160, 0xbfb8aa3b, v165
	v_exp_f32_e32 v160, v160
	v_mul_f32_e32 v162, v139, v171
	v_mul_f32_e32 v191, v151, v169
	s_nop 0
	v_fmac_f32_dpp v162, v171, v135 row_shr:1 row_mask:0xf bank_mask:0xf bound_ctrl:1
	v_fmac_f32_dpp v162, v171, v131 row_shr:2 row_mask:0xf bank_mask:0xf bound_ctrl:1
	v_fmac_f32_dpp v191, v169, v147 row_shr:1 row_mask:0xf bank_mask:0xf bound_ctrl:1
	v_fmac_f32_dpp v191, v169, v143 row_shr:2 row_mask:0xf bank_mask:0xf bound_ctrl:1
	v_add_f32_e32 v160, 1.0, v160
	v_rcp_f32_e32 v160, v160
	v_fmac_f32_dpp v162, v163, v210 row_ror:1 row_mask:0xf bank_mask:0xf bound_ctrl:1
	v_fmac_f32_dpp v162, v163, v211 row_ror:2 row_mask:0xf bank_mask:0xf bound_ctrl:1
	v_fmac_f32_dpp v191, v161, v216 row_ror:1 row_mask:0xf bank_mask:0xf bound_ctrl:1
	v_fmac_f32_dpp v191, v161, v217 row_ror:2 row_mask:0xf bank_mask:0xf bound_ctrl:1
	v_mul_f32_e32 v163, 0xbfb8aa3b, v184
	v_exp_f32_e32 v163, v163
	v_mul_f32_e32 v160, v165, v160
	v_mul_f32_e32 v161, v167, v160
	v_add_f32_e32 v160, 1.0, v198
	v_mul_f32_e32 v165, 0xbfb8aa3b, v162
	v_rcp_f32_e32 v160, v160
	v_exp_f32_e32 v165, v165
	v_add_f32_e32 v163, 1.0, v163
	v_rcp_f32_e32 v163, v163
	v_mul_f32_e32 v160, v164, v160
	v_add_f32_e32 v164, 1.0, v165
	v_rcp_f32_e32 v164, v164
	v_mul_f32_e32 v163, v184, v163
	v_mul_f32_e32 v160, v166, v160
	v_mul_f32_e32 v163, v190, v163
	v_mul_f32_e32 v162, v162, v164
	v_mul_f32_e32 v162, v191, v162
	v_add_u32_e32 v184, v228, v204
	v_cvt_pk_bf16_f32 v160, v163, v160
	v_cvt_pk_bf16_f32 v161, v161, v162
	v_lshl_add_u64 v[162:163], v[184:185], 1, s[38:39]
	global_store_dwordx2 v[162:163], v[160:161], off
	v_pk_fma_f32 v[152:153], v[104:105], v[196:197], v[152:153]
	v_pk_fma_f32 v[156:157], v[96:97], v[196:197], v[156:157]
	v_mov_b32_e32 v160, v196
	v_mov_b32_e32 v161, v196
	v_mul_f32_e32 v136, v136, v152
	v_mul_f32_e32 v148, v148, v156
	v_pk_fma_f32 v[154:155], v[106:107], v[160:161], v[154:155]
	v_pk_fma_f32 v[158:159], v[98:99], v[160:161], v[158:159]
	v_fmac_f32_dpp v136, v152, v132 row_shr:1 row_mask:0xf bank_mask:0xf bound_ctrl:1
	v_fmac_f32_dpp v136, v152, v128 row_shr:2 row_mask:0xf bank_mask:0xf bound_ctrl:1
	v_fmac_f32_dpp v148, v156, v144 row_shr:1 row_mask:0xf bank_mask:0xf bound_ctrl:1
	v_fmac_f32_dpp v148, v156, v140 row_shr:2 row_mask:0xf bank_mask:0xf bound_ctrl:1
	v_mul_f32_e32 v128, v137, v153
	v_mul_f32_e32 v132, v149, v157
	s_nop 0
	v_fmac_f32_dpp v128, v153, v133 row_shr:1 row_mask:0xf bank_mask:0xf bound_ctrl:1
	v_fmac_f32_dpp v128, v153, v129 row_shr:2 row_mask:0xf bank_mask:0xf bound_ctrl:1
	v_fmac_f32_dpp v132, v157, v145 row_shr:1 row_mask:0xf bank_mask:0xf bound_ctrl:1
	v_fmac_f32_dpp v132, v157, v141 row_shr:2 row_mask:0xf bank_mask:0xf bound_ctrl:1
	v_mul_f32_e32 v129, v138, v154
	v_mul_f32_e32 v133, v150, v158
	s_nop 0
	v_fmac_f32_dpp v129, v154, v134 row_shr:1 row_mask:0xf bank_mask:0xf bound_ctrl:1
	v_fmac_f32_dpp v129, v154, v130 row_shr:2 row_mask:0xf bank_mask:0xf bound_ctrl:1
	v_fmac_f32_dpp v133, v158, v146 row_shr:1 row_mask:0xf bank_mask:0xf bound_ctrl:1
	v_fmac_f32_dpp v133, v158, v142 row_shr:2 row_mask:0xf bank_mask:0xf bound_ctrl:1
	v_mul_f32_e32 v134, v139, v155
	v_fmac_f32_dpp v129, v170, v218 row_ror:1 row_mask:0xf bank_mask:0xf bound_ctrl:1
	v_fmac_f32_dpp v129, v170, v219 row_ror:2 row_mask:0xf bank_mask:0xf bound_ctrl:1
	v_fmac_f32_dpp v133, v168, v235 row_ror:1 row_mask:0xf bank_mask:0xf bound_ctrl:1
	v_fmac_f32_dpp v133, v168, v236 row_ror:2 row_mask:0xf bank_mask:0xf bound_ctrl:1
	v_mul_f32_e32 v137, v151, v159
	v_mul_f32_e32 v130, 0xbfb8aa3b, v129
	v_exp_f32_e32 v130, v130
	v_fmac_f32_dpp v128, v173, v237 row_ror:1 row_mask:0xf bank_mask:0xf bound_ctrl:1
	v_fmac_f32_dpp v128, v173, v238 row_ror:2 row_mask:0xf bank_mask:0xf bound_ctrl:1
	v_fmac_f32_dpp v132, v175, v239 row_ror:1 row_mask:0xf bank_mask:0xf bound_ctrl:1
	v_fmac_f32_dpp v132, v175, v240 row_ror:2 row_mask:0xf bank_mask:0xf bound_ctrl:1
	v_fmac_f32_dpp v134, v155, v135 row_shr:1 row_mask:0xf bank_mask:0xf bound_ctrl:1
	v_fmac_f32_dpp v134, v155, v131 row_shr:2 row_mask:0xf bank_mask:0xf bound_ctrl:1
	v_fmac_f32_dpp v137, v159, v147 row_shr:1 row_mask:0xf bank_mask:0xf bound_ctrl:1
	v_fmac_f32_dpp v137, v159, v143 row_shr:2 row_mask:0xf bank_mask:0xf bound_ctrl:1
	v_fmac_f32_dpp v136, v172, v241 row_ror:1 row_mask:0xf bank_mask:0xf bound_ctrl:1
	v_fmac_f32_dpp v136, v172, v242 row_ror:2 row_mask:0xf bank_mask:0xf bound_ctrl:1
	v_fmac_f32_dpp v148, v174, v243 row_ror:1 row_mask:0xf bank_mask:0xf bound_ctrl:1
	v_fmac_f32_dpp v148, v174, v244 row_ror:2 row_mask:0xf bank_mask:0xf bound_ctrl:1
	v_add_u32_e32 v184, v227, v204
	v_add_f32_e32 v130, 1.0, v130
	v_rcp_f32_e32 v130, v130
	v_mul_f32_e32 v131, 0xbfb8aa3b, v128
	v_exp_f32_e32 v131, v131
	v_fmac_f32_dpp v134, v171, v210 row_ror:1 row_mask:0xf bank_mask:0xf bound_ctrl:1
	v_fmac_f32_dpp v134, v171, v211 row_ror:2 row_mask:0xf bank_mask:0xf bound_ctrl:1
	v_fmac_f32_dpp v137, v169, v216 row_ror:1 row_mask:0xf bank_mask:0xf bound_ctrl:1
	v_fmac_f32_dpp v137, v169, v217 row_ror:2 row_mask:0xf bank_mask:0xf bound_ctrl:1
	v_mul_f32_e32 v129, v129, v130
	v_mul_f32_e32 v129, v133, v129
	v_add_f32_e32 v130, 1.0, v131
	v_mul_f32_e32 v131, 0xbfb8aa3b, v136
	v_mul_f32_e32 v133, 0xbfb8aa3b, v134
	v_rcp_f32_e32 v130, v130
	v_exp_f32_e32 v131, v131
	v_exp_f32_e32 v133, v133
	v_mul_f32_e32 v128, v128, v130
	v_add_f32_e32 v130, 1.0, v131
	v_add_f32_e32 v131, 1.0, v133
	v_rcp_f32_e32 v130, v130
	v_rcp_f32_e32 v131, v131
	v_mul_f32_e32 v128, v132, v128
	v_mul_f32_e32 v130, v136, v130
	v_mul_f32_e32 v131, v134, v131
	v_mul_f32_e32 v130, v148, v130
	v_mul_f32_e32 v131, v137, v131
	v_cvt_pk_bf16_f32 v128, v130, v128
	v_cvt_pk_bf16_f32 v129, v129, v131
	v_lshl_add_u64 v[130:131], v[184:185], 1, s[38:39]
	global_store_dwordx2 v[130:131], v[128:129], off
	v_mov_b64_e32 v[248:249], v[192:193]
	s_branch .LBB0_578

; #define LAS __attribute__((address_space(3)))
;     template <bool tail> __device__ __forceinline__ void run(f32x4 (&acc)[2][2][4][2], const pg8::Unit& u, int wr, int wc, int fr_in, int fq_in) const {
;     ...
; #pragma unroll
;         for (int ai = 0; ai < 2; ++ai)
; #pragma unroll
;             for (int m = 0; m < 4; ++m) {
;                 const int r = rbase + 128 * ai + 16 * m; int grow = tail ? (r >> 5) * S_ + 2016 + (r & 31) : tok0 + r; grow = grow < 0 ? 0 : grow;
;                 const f32x4 s4 = *(const f32x4*)(rowss + (unsigned)grow * 16 + 4 * fq); float sq = (s4.x + s4.y) + (s4.z + s4.w); sq += __shfl_xor(sq, 16); sq += __shfl_xor(sq, 32);
;                 rstd[ai][m] = rsqrtf(sq * (1.f / D_) + EPS);
;             }
; #pragma unroll
;         for (int ai = 0; ai < 2; ++ai) { const float* bp = bias2 + (tail ? (4 * ai + 2 * wr + 1) : breg) * (2 * DFF) + chan0;
; #pragma unroll
;             for (int bj = 0; bj < 2; ++bj)
; #pragma unroll
;                 for (int n = 0; n < 2; ++n) { const f32x4 v = acc[ai][bj][3][n] * rstd[ai][3] + *(const f32x4*)(bp + bj * DFF + 4 * n);
;                     if (fr >= 14) *(LAS f32x4*)(xch + (((2 * ai + wr) * 2 + (fr - 14)) * 256 + 128 * bj + colg + 4 * n)) = v; } }
;         asm volatile("s_waitcnt lgkmcnt(0)" ::: "memory"); __builtin_amdgcn_s_barrier(); asm volatile("" ::: "memory");
; #pragma unroll
;         for (int n = 0; n < 2; ++n) {
;             const float* wp = fcw + chan0 + 4 * n;
;             const f32x4 wg0 = *(const f32x4*)(wp), wg1 = *(const f32x4*)(wp + 2 * DFF), wg2 = *(const f32x4*)(wp + 4 * DFF);
;             const f32x4 wv0 = *(const f32x4*)(wp + DFF), wv1 = *(const f32x4*)(wp + 3 * DFF), wv2 = *(const f32x4*)(wp + 5 * DFF);
;             f32x4 bg = (f32x4){0.f, 0.f, 0.f, 0.f}, bvl = bg;
;             if (!tail) { bg = *(const f32x4*)(bias2 + breg * (2 * DFF) + chan0 + 4 * n); bvl = *(const f32x4*)(bias2 + breg * (2 * DFF) + DFF + chan0 + 4 * n); }
;             f32x4 ag, bgm, av, bvm;
; #pragma unroll
;             for (int e = 0; e < 4; ++e) { ag[e] = fr == 0 ? wg1[e] : 0.f; bgm[e] = fr < 2 ? wg0[e] : 0.f; av[e] = fr == 0 ? wv1[e] : 0.f; bvm[e] = fr < 2 ? wv0[e] : 0.f; }
; #pragma unroll
;             for (int ai = 0; ai < 2; ++ai) {
;                 const int slot = 2 * ai + wr - 1;
;                 f32x4 g14 = (f32x4){0.f, 0.f, 0.f, 0.f}, g15 = g14, v14 = g14, v15 = g14;
.LBB0_597:
	s_or_b64 exec, exec, s[10:11]
	v_lshl_add_u64 v[174:175], s[30:31], 0, v[164:165]
	s_movk_i32 s0, 0x5000
	v_add_co_u32_e32 v196, vcc, s0, v174
	s_mov_b32 s0, 0xb000
	s_nop 0
	v_addc_co_u32_e32 v197, vcc, 0, v175, vcc
	v_add_co_u32_e32 v198, vcc, s80, v174
	v_lshl_add_u64 v[170:171], s[50:51], 0, v[164:165]
	s_nop 0
	v_addc_co_u32_e32 v199, vcc, 0, v175, vcc
	v_add_co_u32_e32 v200, vcc, s87, v174
	s_waitcnt lgkmcnt(0)
	s_barrier
	s_nop 0
	v_addc_co_u32_e32 v201, vcc, 0, v175, vcc
	v_add_co_u32_e32 v168, vcc, s0, v174
	s_mov_b32 s0, 0xd000
	s_nop 0
	v_addc_co_u32_e32 v169, vcc, 0, v175, vcc
	v_add_co_u32_e32 v172, vcc, s80, v170
	global_load_dwordx4 v[96:99], v[174:175], off
	global_load_dwordx4 v[100:103], v[196:197], off offset:2048
	v_addc_co_u32_e32 v173, vcc, 0, v171, vcc
	v_add_co_u32_e32 v202, vcc, s0, v174
	global_load_dwordx4 v[104:107], v[200:201], off offset:1024
	global_load_dwordx4 v[108:111], v[198:199], off offset:3072
	global_load_dwordx4 v[112:115], v[168:169], off
	global_load_dwordx4 v[228:231], v[170:171], off
	global_load_dwordx4 v[232:235], v[172:173], off offset:3072
	v_addc_co_u32_e32 v203, vcc, 0, v175, vcc
	global_load_dwordx4 v[116:119], v[202:203], off offset:3072
	s_waitcnt lgkmcnt(0)
	v_pk_add_f32 v[122:123], v[212:213], v[214:215]
	v_mov_b64_e32 v[124:125], s[58:59]
	v_pk_add_f32 v[126:127], v[206:207], v[210:211]
	v_pk_add_f32 v[166:167], v[166:167], v[204:205]
	v_pk_fma_f32 v[122:123], v[122:123], s[56:57], v[124:125] op_sel_hi:[1,0,0]
	v_pk_fma_f32 v[126:127], v[126:127], s[56:57], v[124:125] op_sel_hi:[1,0,0]
	v_pk_fma_f32 v[124:125], v[166:167], s[56:57], v[124:125] op_sel_hi:[1,0,0]
	v_mul_f32_e32 v163, 0x4b800000, v122
	v_cmp_gt_f32_e64 s[10:11], s6, v122
	v_mul_f32_e32 v120, 0x4b800000, v123
	v_mul_f32_e32 v190, 0x4b800000, v124
	v_cmp_gt_f32_e32 vcc, s6, v123
	v_cndmask_b32_e64 v122, v122, v163, s[10:11]
	v_cmp_gt_f32_e64 s[18:19], s6, v124
	v_mul_f32_e32 v166, 0x4b800000, v127
	v_mul_f32_e32 v167, 0x4b800000, v126
	v_mul_f32_e32 v184, 0x4b800000, v125
	v_cndmask_b32_e32 v120, v123, v120, vcc
	v_cmp_gt_f32_e64 s[12:13], s6, v127
	v_cmp_gt_f32_e64 s[14:15], s6, v126
	v_cmp_gt_f32_e64 s[16:17], s6, v125
	v_cndmask_b32_e64 v124, v124, v190, s[18:19]
	v_rsq_f32_e32 v122, v122
	v_cndmask_b32_e64 v123, v127, v166, s[12:13]
	v_cndmask_b32_e64 v126, v126, v167, s[14:15]
	v_cndmask_b32_e64 v125, v125, v184, s[16:17]
	v_rsq_f32_e32 v120, v120
	v_rsq_f32_e32 v127, v124
	v_rsq_f32_e32 v123, v123
	v_rsq_f32_e32 v126, v126
	v_rsq_f32_e32 v125, v125
	v_mul_f32_e32 v163, 0x45800000, v122
	v_mul_f32_e32 v124, 0x45800000, v120
	v_mul_f32_e32 v190, 0x45800000, v127
	v_cndmask_b32_e64 v122, v122, v163, s[10:11]
	v_cmp_gt_u32_e64 s[10:11], 2, v219
	v_mul_f32_e32 v166, 0x45800000, v123
	v_mul_f32_e32 v167, 0x45800000, v126
	v_mul_f32_e32 v184, 0x45800000, v125
	v_cndmask_b32_e32 v120, v120, v124, vcc
	v_cndmask_b32_e64 v204, v127, v190, s[18:19]
	v_cmp_eq_u32_e32 vcc, 0, v219
	v_or_b32_e32 v121, 16, v219
	v_cndmask_b32_e64 v124, v123, v166, s[12:13]
	v_cndmask_b32_e64 v126, v126, v167, s[14:15]
	v_cndmask_b32_e64 v166, v125, v184, s[16:17]
	s_waitcnt vmcnt(7)
	v_cndmask_b32_e64 v205, 0, v97, s[10:11]
	s_waitcnt vmcnt(6)
	v_cndmask_b32_e32 v123, 0, v100, vcc
	v_cndmask_b32_e64 v125, 0, v96, s[10:11]
	v_cndmask_b32_e32 v167, 0, v101, vcc
	v_cndmask_b32_e32 v210, 0, v102, vcc
	s_waitcnt vmcnt(5)
	v_cndmask_b32_e32 v127, 0, v104, vcc
	s_waitcnt vmcnt(4)
	v_cndmask_b32_e64 v163, 0, v108, s[10:11]
	v_cndmask_b32_e32 v206, 0, v105, vcc
	v_cndmask_b32_e64 v207, 0, v109, s[10:11]
	v_cndmask_b32_e64 v211, 0, v98, s[10:11]
	v_cndmask_b32_e32 v212, 0, v106, vcc
	v_cndmask_b32_e64 v213, 0, v110, s[10:11]
	v_cndmask_b32_e32 v214, 0, v103, vcc
	v_cndmask_b32_e64 v215, 0, v99, s[10:11]
	v_cndmask_b32_e32 v219, 0, v107, vcc
	v_cndmask_b32_e64 v220, 0, v111, s[10:11]
	s_waitcnt vmcnt(2)
	v_pk_fma_f32 v[94:95], v[94:95], v[204:205], v[230:231] op_sel_hi:[1,0,1]
	v_pk_fma_f32 v[236:237], v[92:93], v[204:205], v[228:229] op_sel_hi:[1,0,1]
	s_waitcnt vmcnt(1)
	v_pk_fma_f32 v[234:235], v[90:91], v[204:205], v[234:235] op_sel_hi:[1,0,1]
	v_pk_fma_f32 v[232:233], v[88:89], v[204:205], v[232:233] op_sel_hi:[1,0,1]
	global_load_dwordx4 v[90:93], v[170:171], off
	global_load_dwordx4 v[228:231], v[172:173], off offset:3072
	v_or_b32_e32 v88, s91, v121
	v_mul_lo_u32 v88, v88, s7
	v_add_u32_e32 v88, 0x56a000, v88
	v_add_u32_e32 v184, v88, v162
	s_waitcnt vmcnt(1)
	v_pk_fma_f32 v[86:87], v[86:87], v[166:167], v[92:93] op_sel_hi:[1,0,1]
	v_pk_fma_f32 v[84:85], v[84:85], v[166:167], v[90:91] op_sel_hi:[1,0,1]
	s_waitcnt vmcnt(0)
; __device__ __forceinline__ unsigned pk2(float lo, float hi) { return pg8::cvt_pk_bf16(lo, hi); }
;     template <bool tail> __device__ __forceinline__ void run(f32x4 (&acc)[2][2][4][2], const pg8::Unit& u, int wr, int wc, int fr_in, int fq_in) const {
;     ...
; #pragma unroll
;                 for (int m = 0; m < 4; ++m) {
;                     const int r = rbase + 128 * ai + 16 * m;
;                     if (tail) { const float* bp = bias2 + (4 * ai + 2 * wr + (m >> 1)) * (2 * DFF) + chan0 + 4 * n; bg = *(const f32x4*)(bp); bvl = *(const f32x4*)(bp + DFF); }
;                     f32x4 cg_ = acc[ai][0][m][n] * rstd[ai][m] + bg, cv_ = acc[ai][1][m][n] * rstd[ai][m] + bvl;
;                     if (ai == 0 && m == 0) { if (zfirst) { cg_ = (f32x4){0.f, 0.f, 0.f, 0.f}; cv_ = cg_; } }
;                     float o[4];
; #pragma unroll
;                     for (int e = 0; e < 4; ++e) {
;                         float G = wg2[e] * cg_[e], V = wv2[e] * cv_[e];
;                         FMAC_DPP4(G, V, cg_[e], cv_[e], wg1[e], wg0[e], wv1[e], wv0[e], "row_shr:1", "row_shr:2");
;                         if (m == 0) { const float x2g = (fr == 0) ? g14[e] : g15[e], x2v = (fr == 0) ? v14[e] : v15[e];
;                             G = __builtin_fmaf(g15[e], ag[e], G); G = __builtin_fmaf(x2g, bgm[e], G); V = __builtin_fmaf(v15[e], av[e], V); V = __builtin_fmaf(x2v, bvm[e], V); }
;                         else { FMAC_DPP4(G, V, pg[e], pv[e], ag[e], bgm[e], av[e], bvm[e], "row_ror:1", "row_ror:2"); }
;                         o[e] = G * __builtin_amdgcn_rcpf(1.f + __expf(-G)) * V;
;                     }
;                     pg = cg_; pv = cv_;
;                     bool outv; int tg;
;                     if (tail) { outv = (m & 1) != 0; tg = (r >> 5) * S_ + 2016 + (r & 31); } else { outv = r >= 2; tg = tok0 + r; }
;                     if (outv) { u32x2 w; w.x = pk2(o[0], o[1]); w.y = pk2(o[2], o[3]); *(u32x2*)(act + ((unsigned)tg * DFF + chan0 + 4 * n)) = w; }
	v_pk_fma_f32 v[82:83], v[82:83], v[166:167], v[230:231] op_sel_hi:[1,0,1]
	v_pk_fma_f32 v[80:81], v[80:81], v[166:167], v[228:229] op_sel_hi:[1,0,1]
	v_mul_f32_e32 v89, v112, v84
	v_mul_f32_e32 v90, v116, v80
	v_mul_f32_e32 v91, v113, v85
	v_mul_f32_e32 v92, v117, v81
	v_mul_f32_e32 v93, v114, v86
	v_mul_f32_e32 v190, v118, v82
	v_mul_f32_e32 v191, v115, v87
	v_mul_f32_e32 v221, v119, v83
	v_fmac_f32_dpp v89, v84, v100 row_shr:1 row_mask:0xf bank_mask:0xf bound_ctrl:1
	v_fmac_f32_dpp v89, v84, v96 row_shr:2 row_mask:0xf bank_mask:0xf bound_ctrl:1
	v_fmac_f32_dpp v90, v80, v104 row_shr:1 row_mask:0xf bank_mask:0xf bound_ctrl:1
	v_fmac_f32_dpp v90, v80, v108 row_shr:2 row_mask:0xf bank_mask:0xf bound_ctrl:1
	v_fmac_f32_dpp v91, v85, v101 row_shr:1 row_mask:0xf bank_mask:0xf bound_ctrl:1
	v_fmac_f32_dpp v91, v85, v97 row_shr:2 row_mask:0xf bank_mask:0xf bound_ctrl:1
	v_fmac_f32_dpp v92, v81, v105 row_shr:1 row_mask:0xf bank_mask:0xf bound_ctrl:1
	v_fmac_f32_dpp v92, v81, v109 row_shr:2 row_mask:0xf bank_mask:0xf bound_ctrl:1
	v_fmac_f32_dpp v93, v86, v102 row_shr:1 row_mask:0xf bank_mask:0xf bound_ctrl:1
	v_fmac_f32_dpp v93, v86, v98 row_shr:2 row_mask:0xf bank_mask:0xf bound_ctrl:1
	v_fmac_f32_dpp v190, v82, v106 row_shr:1 row_mask:0xf bank_mask:0xf bound_ctrl:1
	v_fmac_f32_dpp v190, v82, v110 row_shr:2 row_mask:0xf bank_mask:0xf bound_ctrl:1
	v_fmac_f32_dpp v191, v87, v103 row_shr:1 row_mask:0xf bank_mask:0xf bound_ctrl:1
	v_fmac_f32_dpp v191, v87, v99 row_shr:2 row_mask:0xf bank_mask:0xf bound_ctrl:1
	v_fmac_f32_dpp v221, v83, v107 row_shr:1 row_mask:0xf bank_mask:0xf bound_ctrl:1
	v_fmac_f32_dpp v221, v83, v111 row_shr:2 row_mask:0xf bank_mask:0xf bound_ctrl:1
	s_nop 0
	v_fmac_f32_dpp v89, v236, v123 row_ror:1 row_mask:0xf bank_mask:0xf bound_ctrl:1
	v_fmac_f32_dpp v89, v236, v125 row_ror:2 row_mask:0xf bank_mask:0xf bound_ctrl:1
	v_fmac_f32_dpp v90, v232, v127 row_ror:1 row_mask:0xf bank_mask:0xf bound_ctrl:1
	v_fmac_f32_dpp v90, v232, v163 row_ror:2 row_mask:0xf bank_mask:0xf bound_ctrl:1
	v_fmac_f32_dpp v91, v237, v167 row_ror:1 row_mask:0xf bank_mask:0xf bound_ctrl:1
	v_fmac_f32_dpp v91, v237, v205 row_ror:2 row_mask:0xf bank_mask:0xf bound_ctrl:1
	v_fmac_f32_dpp v92, v233, v206 row_ror:1 row_mask:0xf bank_mask:0xf bound_ctrl:1
	v_fmac_f32_dpp v92, v233, v207 row_ror:2 row_mask:0xf bank_mask:0xf bound_ctrl:1
	v_fmac_f32_dpp v93, v94, v210 row_ror:1 row_mask:0xf bank_mask:0xf bound_ctrl:1
	v_fmac_f32_dpp v93, v94, v211 row_ror:2 row_mask:0xf bank_mask:0xf bound_ctrl:1
	v_fmac_f32_dpp v190, v234, v212 row_ror:1 row_mask:0xf bank_mask:0xf bound_ctrl:1
	v_fmac_f32_dpp v190, v234, v213 row_ror:2 row_mask:0xf bank_mask:0xf bound_ctrl:1
	v_fmac_f32_dpp v191, v95, v214 row_ror:1 row_mask:0xf bank_mask:0xf bound_ctrl:1
	v_fmac_f32_dpp v191, v95, v215 row_ror:2 row_mask:0xf bank_mask:0xf bound_ctrl:1
	v_fmac_f32_dpp v221, v235, v219 row_ror:1 row_mask:0xf bank_mask:0xf bound_ctrl:1
	v_fmac_f32_dpp v221, v235, v220 row_ror:2 row_mask:0xf bank_mask:0xf bound_ctrl:1
	s_nop 0
	v_mul_f32_e32 v80, 0xbfb8aa3b, v89
	v_mul_f32_e32 v81, 0xbfb8aa3b, v91
	v_mul_f32_e32 v82, 0xbfb8aa3b, v93
	v_mul_f32_e32 v83, 0xbfb8aa3b, v191
	v_exp_f32_e32 v80, v80
	v_exp_f32_e32 v81, v81
	v_exp_f32_e32 v82, v82
	v_exp_f32_e32 v83, v83
	v_add_f32_e32 v80, 1.0, v80
	v_add_f32_e32 v81, 1.0, v81
	v_add_f32_e32 v82, 1.0, v82
	v_add_f32_e32 v83, 1.0, v83
	v_rcp_f32_e32 v80, v80
	v_rcp_f32_e32 v81, v81
	v_rcp_f32_e32 v82, v82
	v_rcp_f32_e32 v83, v83
	v_mul_f32_e32 v80, v89, v80
	v_mul_f32_e32 v81, v91, v81
	v_mul_f32_e32 v82, v93, v82
	v_mul_f32_e32 v83, v191, v83
	v_mul_f32_e32 v80, v90, v80
	v_mul_f32_e32 v81, v92, v81
	v_mul_f32_e32 v82, v190, v82
	v_mul_f32_e32 v83, v221, v83
	v_cvt_pk_bf16_f32 v80, v80, v81
	v_cvt_pk_bf16_f32 v81, v82, v83
	v_lshl_add_u64 v[82:83], v[184:185], 1, s[38:39]
	global_store_dwordx2 v[82:83], v[80:81], off
	v_add_co_u32_e64 v80, s[12:13], s80, v160
	global_load_dwordx4 v[82:85], v[160:161], off
	s_nop 0
	v_addc_co_u32_e64 v81, s[12:13], 0, v161, s[12:13]
	global_load_dwordx4 v[90:93], v[80:81], off offset:3072
	s_waitcnt vmcnt(1)
	v_pk_fma_f32 v[84:85], v[78:79], v[126:127], v[84:85] op_sel_hi:[1,0,1]
	v_pk_fma_f32 v[86:87], v[76:77], v[126:127], v[82:83] op_sel_hi:[1,0,1]
	s_waitcnt vmcnt(0)
	v_pk_fma_f32 v[92:93], v[74:75], v[126:127], v[92:93] op_sel_hi:[1,0,1]
	v_pk_fma_f32 v[90:91], v[72:73], v[126:127], v[90:91] op_sel_hi:[1,0,1]
	global_load_dwordx4 v[72:75], v[160:161], off
	global_load_dwordx4 v[76:79], v[80:81], off offset:3072
	v_lshlrev_b32_e32 v82, 6, v218
	v_or3_b32 v82, v82, v121, s5
	v_mul_lo_u32 v82, v82, s7
	v_add_u32_e32 v184, v82, v162
	s_waitcnt vmcnt(1)
	v_pk_add_f32 v[74:75], v[154:155], v[74:75]
	v_pk_add_f32 v[72:73], v[152:153], v[72:73]
	s_waitcnt vmcnt(0)
; __device__ __forceinline__ unsigned pk2(float lo, float hi) { return pg8::cvt_pk_bf16(lo, hi); }
;     template <bool tail> __device__ __forceinline__ void run(f32x4 (&acc)[2][2][4][2], const pg8::Unit& u, int wr, int wc, int fr_in, int fq_in) const {
;     ...
;                 for (int m = 0; m < 4; ++m) {
;                     const int r = rbase + 128 * ai + 16 * m;
;                     if (tail) { const float* bp = bias2 + (4 * ai + 2 * wr + (m >> 1)) * (2 * DFF) + chan0 + 4 * n; bg = *(const f32x4*)(bp); bvl = *(const f32x4*)(bp + DFF); }
;                     f32x4 cg_ = acc[ai][0][m][n] * rstd[ai][m] + bg, cv_ = acc[ai][1][m][n] * rstd[ai][m] + bvl;
;                     if (ai == 0 && m == 0) { if (zfirst) { cg_ = (f32x4){0.f, 0.f, 0.f, 0.f}; cv_ = cg_; } }
;                     float o[4];
; #pragma unroll
;                     for (int e = 0; e < 4; ++e) {
;                         float G = wg2[e] * cg_[e], V = wv2[e] * cv_[e];
;                         FMAC_DPP4(G, V, cg_[e], cv_[e], wg1[e], wg0[e], wv1[e], wv0[e], "row_shr:1", "row_shr:2");
;                         if (m == 0) { const float x2g = (fr == 0) ? g14[e] : g15[e], x2v = (fr == 0) ? v14[e] : v15[e];
;                             G = __builtin_fmaf(g15[e], ag[e], G); G = __builtin_fmaf(x2g, bgm[e], G); V = __builtin_fmaf(v15[e], av[e], V); V = __builtin_fmaf(x2v, bvm[e], V); }
;                         else { FMAC_DPP4(G, V, pg[e], pv[e], ag[e], bgm[e], av[e], bvm[e], "row_ror:1", "row_ror:2"); }
;                         o[e] = G * __builtin_amdgcn_rcpf(1.f + __expf(-G)) * V;
;                     }
;                     pg = cg_; pv = cv_;
;                     bool outv; int tg;
;                     if (tail) { outv = (m & 1) != 0; tg = (r >> 5) * S_ + 2016 + (r & 31); } else { outv = r >= 2; tg = tok0 + r; }
;                     if (outv) { u32x2 w; w.x = pk2(o[0], o[1]); w.y = pk2(o[2], o[3]); *(u32x2*)(act + ((unsigned)tg * DFF + chan0 + 4 * n)) = w; }
	v_pk_add_f32 v[78:79], v[158:159], v[78:79]
	v_pk_add_f32 v[76:77], v[156:157], v[76:77]
	v_mul_f32_e32 v83, v112, v72
	v_mul_f32_e32 v89, v116, v76
	v_mul_f32_e32 v94, v113, v73
	v_mul_f32_e32 v95, v117, v77
	v_mul_f32_e32 v152, v114, v74
	v_mul_f32_e32 v153, v118, v78
	v_mul_f32_e32 v154, v115, v75
	v_mul_f32_e32 v155, v119, v79
	v_fmac_f32_dpp v83, v72, v100 row_shr:1 row_mask:0xf bank_mask:0xf bound_ctrl:1
	v_fmac_f32_dpp v83, v72, v96 row_shr:2 row_mask:0xf bank_mask:0xf bound_ctrl:1
	v_fmac_f32_dpp v89, v76, v104 row_shr:1 row_mask:0xf bank_mask:0xf bound_ctrl:1
	v_fmac_f32_dpp v89, v76, v108 row_shr:2 row_mask:0xf bank_mask:0xf bound_ctrl:1
	v_fmac_f32_dpp v94, v73, v101 row_shr:1 row_mask:0xf bank_mask:0xf bound_ctrl:1
	v_fmac_f32_dpp v94, v73, v97 row_shr:2 row_mask:0xf bank_mask:0xf bound_ctrl:1
	v_fmac_f32_dpp v95, v77, v105 row_shr:1 row_mask:0xf bank_mask:0xf bound_ctrl:1
	v_fmac_f32_dpp v95, v77, v109 row_shr:2 row_mask:0xf bank_mask:0xf bound_ctrl:1
	v_fmac_f32_dpp v152, v74, v102 row_shr:1 row_mask:0xf bank_mask:0xf bound_ctrl:1
	v_fmac_f32_dpp v152, v74, v98 row_shr:2 row_mask:0xf bank_mask:0xf bound_ctrl:1
	v_fmac_f32_dpp v153, v78, v106 row_shr:1 row_mask:0xf bank_mask:0xf bound_ctrl:1
	v_fmac_f32_dpp v153, v78, v110 row_shr:2 row_mask:0xf bank_mask:0xf bound_ctrl:1
	v_fmac_f32_dpp v154, v75, v103 row_shr:1 row_mask:0xf bank_mask:0xf bound_ctrl:1
	v_fmac_f32_dpp v154, v75, v99 row_shr:2 row_mask:0xf bank_mask:0xf bound_ctrl:1
	v_fmac_f32_dpp v155, v79, v107 row_shr:1 row_mask:0xf bank_mask:0xf bound_ctrl:1
	v_fmac_f32_dpp v155, v79, v111 row_shr:2 row_mask:0xf bank_mask:0xf bound_ctrl:1
	s_nop 0
	v_fmac_f32_dpp v83, v86, v123 row_ror:1 row_mask:0xf bank_mask:0xf bound_ctrl:1
	v_fmac_f32_dpp v83, v86, v125 row_ror:2 row_mask:0xf bank_mask:0xf bound_ctrl:1
	v_fmac_f32_dpp v89, v90, v127 row_ror:1 row_mask:0xf bank_mask:0xf bound_ctrl:1
	v_fmac_f32_dpp v89, v90, v163 row_ror:2 row_mask:0xf bank_mask:0xf bound_ctrl:1
	v_fmac_f32_dpp v94, v87, v167 row_ror:1 row_mask:0xf bank_mask:0xf bound_ctrl:1
	v_fmac_f32_dpp v94, v87, v205 row_ror:2 row_mask:0xf bank_mask:0xf bound_ctrl:1
	v_fmac_f32_dpp v95, v91, v206 row_ror:1 row_mask:0xf bank_mask:0xf bound_ctrl:1
	v_fmac_f32_dpp v95, v91, v207 row_ror:2 row_mask:0xf bank_mask:0xf bound_ctrl:1
	v_fmac_f32_dpp v152, v84, v210 row_ror:1 row_mask:0xf bank_mask:0xf bound_ctrl:1
	v_fmac_f32_dpp v152, v84, v211 row_ror:2 row_mask:0xf bank_mask:0xf bound_ctrl:1
	v_fmac_f32_dpp v153, v92, v212 row_ror:1 row_mask:0xf bank_mask:0xf bound_ctrl:1
	v_fmac_f32_dpp v153, v92, v213 row_ror:2 row_mask:0xf bank_mask:0xf bound_ctrl:1
	v_fmac_f32_dpp v154, v85, v214 row_ror:1 row_mask:0xf bank_mask:0xf bound_ctrl:1
	v_fmac_f32_dpp v154, v85, v215 row_ror:2 row_mask:0xf bank_mask:0xf bound_ctrl:1
	v_fmac_f32_dpp v155, v93, v219 row_ror:1 row_mask:0xf bank_mask:0xf bound_ctrl:1
	v_fmac_f32_dpp v155, v93, v220 row_ror:2 row_mask:0xf bank_mask:0xf bound_ctrl:1
	s_nop 0
	v_mul_f32_e32 v72, 0xbfb8aa3b, v83
	v_mul_f32_e32 v73, 0xbfb8aa3b, v94
	v_mul_f32_e32 v74, 0xbfb8aa3b, v152
	v_mul_f32_e32 v75, 0xbfb8aa3b, v154
	v_exp_f32_e32 v72, v72
	v_exp_f32_e32 v73, v73
	v_exp_f32_e32 v74, v74
	v_exp_f32_e32 v75, v75
	v_add_f32_e32 v72, 1.0, v72
	v_add_f32_e32 v73, 1.0, v73
	v_add_f32_e32 v74, 1.0, v74
	v_add_f32_e32 v75, 1.0, v75
	v_rcp_f32_e32 v72, v72
	v_rcp_f32_e32 v73, v73
	v_rcp_f32_e32 v74, v74
	v_rcp_f32_e32 v75, v75
	v_mul_f32_e32 v72, v83, v72
	v_mul_f32_e32 v73, v94, v73
	v_mul_f32_e32 v74, v152, v74
	v_mul_f32_e32 v75, v154, v75
	v_mul_f32_e32 v72, v89, v72
	v_mul_f32_e32 v73, v95, v73
	v_mul_f32_e32 v74, v153, v74
	v_mul_f32_e32 v75, v155, v75
	v_cvt_pk_bf16_f32 v72, v72, v73
	v_cvt_pk_bf16_f32 v73, v74, v75
	v_lshl_add_u64 v[74:75], v[184:185], 1, s[38:39]
	global_store_dwordx2 v[74:75], v[72:73], off
	v_lshl_add_u64 v[72:73], s[52:53], 0, v[164:165]
	v_add_co_u32_e64 v74, s[12:13], s80, v72
	global_load_dwordx4 v[76:79], v[72:73], off
	s_nop 0
	v_addc_co_u32_e64 v75, s[12:13], 0, v73, s[12:13]
	global_load_dwordx4 v[84:87], v[74:75], off offset:3072
	s_waitcnt vmcnt(1)
	v_pk_fma_f32 v[78:79], v[70:71], v[124:125], v[78:79] op_sel_hi:[1,0,1]
	v_pk_fma_f32 v[76:77], v[68:69], v[124:125], v[76:77] op_sel_hi:[1,0,1]
	s_waitcnt vmcnt(0)
	v_pk_fma_f32 v[86:87], v[66:67], v[124:125], v[86:87] op_sel_hi:[1,0,1]
	v_pk_fma_f32 v[84:85], v[64:65], v[124:125], v[84:85] op_sel_hi:[1,0,1]
	global_load_dwordx4 v[64:67], v[72:73], off
	global_load_dwordx4 v[68:71], v[74:75], off offset:3072
	v_lshlrev_b32_e32 v83, 6, v217
	v_or3_b32 v83, v83, v121, s5
	v_mul_lo_u32 v83, v83, s7
	v_add_u32_e32 v184, v83, v162
	s_waitcnt vmcnt(1)
	v_pk_fma_f32 v[62:63], v[62:63], v[122:123], v[66:67] op_sel_hi:[1,0,1]
	v_pk_fma_f32 v[60:61], v[60:61], v[122:123], v[64:65] op_sel_hi:[1,0,1]
	s_waitcnt vmcnt(0)
; __device__ __forceinline__ unsigned pk2(float lo, float hi) { return pg8::cvt_pk_bf16(lo, hi); }
;     template <bool tail> __device__ __forceinline__ void run(f32x4 (&acc)[2][2][4][2], const pg8::Unit& u, int wr, int wc, int fr_in, int fq_in) const {
;     ...
;                 for (int m = 0; m < 4; ++m) {
;                     const int r = rbase + 128 * ai + 16 * m;
;                     if (tail) { const float* bp = bias2 + (4 * ai + 2 * wr + (m >> 1)) * (2 * DFF) + chan0 + 4 * n; bg = *(const f32x4*)(bp); bvl = *(const f32x4*)(bp + DFF); }
;                     f32x4 cg_ = acc[ai][0][m][n] * rstd[ai][m] + bg, cv_ = acc[ai][1][m][n] * rstd[ai][m] + bvl;
;                     if (ai == 0 && m == 0) { if (zfirst) { cg_ = (f32x4){0.f, 0.f, 0.f, 0.f}; cv_ = cg_; } }
;                     float o[4];
; #pragma unroll
;                     for (int e = 0; e < 4; ++e) {
;                         float G = wg2[e] * cg_[e], V = wv2[e] * cv_[e];
;                         FMAC_DPP4(G, V, cg_[e], cv_[e], wg1[e], wg0[e], wv1[e], wv0[e], "row_shr:1", "row_shr:2");
;                         if (m == 0) { const float x2g = (fr == 0) ? g14[e] : g15[e], x2v = (fr == 0) ? v14[e] : v15[e];
;                             G = __builtin_fmaf(g15[e], ag[e], G); G = __builtin_fmaf(x2g, bgm[e], G); V = __builtin_fmaf(v15[e], av[e], V); V = __builtin_fmaf(x2v, bvm[e], V); }
;                         else { FMAC_DPP4(G, V, pg[e], pv[e], ag[e], bgm[e], av[e], bvm[e], "row_ror:1", "row_ror:2"); }
;                         o[e] = G * __builtin_amdgcn_rcpf(1.f + __expf(-G)) * V;
;                     }
;                     pg = cg_; pv = cv_;
;                     bool outv; int tg;
;                     if (tail) { outv = (m & 1) != 0; tg = (r >> 5) * S_ + 2016 + (r & 31); } else { outv = r >= 2; tg = tok0 + r; }
;                     if (outv) { u32x2 w; w.x = pk2(o[0], o[1]); w.y = pk2(o[2], o[3]); *(u32x2*)(act + ((unsigned)tg * DFF + chan0 + 4 * n)) = w; }
	v_pk_fma_f32 v[58:59], v[58:59], v[122:123], v[70:71] op_sel_hi:[1,0,1]
	v_pk_fma_f32 v[56:57], v[56:57], v[122:123], v[68:69] op_sel_hi:[1,0,1]
	v_mul_f32_e32 v64, v112, v60
	v_mul_f32_e32 v65, v116, v56
	v_mul_f32_e32 v66, v113, v61
	v_mul_f32_e32 v67, v117, v57
	v_mul_f32_e32 v68, v114, v62
	v_mul_f32_e32 v69, v118, v58
	v_mul_f32_e32 v70, v115, v63
	v_mul_f32_e32 v71, v119, v59
	v_fmac_f32_dpp v64, v60, v100 row_shr:1 row_mask:0xf bank_mask:0xf bound_ctrl:1
	v_fmac_f32_dpp v64, v60, v96 row_shr:2 row_mask:0xf bank_mask:0xf bound_ctrl:1
	v_fmac_f32_dpp v65, v56, v104 row_shr:1 row_mask:0xf bank_mask:0xf bound_ctrl:1
	v_fmac_f32_dpp v65, v56, v108 row_shr:2 row_mask:0xf bank_mask:0xf bound_ctrl:1
	v_fmac_f32_dpp v66, v61, v101 row_shr:1 row_mask:0xf bank_mask:0xf bound_ctrl:1
	v_fmac_f32_dpp v66, v61, v97 row_shr:2 row_mask:0xf bank_mask:0xf bound_ctrl:1
	v_fmac_f32_dpp v67, v57, v105 row_shr:1 row_mask:0xf bank_mask:0xf bound_ctrl:1
	v_fmac_f32_dpp v67, v57, v109 row_shr:2 row_mask:0xf bank_mask:0xf bound_ctrl:1
	v_fmac_f32_dpp v68, v62, v102 row_shr:1 row_mask:0xf bank_mask:0xf bound_ctrl:1
	v_fmac_f32_dpp v68, v62, v98 row_shr:2 row_mask:0xf bank_mask:0xf bound_ctrl:1
	v_fmac_f32_dpp v69, v58, v106 row_shr:1 row_mask:0xf bank_mask:0xf bound_ctrl:1
	v_fmac_f32_dpp v69, v58, v110 row_shr:2 row_mask:0xf bank_mask:0xf bound_ctrl:1
	v_fmac_f32_dpp v70, v63, v103 row_shr:1 row_mask:0xf bank_mask:0xf bound_ctrl:1
	v_fmac_f32_dpp v70, v63, v99 row_shr:2 row_mask:0xf bank_mask:0xf bound_ctrl:1
	v_fmac_f32_dpp v71, v59, v107 row_shr:1 row_mask:0xf bank_mask:0xf bound_ctrl:1
	v_fmac_f32_dpp v71, v59, v111 row_shr:2 row_mask:0xf bank_mask:0xf bound_ctrl:1
	s_nop 0
	v_fmac_f32_dpp v64, v76, v123 row_ror:1 row_mask:0xf bank_mask:0xf bound_ctrl:1
	v_fmac_f32_dpp v64, v76, v125 row_ror:2 row_mask:0xf bank_mask:0xf bound_ctrl:1
	v_fmac_f32_dpp v65, v84, v127 row_ror:1 row_mask:0xf bank_mask:0xf bound_ctrl:1
	v_fmac_f32_dpp v65, v84, v163 row_ror:2 row_mask:0xf bank_mask:0xf bound_ctrl:1
	v_fmac_f32_dpp v66, v77, v167 row_ror:1 row_mask:0xf bank_mask:0xf bound_ctrl:1
	v_fmac_f32_dpp v66, v77, v205 row_ror:2 row_mask:0xf bank_mask:0xf bound_ctrl:1
	v_fmac_f32_dpp v67, v85, v206 row_ror:1 row_mask:0xf bank_mask:0xf bound_ctrl:1
	v_fmac_f32_dpp v67, v85, v207 row_ror:2 row_mask:0xf bank_mask:0xf bound_ctrl:1
	v_fmac_f32_dpp v68, v78, v210 row_ror:1 row_mask:0xf bank_mask:0xf bound_ctrl:1
	v_fmac_f32_dpp v68, v78, v211 row_ror:2 row_mask:0xf bank_mask:0xf bound_ctrl:1
	v_fmac_f32_dpp v69, v86, v212 row_ror:1 row_mask:0xf bank_mask:0xf bound_ctrl:1
	v_fmac_f32_dpp v69, v86, v213 row_ror:2 row_mask:0xf bank_mask:0xf bound_ctrl:1
	v_fmac_f32_dpp v70, v79, v214 row_ror:1 row_mask:0xf bank_mask:0xf bound_ctrl:1
	v_fmac_f32_dpp v70, v79, v215 row_ror:2 row_mask:0xf bank_mask:0xf bound_ctrl:1
	v_fmac_f32_dpp v71, v87, v219 row_ror:1 row_mask:0xf bank_mask:0xf bound_ctrl:1
	v_fmac_f32_dpp v71, v87, v220 row_ror:2 row_mask:0xf bank_mask:0xf bound_ctrl:1
	s_nop 0
	v_mul_f32_e32 v56, 0xbfb8aa3b, v64
	v_mul_f32_e32 v57, 0xbfb8aa3b, v66
	v_mul_f32_e32 v58, 0xbfb8aa3b, v68
	v_mul_f32_e32 v59, 0xbfb8aa3b, v70
	v_exp_f32_e32 v56, v56
	v_exp_f32_e32 v57, v57
	v_exp_f32_e32 v58, v58
	v_exp_f32_e32 v59, v59
	v_add_f32_e32 v56, 1.0, v56
	v_add_f32_e32 v57, 1.0, v57
	v_add_f32_e32 v58, 1.0, v58
	v_add_f32_e32 v59, 1.0, v59
	v_rcp_f32_e32 v56, v56
	v_rcp_f32_e32 v57, v57
	v_rcp_f32_e32 v58, v58
	v_rcp_f32_e32 v59, v59
	v_mul_f32_e32 v56, v64, v56
	v_mul_f32_e32 v57, v66, v57
	v_mul_f32_e32 v58, v68, v58
	v_mul_f32_e32 v59, v70, v59
	v_mul_f32_e32 v56, v65, v56
	v_mul_f32_e32 v57, v67, v57
	v_mul_f32_e32 v58, v69, v58
	v_mul_f32_e32 v59, v71, v59
	v_cvt_pk_bf16_f32 v56, v56, v57
	v_cvt_pk_bf16_f32 v57, v58, v59
	v_lshl_add_u64 v[58:59], v[184:185], 1, s[38:39]
	global_store_dwordx2 v[58:59], v[56:57], off
	v_lshl_add_u64 v[76:77], s[54:55], 0, v[164:165]
	v_add_co_u32_e64 v78, s[12:13], s80, v76
	global_load_dwordx4 v[56:59], v[76:77], off
	s_nop 0
	v_addc_co_u32_e64 v79, s[12:13], 0, v77, s[12:13]
	global_load_dwordx4 v[60:63], v[78:79], off offset:3072
	s_waitcnt vmcnt(1)
	v_pk_fma_f32 v[58:59], v[54:55], v[120:121], v[58:59] op_sel_hi:[1,0,1]
	v_pk_fma_f32 v[56:57], v[52:53], v[120:121], v[56:57] op_sel_hi:[1,0,1]
	s_waitcnt vmcnt(0)
	v_pk_fma_f32 v[62:63], v[50:51], v[120:121], v[62:63] op_sel_hi:[1,0,1]
	v_pk_fma_f32 v[60:61], v[48:49], v[120:121], v[60:61] op_sel_hi:[1,0,1]
	global_load_dwordx4 v[48:51], v[76:77], off
	global_load_dwordx4 v[52:55], v[78:79], off offset:3072
	v_lshlrev_b32_e32 v64, 6, v216
	v_or3_b32 v64, v64, v121, s5
	v_mul_lo_u32 v84, v64, s7
	v_add_u32_e32 v184, v84, v162
	s_waitcnt vmcnt(1)
	v_pk_add_f32 v[50:51], v[146:147], v[50:51]
	v_pk_add_f32 v[48:49], v[144:145], v[48:49]
	s_waitcnt vmcnt(0)
; __device__ __forceinline__ unsigned pk2(float lo, float hi) { return pg8::cvt_pk_bf16(lo, hi); }
;     template <bool tail> __device__ __forceinline__ void run(f32x4 (&acc)[2][2][4][2], const pg8::Unit& u, int wr, int wc, int fr_in, int fq_in) const {
;     ...
;             const float* wp = fcw + chan0 + 4 * n;
;             const f32x4 wg0 = *(const f32x4*)(wp), wg1 = *(const f32x4*)(wp + 2 * DFF), wg2 = *(const f32x4*)(wp + 4 * DFF);
;             const f32x4 wv0 = *(const f32x4*)(wp + DFF), wv1 = *(const f32x4*)(wp + 3 * DFF), wv2 = *(const f32x4*)(wp + 5 * DFF);
;             f32x4 bg = (f32x4){0.f, 0.f, 0.f, 0.f}, bvl = bg;
;     ...
;                 for (int m = 0; m < 4; ++m) {
;                     const int r = rbase + 128 * ai + 16 * m;
;                     if (tail) { const float* bp = bias2 + (4 * ai + 2 * wr + (m >> 1)) * (2 * DFF) + chan0 + 4 * n; bg = *(const f32x4*)(bp); bvl = *(const f32x4*)(bp + DFF); }
;                     f32x4 cg_ = acc[ai][0][m][n] * rstd[ai][m] + bg, cv_ = acc[ai][1][m][n] * rstd[ai][m] + bvl;
;                     if (ai == 0 && m == 0) { if (zfirst) { cg_ = (f32x4){0.f, 0.f, 0.f, 0.f}; cv_ = cg_; } }
;                     float o[4];
; #pragma unroll
;                     for (int e = 0; e < 4; ++e) {
;                         float G = wg2[e] * cg_[e], V = wv2[e] * cv_[e];
;                         FMAC_DPP4(G, V, cg_[e], cv_[e], wg1[e], wg0[e], wv1[e], wv0[e], "row_shr:1", "row_shr:2");
;                         if (m == 0) { const float x2g = (fr == 0) ? g14[e] : g15[e], x2v = (fr == 0) ? v14[e] : v15[e];
;                             G = __builtin_fmaf(g15[e], ag[e], G); G = __builtin_fmaf(x2g, bgm[e], G); V = __builtin_fmaf(v15[e], av[e], V); V = __builtin_fmaf(x2v, bvm[e], V); }
;                         else { FMAC_DPP4(G, V, pg[e], pv[e], ag[e], bgm[e], av[e], bvm[e], "row_ror:1", "row_ror:2"); }
;                         o[e] = G * __builtin_amdgcn_rcpf(1.f + __expf(-G)) * V;
;                     }
;                     pg = cg_; pv = cv_;
;                     bool outv; int tg;
;                     if (tail) { outv = (m & 1) != 0; tg = (r >> 5) * S_ + 2016 + (r & 31); } else { outv = r >= 2; tg = tok0 + r; }
;                     if (outv) { u32x2 w; w.x = pk2(o[0], o[1]); w.y = pk2(o[2], o[3]); *(u32x2*)(act + ((unsigned)tg * DFF + chan0 + 4 * n)) = w; }
	v_pk_add_f32 v[54:55], v[150:151], v[54:55]
	v_pk_add_f32 v[52:53], v[148:149], v[52:53]
	v_mul_f32_e32 v64, v112, v48
	v_mul_f32_e32 v65, v116, v52
	v_mul_f32_e32 v66, v113, v49
	v_mul_f32_e32 v67, v117, v53
	v_mul_f32_e32 v68, v114, v50
	v_mul_f32_e32 v69, v118, v54
	v_mul_f32_e32 v70, v115, v51
	v_mul_f32_e32 v71, v119, v55
	v_fmac_f32_dpp v64, v48, v100 row_shr:1 row_mask:0xf bank_mask:0xf bound_ctrl:1
	v_fmac_f32_dpp v64, v48, v96 row_shr:2 row_mask:0xf bank_mask:0xf bound_ctrl:1
	v_fmac_f32_dpp v65, v52, v104 row_shr:1 row_mask:0xf bank_mask:0xf bound_ctrl:1
	v_fmac_f32_dpp v65, v52, v108 row_shr:2 row_mask:0xf bank_mask:0xf bound_ctrl:1
	v_fmac_f32_dpp v66, v49, v101 row_shr:1 row_mask:0xf bank_mask:0xf bound_ctrl:1
	v_fmac_f32_dpp v66, v49, v97 row_shr:2 row_mask:0xf bank_mask:0xf bound_ctrl:1
	v_fmac_f32_dpp v67, v53, v105 row_shr:1 row_mask:0xf bank_mask:0xf bound_ctrl:1
	v_fmac_f32_dpp v67, v53, v109 row_shr:2 row_mask:0xf bank_mask:0xf bound_ctrl:1
	v_fmac_f32_dpp v68, v50, v102 row_shr:1 row_mask:0xf bank_mask:0xf bound_ctrl:1
	v_fmac_f32_dpp v68, v50, v98 row_shr:2 row_mask:0xf bank_mask:0xf bound_ctrl:1
	v_fmac_f32_dpp v69, v54, v106 row_shr:1 row_mask:0xf bank_mask:0xf bound_ctrl:1
	v_fmac_f32_dpp v69, v54, v110 row_shr:2 row_mask:0xf bank_mask:0xf bound_ctrl:1
	v_fmac_f32_dpp v70, v51, v103 row_shr:1 row_mask:0xf bank_mask:0xf bound_ctrl:1
	v_fmac_f32_dpp v70, v51, v99 row_shr:2 row_mask:0xf bank_mask:0xf bound_ctrl:1
	v_fmac_f32_dpp v71, v55, v107 row_shr:1 row_mask:0xf bank_mask:0xf bound_ctrl:1
	v_fmac_f32_dpp v71, v55, v111 row_shr:2 row_mask:0xf bank_mask:0xf bound_ctrl:1
	s_nop 0
	v_fmac_f32_dpp v64, v56, v123 row_ror:1 row_mask:0xf bank_mask:0xf bound_ctrl:1
	v_fmac_f32_dpp v64, v56, v125 row_ror:2 row_mask:0xf bank_mask:0xf bound_ctrl:1
	v_fmac_f32_dpp v65, v60, v127 row_ror:1 row_mask:0xf bank_mask:0xf bound_ctrl:1
	v_fmac_f32_dpp v65, v60, v163 row_ror:2 row_mask:0xf bank_mask:0xf bound_ctrl:1
	v_fmac_f32_dpp v66, v57, v167 row_ror:1 row_mask:0xf bank_mask:0xf bound_ctrl:1
	v_fmac_f32_dpp v66, v57, v205 row_ror:2 row_mask:0xf bank_mask:0xf bound_ctrl:1
	v_fmac_f32_dpp v67, v61, v206 row_ror:1 row_mask:0xf bank_mask:0xf bound_ctrl:1
	v_fmac_f32_dpp v67, v61, v207 row_ror:2 row_mask:0xf bank_mask:0xf bound_ctrl:1
	v_fmac_f32_dpp v68, v58, v210 row_ror:1 row_mask:0xf bank_mask:0xf bound_ctrl:1
	v_fmac_f32_dpp v68, v58, v211 row_ror:2 row_mask:0xf bank_mask:0xf bound_ctrl:1
	v_fmac_f32_dpp v69, v62, v212 row_ror:1 row_mask:0xf bank_mask:0xf bound_ctrl:1
	v_fmac_f32_dpp v69, v62, v213 row_ror:2 row_mask:0xf bank_mask:0xf bound_ctrl:1
	v_fmac_f32_dpp v70, v59, v214 row_ror:1 row_mask:0xf bank_mask:0xf bound_ctrl:1
	v_fmac_f32_dpp v70, v59, v215 row_ror:2 row_mask:0xf bank_mask:0xf bound_ctrl:1
	v_fmac_f32_dpp v71, v63, v219 row_ror:1 row_mask:0xf bank_mask:0xf bound_ctrl:1
	v_fmac_f32_dpp v71, v63, v220 row_ror:2 row_mask:0xf bank_mask:0xf bound_ctrl:1
	s_nop 0
	v_mul_f32_e32 v48, 0xbfb8aa3b, v64
	v_mul_f32_e32 v49, 0xbfb8aa3b, v66
	v_mul_f32_e32 v50, 0xbfb8aa3b, v68
	v_mul_f32_e32 v51, 0xbfb8aa3b, v70
	v_exp_f32_e32 v48, v48
	v_exp_f32_e32 v49, v49
	v_exp_f32_e32 v50, v50
	v_exp_f32_e32 v51, v51
	v_add_f32_e32 v48, 1.0, v48
	v_add_f32_e32 v49, 1.0, v49
	v_add_f32_e32 v50, 1.0, v50
	v_add_f32_e32 v51, 1.0, v51
	v_rcp_f32_e32 v48, v48
	v_rcp_f32_e32 v49, v49
	v_rcp_f32_e32 v50, v50
	v_rcp_f32_e32 v51, v51
	v_mul_f32_e32 v48, v64, v48
	v_mul_f32_e32 v49, v66, v49
	v_mul_f32_e32 v50, v68, v50
	v_mul_f32_e32 v51, v70, v51
	v_mul_f32_e32 v48, v65, v48
	v_mul_f32_e32 v49, v67, v49
	v_mul_f32_e32 v50, v69, v50
	v_mul_f32_e32 v51, v71, v51
	v_cvt_pk_bf16_f32 v48, v48, v49
	v_cvt_pk_bf16_f32 v49, v50, v51
	v_lshl_add_u64 v[50:51], v[184:185], 1, s[38:39]
	global_store_dwordx2 v[50:51], v[48:49], off
	global_load_dwordx4 v[48:51], v[196:197], off offset:2064
	s_nop 0
	global_load_dwordx4 v[52:55], v[174:175], off offset:16
	global_load_dwordx4 v[56:59], v[200:201], off offset:1040
	global_load_dwordx4 v[60:63], v[198:199], off offset:3088
	global_load_dwordx4 v[104:107], v[170:171], off offset:16
	global_load_dwordx4 v[108:111], v[172:173], off offset:3088
	global_load_dwordx4 v[64:67], v[168:169], off offset:16
	global_load_dwordx4 v[68:71], v[202:203], off offset:3088
	v_or_b32_e32 v102, 4, v162
	s_waitcnt vmcnt(7)
	v_cndmask_b32_e32 v85, 0, v48, vcc
	s_waitcnt vmcnt(6)
	v_cndmask_b32_e64 v86, 0, v52, s[10:11]
	s_waitcnt vmcnt(5)
	v_cndmask_b32_e32 v87, 0, v56, vcc
	s_waitcnt vmcnt(4)
	v_cndmask_b32_e64 v89, 0, v60, s[10:11]
	v_cndmask_b32_e32 v90, 0, v49, vcc
	v_cndmask_b32_e64 v91, 0, v53, s[10:11]
	v_cndmask_b32_e32 v92, 0, v57, vcc
	v_cndmask_b32_e64 v93, 0, v61, s[10:11]
	v_cndmask_b32_e32 v94, 0, v50, vcc
	v_cndmask_b32_e64 v95, 0, v54, s[10:11]
	v_cndmask_b32_e32 v96, 0, v58, vcc
	v_cndmask_b32_e64 v97, 0, v62, s[10:11]
	v_cndmask_b32_e32 v98, 0, v51, vcc
	v_cndmask_b32_e64 v99, 0, v55, s[10:11]
	v_cndmask_b32_e32 v100, 0, v59, vcc
	v_cndmask_b32_e64 v101, 0, v63, s[10:11]
	s_waitcnt vmcnt(3)
	v_pk_fma_f32 v[106:107], v[46:47], v[204:205], v[106:107] op_sel_hi:[1,0,1]
	v_pk_fma_f32 v[104:105], v[44:45], v[204:205], v[104:105] op_sel_hi:[1,0,1]
	s_waitcnt vmcnt(2)
	v_pk_fma_f32 v[110:111], v[42:43], v[204:205], v[110:111] op_sel_hi:[1,0,1]
	v_pk_fma_f32 v[108:109], v[40:41], v[204:205], v[108:109] op_sel_hi:[1,0,1]
	global_load_dwordx4 v[40:43], v[170:171], off offset:16
	global_load_dwordx4 v[44:47], v[172:173], off offset:3088
	v_add_u32_e32 v184, v88, v102
	s_waitcnt vmcnt(1)
	v_pk_fma_f32 v[38:39], v[38:39], v[166:167], v[42:43] op_sel_hi:[1,0,1]
	v_pk_fma_f32 v[36:37], v[36:37], v[166:167], v[40:41] op_sel_hi:[1,0,1]
	s_waitcnt vmcnt(0)
; __device__ __forceinline__ unsigned pk2(float lo, float hi) { return pg8::cvt_pk_bf16(lo, hi); }
;     template <bool tail> __device__ __forceinline__ void run(f32x4 (&acc)[2][2][4][2], const pg8::Unit& u, int wr, int wc, int fr_in, int fq_in) const {
;     ...
;                 for (int m = 0; m < 4; ++m) {
;                     const int r = rbase + 128 * ai + 16 * m;
;                     if (tail) { const float* bp = bias2 + (4 * ai + 2 * wr + (m >> 1)) * (2 * DFF) + chan0 + 4 * n; bg = *(const f32x4*)(bp); bvl = *(const f32x4*)(bp + DFF); }
;                     f32x4 cg_ = acc[ai][0][m][n] * rstd[ai][m] + bg, cv_ = acc[ai][1][m][n] * rstd[ai][m] + bvl;
;                     if (ai == 0 && m == 0) { if (zfirst) { cg_ = (f32x4){0.f, 0.f, 0.f, 0.f}; cv_ = cg_; } }
;                     float o[4];
; #pragma unroll
;                     for (int e = 0; e < 4; ++e) {
;                         float G = wg2[e] * cg_[e], V = wv2[e] * cv_[e];
;                         FMAC_DPP4(G, V, cg_[e], cv_[e], wg1[e], wg0[e], wv1[e], wv0[e], "row_shr:1", "row_shr:2");
;                         if (m == 0) { const float x2g = (fr == 0) ? g14[e] : g15[e], x2v = (fr == 0) ? v14[e] : v15[e];
;                             G = __builtin_fmaf(g15[e], ag[e], G); G = __builtin_fmaf(x2g, bgm[e], G); V = __builtin_fmaf(v15[e], av[e], V); V = __builtin_fmaf(x2v, bvm[e], V); }
;                         else { FMAC_DPP4(G, V, pg[e], pv[e], ag[e], bgm[e], av[e], bvm[e], "row_ror:1", "row_ror:2"); }
;                         o[e] = G * __builtin_amdgcn_rcpf(1.f + __expf(-G)) * V;
;                     }
;                     pg = cg_; pv = cv_;
;                     bool outv; int tg;
;                     if (tail) { outv = (m & 1) != 0; tg = (r >> 5) * S_ + 2016 + (r & 31); } else { outv = r >= 2; tg = tok0 + r; }
;                     if (outv) { u32x2 w; w.x = pk2(o[0], o[1]); w.y = pk2(o[2], o[3]); *(u32x2*)(act + ((unsigned)tg * DFF + chan0 + 4 * n)) = w; }
	v_pk_fma_f32 v[34:35], v[34:35], v[166:167], v[46:47] op_sel_hi:[1,0,1]
	v_pk_fma_f32 v[32:33], v[32:33], v[166:167], v[44:45] op_sel_hi:[1,0,1]
	v_mul_f32_e32 v40, v64, v36
	v_mul_f32_e32 v41, v68, v32
	v_mul_f32_e32 v42, v65, v37
	v_mul_f32_e32 v43, v69, v33
	v_mul_f32_e32 v44, v66, v38
	v_mul_f32_e32 v45, v70, v34
	v_mul_f32_e32 v46, v67, v39
	v_mul_f32_e32 v47, v71, v35
	v_fmac_f32_dpp v40, v36, v48 row_shr:1 row_mask:0xf bank_mask:0xf bound_ctrl:1
	v_fmac_f32_dpp v40, v36, v52 row_shr:2 row_mask:0xf bank_mask:0xf bound_ctrl:1
	v_fmac_f32_dpp v41, v32, v56 row_shr:1 row_mask:0xf bank_mask:0xf bound_ctrl:1
	v_fmac_f32_dpp v41, v32, v60 row_shr:2 row_mask:0xf bank_mask:0xf bound_ctrl:1
	v_fmac_f32_dpp v42, v37, v49 row_shr:1 row_mask:0xf bank_mask:0xf bound_ctrl:1
	v_fmac_f32_dpp v42, v37, v53 row_shr:2 row_mask:0xf bank_mask:0xf bound_ctrl:1
	v_fmac_f32_dpp v43, v33, v57 row_shr:1 row_mask:0xf bank_mask:0xf bound_ctrl:1
	v_fmac_f32_dpp v43, v33, v61 row_shr:2 row_mask:0xf bank_mask:0xf bound_ctrl:1
	v_fmac_f32_dpp v44, v38, v50 row_shr:1 row_mask:0xf bank_mask:0xf bound_ctrl:1
	v_fmac_f32_dpp v44, v38, v54 row_shr:2 row_mask:0xf bank_mask:0xf bound_ctrl:1
	v_fmac_f32_dpp v45, v34, v58 row_shr:1 row_mask:0xf bank_mask:0xf bound_ctrl:1
	v_fmac_f32_dpp v45, v34, v62 row_shr:2 row_mask:0xf bank_mask:0xf bound_ctrl:1
	v_fmac_f32_dpp v46, v39, v51 row_shr:1 row_mask:0xf bank_mask:0xf bound_ctrl:1
	v_fmac_f32_dpp v46, v39, v55 row_shr:2 row_mask:0xf bank_mask:0xf bound_ctrl:1
	v_fmac_f32_dpp v47, v35, v59 row_shr:1 row_mask:0xf bank_mask:0xf bound_ctrl:1
	v_fmac_f32_dpp v47, v35, v63 row_shr:2 row_mask:0xf bank_mask:0xf bound_ctrl:1
	s_nop 0
	v_fmac_f32_dpp v40, v104, v85 row_ror:1 row_mask:0xf bank_mask:0xf bound_ctrl:1
	v_fmac_f32_dpp v40, v104, v86 row_ror:2 row_mask:0xf bank_mask:0xf bound_ctrl:1
	v_fmac_f32_dpp v41, v108, v87 row_ror:1 row_mask:0xf bank_mask:0xf bound_ctrl:1
	v_fmac_f32_dpp v41, v108, v89 row_ror:2 row_mask:0xf bank_mask:0xf bound_ctrl:1
	v_fmac_f32_dpp v42, v105, v90 row_ror:1 row_mask:0xf bank_mask:0xf bound_ctrl:1
	v_fmac_f32_dpp v42, v105, v91 row_ror:2 row_mask:0xf bank_mask:0xf bound_ctrl:1
	v_fmac_f32_dpp v43, v109, v92 row_ror:1 row_mask:0xf bank_mask:0xf bound_ctrl:1
	v_fmac_f32_dpp v43, v109, v93 row_ror:2 row_mask:0xf bank_mask:0xf bound_ctrl:1
	v_fmac_f32_dpp v44, v106, v94 row_ror:1 row_mask:0xf bank_mask:0xf bound_ctrl:1
	v_fmac_f32_dpp v44, v106, v95 row_ror:2 row_mask:0xf bank_mask:0xf bound_ctrl:1
	v_fmac_f32_dpp v45, v110, v96 row_ror:1 row_mask:0xf bank_mask:0xf bound_ctrl:1
	v_fmac_f32_dpp v45, v110, v97 row_ror:2 row_mask:0xf bank_mask:0xf bound_ctrl:1
	v_fmac_f32_dpp v46, v107, v98 row_ror:1 row_mask:0xf bank_mask:0xf bound_ctrl:1
	v_fmac_f32_dpp v46, v107, v99 row_ror:2 row_mask:0xf bank_mask:0xf bound_ctrl:1
	v_fmac_f32_dpp v47, v111, v100 row_ror:1 row_mask:0xf bank_mask:0xf bound_ctrl:1
	v_fmac_f32_dpp v47, v111, v101 row_ror:2 row_mask:0xf bank_mask:0xf bound_ctrl:1
	s_nop 0
	v_mul_f32_e32 v32, 0xbfb8aa3b, v40
	v_mul_f32_e32 v33, 0xbfb8aa3b, v42
	v_mul_f32_e32 v34, 0xbfb8aa3b, v44
	v_mul_f32_e32 v35, 0xbfb8aa3b, v46
	v_exp_f32_e32 v32, v32
	v_exp_f32_e32 v33, v33
	v_exp_f32_e32 v34, v34
	v_exp_f32_e32 v35, v35
	v_add_f32_e32 v32, 1.0, v32
	v_add_f32_e32 v33, 1.0, v33
	v_add_f32_e32 v34, 1.0, v34
	v_add_f32_e32 v35, 1.0, v35
	v_rcp_f32_e32 v32, v32
	v_rcp_f32_e32 v33, v33
	v_rcp_f32_e32 v34, v34
	v_rcp_f32_e32 v35, v35
	v_mul_f32_e32 v32, v40, v32
	v_mul_f32_e32 v33, v42, v33
	v_mul_f32_e32 v34, v44, v34
	v_mul_f32_e32 v35, v46, v35
	v_mul_f32_e32 v32, v41, v32
	v_mul_f32_e32 v33, v43, v33
	v_mul_f32_e32 v34, v45, v34
	v_mul_f32_e32 v35, v47, v35
	v_cvt_pk_bf16_f32 v32, v32, v33
	v_cvt_pk_bf16_f32 v33, v34, v35
	v_lshl_add_u64 v[34:35], v[184:185], 1, s[38:39]
	global_store_dwordx2 v[34:35], v[32:33], off
	global_load_dwordx4 v[32:35], v[160:161], off offset:16
	s_nop 0
	global_load_dwordx4 v[36:39], v[80:81], off offset:3088
	s_waitcnt vmcnt(1)
	v_pk_fma_f32 v[34:35], v[30:31], v[126:127], v[34:35] op_sel_hi:[1,0,1]
	v_pk_fma_f32 v[32:33], v[28:29], v[126:127], v[32:33] op_sel_hi:[1,0,1]
	s_waitcnt vmcnt(0)
	v_pk_fma_f32 v[38:39], v[26:27], v[126:127], v[38:39] op_sel_hi:[1,0,1]
	v_pk_fma_f32 v[36:37], v[24:25], v[126:127], v[36:37] op_sel_hi:[1,0,1]
	global_load_dwordx4 v[24:27], v[160:161], off offset:16
	global_load_dwordx4 v[28:31], v[80:81], off offset:3088
	v_add_u32_e32 v184, v82, v102
	s_waitcnt vmcnt(1)
	v_pk_add_f32 v[26:27], v[138:139], v[26:27]
	v_pk_add_f32 v[24:25], v[136:137], v[24:25]
	s_waitcnt vmcnt(0)
; __device__ __forceinline__ unsigned pk2(float lo, float hi) { return pg8::cvt_pk_bf16(lo, hi); }
;     template <bool tail> __device__ __forceinline__ void run(f32x4 (&acc)[2][2][4][2], const pg8::Unit& u, int wr, int wc, int fr_in, int fq_in) const {
;     ...
;                 for (int m = 0; m < 4; ++m) {
;                     const int r = rbase + 128 * ai + 16 * m;
;                     if (tail) { const float* bp = bias2 + (4 * ai + 2 * wr + (m >> 1)) * (2 * DFF) + chan0 + 4 * n; bg = *(const f32x4*)(bp); bvl = *(const f32x4*)(bp + DFF); }
;                     f32x4 cg_ = acc[ai][0][m][n] * rstd[ai][m] + bg, cv_ = acc[ai][1][m][n] * rstd[ai][m] + bvl;
;                     if (ai == 0 && m == 0) { if (zfirst) { cg_ = (f32x4){0.f, 0.f, 0.f, 0.f}; cv_ = cg_; } }
;                     float o[4];
; #pragma unroll
;                     for (int e = 0; e < 4; ++e) {
;                         float G = wg2[e] * cg_[e], V = wv2[e] * cv_[e];
;                         FMAC_DPP4(G, V, cg_[e], cv_[e], wg1[e], wg0[e], wv1[e], wv0[e], "row_shr:1", "row_shr:2");
;                         if (m == 0) { const float x2g = (fr == 0) ? g14[e] : g15[e], x2v = (fr == 0) ? v14[e] : v15[e];
;                             G = __builtin_fmaf(g15[e], ag[e], G); G = __builtin_fmaf(x2g, bgm[e], G); V = __builtin_fmaf(v15[e], av[e], V); V = __builtin_fmaf(x2v, bvm[e], V); }
;                         else { FMAC_DPP4(G, V, pg[e], pv[e], ag[e], bgm[e], av[e], bvm[e], "row_ror:1", "row_ror:2"); }
;                         o[e] = G * __builtin_amdgcn_rcpf(1.f + __expf(-G)) * V;
;                     }
;                     pg = cg_; pv = cv_;
;                     bool outv; int tg;
;                     if (tail) { outv = (m & 1) != 0; tg = (r >> 5) * S_ + 2016 + (r & 31); } else { outv = r >= 2; tg = tok0 + r; }
;                     if (outv) { u32x2 w; w.x = pk2(o[0], o[1]); w.y = pk2(o[2], o[3]); *(u32x2*)(act + ((unsigned)tg * DFF + chan0 + 4 * n)) = w; }
	v_pk_add_f32 v[30:31], v[142:143], v[30:31]
	v_pk_add_f32 v[28:29], v[140:141], v[28:29]
	v_mul_f32_e32 v40, v64, v24
	v_mul_f32_e32 v41, v68, v28
	v_mul_f32_e32 v42, v65, v25
	v_mul_f32_e32 v43, v69, v29
	v_mul_f32_e32 v44, v66, v26
	v_mul_f32_e32 v45, v70, v30
	v_mul_f32_e32 v46, v67, v27
	v_mul_f32_e32 v47, v71, v31
	v_fmac_f32_dpp v40, v24, v48 row_shr:1 row_mask:0xf bank_mask:0xf bound_ctrl:1
	v_fmac_f32_dpp v40, v24, v52 row_shr:2 row_mask:0xf bank_mask:0xf bound_ctrl:1
	v_fmac_f32_dpp v41, v28, v56 row_shr:1 row_mask:0xf bank_mask:0xf bound_ctrl:1
	v_fmac_f32_dpp v41, v28, v60 row_shr:2 row_mask:0xf bank_mask:0xf bound_ctrl:1
	v_fmac_f32_dpp v42, v25, v49 row_shr:1 row_mask:0xf bank_mask:0xf bound_ctrl:1
	v_fmac_f32_dpp v42, v25, v53 row_shr:2 row_mask:0xf bank_mask:0xf bound_ctrl:1
	v_fmac_f32_dpp v43, v29, v57 row_shr:1 row_mask:0xf bank_mask:0xf bound_ctrl:1
	v_fmac_f32_dpp v43, v29, v61 row_shr:2 row_mask:0xf bank_mask:0xf bound_ctrl:1
	v_fmac_f32_dpp v44, v26, v50 row_shr:1 row_mask:0xf bank_mask:0xf bound_ctrl:1
	v_fmac_f32_dpp v44, v26, v54 row_shr:2 row_mask:0xf bank_mask:0xf bound_ctrl:1
	v_fmac_f32_dpp v45, v30, v58 row_shr:1 row_mask:0xf bank_mask:0xf bound_ctrl:1
	v_fmac_f32_dpp v45, v30, v62 row_shr:2 row_mask:0xf bank_mask:0xf bound_ctrl:1
	v_fmac_f32_dpp v46, v27, v51 row_shr:1 row_mask:0xf bank_mask:0xf bound_ctrl:1
	v_fmac_f32_dpp v46, v27, v55 row_shr:2 row_mask:0xf bank_mask:0xf bound_ctrl:1
	v_fmac_f32_dpp v47, v31, v59 row_shr:1 row_mask:0xf bank_mask:0xf bound_ctrl:1
	v_fmac_f32_dpp v47, v31, v63 row_shr:2 row_mask:0xf bank_mask:0xf bound_ctrl:1
	s_nop 0
	v_fmac_f32_dpp v40, v32, v85 row_ror:1 row_mask:0xf bank_mask:0xf bound_ctrl:1
	v_fmac_f32_dpp v40, v32, v86 row_ror:2 row_mask:0xf bank_mask:0xf bound_ctrl:1
	v_fmac_f32_dpp v41, v36, v87 row_ror:1 row_mask:0xf bank_mask:0xf bound_ctrl:1
	v_fmac_f32_dpp v41, v36, v89 row_ror:2 row_mask:0xf bank_mask:0xf bound_ctrl:1
	v_fmac_f32_dpp v42, v33, v90 row_ror:1 row_mask:0xf bank_mask:0xf bound_ctrl:1
	v_fmac_f32_dpp v42, v33, v91 row_ror:2 row_mask:0xf bank_mask:0xf bound_ctrl:1
	v_fmac_f32_dpp v43, v37, v92 row_ror:1 row_mask:0xf bank_mask:0xf bound_ctrl:1
	v_fmac_f32_dpp v43, v37, v93 row_ror:2 row_mask:0xf bank_mask:0xf bound_ctrl:1
	v_fmac_f32_dpp v44, v34, v94 row_ror:1 row_mask:0xf bank_mask:0xf bound_ctrl:1
	v_fmac_f32_dpp v44, v34, v95 row_ror:2 row_mask:0xf bank_mask:0xf bound_ctrl:1
	v_fmac_f32_dpp v45, v38, v96 row_ror:1 row_mask:0xf bank_mask:0xf bound_ctrl:1
	v_fmac_f32_dpp v45, v38, v97 row_ror:2 row_mask:0xf bank_mask:0xf bound_ctrl:1
	v_fmac_f32_dpp v46, v35, v98 row_ror:1 row_mask:0xf bank_mask:0xf bound_ctrl:1
	v_fmac_f32_dpp v46, v35, v99 row_ror:2 row_mask:0xf bank_mask:0xf bound_ctrl:1
	v_fmac_f32_dpp v47, v39, v100 row_ror:1 row_mask:0xf bank_mask:0xf bound_ctrl:1
	v_fmac_f32_dpp v47, v39, v101 row_ror:2 row_mask:0xf bank_mask:0xf bound_ctrl:1
	s_nop 0
	v_mul_f32_e32 v24, 0xbfb8aa3b, v40
	v_mul_f32_e32 v25, 0xbfb8aa3b, v42
	v_mul_f32_e32 v26, 0xbfb8aa3b, v44
	v_mul_f32_e32 v27, 0xbfb8aa3b, v46
	v_exp_f32_e32 v24, v24
	v_exp_f32_e32 v25, v25
	v_exp_f32_e32 v26, v26
	v_exp_f32_e32 v27, v27
	v_add_f32_e32 v24, 1.0, v24
	v_add_f32_e32 v25, 1.0, v25
	v_add_f32_e32 v26, 1.0, v26
	v_add_f32_e32 v27, 1.0, v27
	v_rcp_f32_e32 v24, v24
	v_rcp_f32_e32 v25, v25
	v_rcp_f32_e32 v26, v26
	v_rcp_f32_e32 v27, v27
	v_mul_f32_e32 v24, v40, v24
	v_mul_f32_e32 v25, v42, v25
	v_mul_f32_e32 v26, v44, v26
	v_mul_f32_e32 v27, v46, v27
	v_mul_f32_e32 v24, v41, v24
	v_mul_f32_e32 v25, v43, v25
	v_mul_f32_e32 v26, v45, v26
	v_mul_f32_e32 v27, v47, v27
	v_cvt_pk_bf16_f32 v24, v24, v25
	v_cvt_pk_bf16_f32 v25, v26, v27
	v_lshl_add_u64 v[26:27], v[184:185], 1, s[38:39]
	global_store_dwordx2 v[26:27], v[24:25], off
	global_load_dwordx4 v[24:27], v[72:73], off offset:16
	s_nop 0
	global_load_dwordx4 v[28:31], v[74:75], off offset:3088
	s_waitcnt vmcnt(1)
	v_pk_fma_f32 v[26:27], v[22:23], v[124:125], v[26:27] op_sel_hi:[1,0,1]
	v_pk_fma_f32 v[24:25], v[20:21], v[124:125], v[24:25] op_sel_hi:[1,0,1]
	s_waitcnt vmcnt(0)
	v_pk_fma_f32 v[30:31], v[18:19], v[124:125], v[30:31] op_sel_hi:[1,0,1]
	v_pk_fma_f32 v[28:29], v[16:17], v[124:125], v[28:29] op_sel_hi:[1,0,1]
	global_load_dwordx4 v[16:19], v[72:73], off offset:16
	global_load_dwordx4 v[20:23], v[74:75], off offset:3088
	v_add_u32_e32 v184, v83, v102
	s_waitcnt vmcnt(1)
	v_pk_fma_f32 v[14:15], v[14:15], v[122:123], v[18:19] op_sel_hi:[1,0,1]
	v_pk_fma_f32 v[12:13], v[12:13], v[122:123], v[16:17] op_sel_hi:[1,0,1]
	s_waitcnt vmcnt(0)
; __device__ __forceinline__ unsigned pk2(float lo, float hi) { return pg8::cvt_pk_bf16(lo, hi); }
;     template <bool tail> __device__ __forceinline__ void run(f32x4 (&acc)[2][2][4][2], const pg8::Unit& u, int wr, int wc, int fr_in, int fq_in) const {
;     ...
;                 for (int m = 0; m < 4; ++m) {
;                     const int r = rbase + 128 * ai + 16 * m;
;                     if (tail) { const float* bp = bias2 + (4 * ai + 2 * wr + (m >> 1)) * (2 * DFF) + chan0 + 4 * n; bg = *(const f32x4*)(bp); bvl = *(const f32x4*)(bp + DFF); }
;                     f32x4 cg_ = acc[ai][0][m][n] * rstd[ai][m] + bg, cv_ = acc[ai][1][m][n] * rstd[ai][m] + bvl;
;                     if (ai == 0 && m == 0) { if (zfirst) { cg_ = (f32x4){0.f, 0.f, 0.f, 0.f}; cv_ = cg_; } }
;                     float o[4];
; #pragma unroll
;                     for (int e = 0; e < 4; ++e) {
;                         float G = wg2[e] * cg_[e], V = wv2[e] * cv_[e];
;                         FMAC_DPP4(G, V, cg_[e], cv_[e], wg1[e], wg0[e], wv1[e], wv0[e], "row_shr:1", "row_shr:2");
;                         if (m == 0) { const float x2g = (fr == 0) ? g14[e] : g15[e], x2v = (fr == 0) ? v14[e] : v15[e];
;                             G = __builtin_fmaf(g15[e], ag[e], G); G = __builtin_fmaf(x2g, bgm[e], G); V = __builtin_fmaf(v15[e], av[e], V); V = __builtin_fmaf(x2v, bvm[e], V); }
;                         else { FMAC_DPP4(G, V, pg[e], pv[e], ag[e], bgm[e], av[e], bvm[e], "row_ror:1", "row_ror:2"); }
;                         o[e] = G * __builtin_amdgcn_rcpf(1.f + __expf(-G)) * V;
;                     }
;                     pg = cg_; pv = cv_;
;                     bool outv; int tg;
;                     if (tail) { outv = (m & 1) != 0; tg = (r >> 5) * S_ + 2016 + (r & 31); } else { outv = r >= 2; tg = tok0 + r; }
;                     if (outv) { u32x2 w; w.x = pk2(o[0], o[1]); w.y = pk2(o[2], o[3]); *(u32x2*)(act + ((unsigned)tg * DFF + chan0 + 4 * n)) = w; }
	v_pk_fma_f32 v[10:11], v[10:11], v[122:123], v[22:23] op_sel_hi:[1,0,1]
	v_pk_fma_f32 v[8:9], v[8:9], v[122:123], v[20:21] op_sel_hi:[1,0,1]
	v_mul_f32_e32 v16, v64, v12
	v_mul_f32_e32 v17, v68, v8
	v_mul_f32_e32 v18, v65, v13
	v_mul_f32_e32 v19, v69, v9
	v_mul_f32_e32 v20, v66, v14
	v_mul_f32_e32 v21, v70, v10
	v_mul_f32_e32 v22, v67, v15
	v_mul_f32_e32 v23, v71, v11
	v_fmac_f32_dpp v16, v12, v48 row_shr:1 row_mask:0xf bank_mask:0xf bound_ctrl:1
	v_fmac_f32_dpp v16, v12, v52 row_shr:2 row_mask:0xf bank_mask:0xf bound_ctrl:1
	v_fmac_f32_dpp v17, v8, v56 row_shr:1 row_mask:0xf bank_mask:0xf bound_ctrl:1
	v_fmac_f32_dpp v17, v8, v60 row_shr:2 row_mask:0xf bank_mask:0xf bound_ctrl:1
	v_fmac_f32_dpp v18, v13, v49 row_shr:1 row_mask:0xf bank_mask:0xf bound_ctrl:1
	v_fmac_f32_dpp v18, v13, v53 row_shr:2 row_mask:0xf bank_mask:0xf bound_ctrl:1
	v_fmac_f32_dpp v19, v9, v57 row_shr:1 row_mask:0xf bank_mask:0xf bound_ctrl:1
	v_fmac_f32_dpp v19, v9, v61 row_shr:2 row_mask:0xf bank_mask:0xf bound_ctrl:1
	v_fmac_f32_dpp v20, v14, v50 row_shr:1 row_mask:0xf bank_mask:0xf bound_ctrl:1
	v_fmac_f32_dpp v20, v14, v54 row_shr:2 row_mask:0xf bank_mask:0xf bound_ctrl:1
	v_fmac_f32_dpp v21, v10, v58 row_shr:1 row_mask:0xf bank_mask:0xf bound_ctrl:1
	v_fmac_f32_dpp v21, v10, v62 row_shr:2 row_mask:0xf bank_mask:0xf bound_ctrl:1
	v_fmac_f32_dpp v22, v15, v51 row_shr:1 row_mask:0xf bank_mask:0xf bound_ctrl:1
	v_fmac_f32_dpp v22, v15, v55 row_shr:2 row_mask:0xf bank_mask:0xf bound_ctrl:1
	v_fmac_f32_dpp v23, v11, v59 row_shr:1 row_mask:0xf bank_mask:0xf bound_ctrl:1
	v_fmac_f32_dpp v23, v11, v63 row_shr:2 row_mask:0xf bank_mask:0xf bound_ctrl:1
	s_nop 0
	v_fmac_f32_dpp v16, v24, v85 row_ror:1 row_mask:0xf bank_mask:0xf bound_ctrl:1
	v_fmac_f32_dpp v16, v24, v86 row_ror:2 row_mask:0xf bank_mask:0xf bound_ctrl:1
	v_fmac_f32_dpp v17, v28, v87 row_ror:1 row_mask:0xf bank_mask:0xf bound_ctrl:1
	v_fmac_f32_dpp v17, v28, v89 row_ror:2 row_mask:0xf bank_mask:0xf bound_ctrl:1
	v_fmac_f32_dpp v18, v25, v90 row_ror:1 row_mask:0xf bank_mask:0xf bound_ctrl:1
	v_fmac_f32_dpp v18, v25, v91 row_ror:2 row_mask:0xf bank_mask:0xf bound_ctrl:1
	v_fmac_f32_dpp v19, v29, v92 row_ror:1 row_mask:0xf bank_mask:0xf bound_ctrl:1
	v_fmac_f32_dpp v19, v29, v93 row_ror:2 row_mask:0xf bank_mask:0xf bound_ctrl:1
	v_fmac_f32_dpp v20, v26, v94 row_ror:1 row_mask:0xf bank_mask:0xf bound_ctrl:1
	v_fmac_f32_dpp v20, v26, v95 row_ror:2 row_mask:0xf bank_mask:0xf bound_ctrl:1
	v_fmac_f32_dpp v21, v30, v96 row_ror:1 row_mask:0xf bank_mask:0xf bound_ctrl:1
	v_fmac_f32_dpp v21, v30, v97 row_ror:2 row_mask:0xf bank_mask:0xf bound_ctrl:1
	v_fmac_f32_dpp v22, v27, v98 row_ror:1 row_mask:0xf bank_mask:0xf bound_ctrl:1
	v_fmac_f32_dpp v22, v27, v99 row_ror:2 row_mask:0xf bank_mask:0xf bound_ctrl:1
	v_fmac_f32_dpp v23, v31, v100 row_ror:1 row_mask:0xf bank_mask:0xf bound_ctrl:1
	v_fmac_f32_dpp v23, v31, v101 row_ror:2 row_mask:0xf bank_mask:0xf bound_ctrl:1
	s_nop 0
	v_mul_f32_e32 v8, 0xbfb8aa3b, v16
	v_mul_f32_e32 v9, 0xbfb8aa3b, v18
	v_mul_f32_e32 v10, 0xbfb8aa3b, v20
	v_mul_f32_e32 v11, 0xbfb8aa3b, v22
	v_exp_f32_e32 v8, v8
	v_exp_f32_e32 v9, v9
	v_exp_f32_e32 v10, v10
	v_exp_f32_e32 v11, v11
	v_add_f32_e32 v8, 1.0, v8
	v_add_f32_e32 v9, 1.0, v9
	v_add_f32_e32 v10, 1.0, v10
	v_add_f32_e32 v11, 1.0, v11
	v_rcp_f32_e32 v8, v8
	v_rcp_f32_e32 v9, v9
	v_rcp_f32_e32 v10, v10
	v_rcp_f32_e32 v11, v11
	v_mul_f32_e32 v8, v16, v8
	v_mul_f32_e32 v9, v18, v9
	v_mul_f32_e32 v10, v20, v10
	v_mul_f32_e32 v11, v22, v11
	v_mul_f32_e32 v8, v17, v8
	v_mul_f32_e32 v9, v19, v9
	v_mul_f32_e32 v10, v21, v10
	v_mul_f32_e32 v11, v23, v11
	v_cvt_pk_bf16_f32 v8, v8, v9
	v_cvt_pk_bf16_f32 v9, v10, v11
	v_lshl_add_u64 v[10:11], v[184:185], 1, s[38:39]
	global_store_dwordx2 v[10:11], v[8:9], off
	global_load_dwordx4 v[8:11], v[76:77], off offset:16
	s_nop 0
	global_load_dwordx4 v[12:15], v[78:79], off offset:3088
	s_waitcnt vmcnt(1)
	v_pk_fma_f32 v[10:11], v[6:7], v[120:121], v[10:11] op_sel_hi:[1,0,1]
	v_pk_fma_f32 v[8:9], v[4:5], v[120:121], v[8:9] op_sel_hi:[1,0,1]
	s_waitcnt vmcnt(0)
; __device__ __forceinline__ unsigned pk2(float lo, float hi) { return pg8::cvt_pk_bf16(lo, hi); }
;     template <bool tail> __device__ __forceinline__ void run(f32x4 (&acc)[2][2][4][2], const pg8::Unit& u, int wr, int wc, int fr_in, int fq_in) const {
;     ...
;                 for (int m = 0; m < 4; ++m) {
;                     const int r = rbase + 128 * ai + 16 * m;
;                     if (tail) { const float* bp = bias2 + (4 * ai + 2 * wr + (m >> 1)) * (2 * DFF) + chan0 + 4 * n; bg = *(const f32x4*)(bp); bvl = *(const f32x4*)(bp + DFF); }
;                     f32x4 cg_ = acc[ai][0][m][n] * rstd[ai][m] + bg, cv_ = acc[ai][1][m][n] * rstd[ai][m] + bvl;
;                     if (ai == 0 && m == 0) { if (zfirst) { cg_ = (f32x4){0.f, 0.f, 0.f, 0.f}; cv_ = cg_; } }
;                     float o[4];
; #pragma unroll
;                     for (int e = 0; e < 4; ++e) {
;                         float G = wg2[e] * cg_[e], V = wv2[e] * cv_[e];
;                         FMAC_DPP4(G, V, cg_[e], cv_[e], wg1[e], wg0[e], wv1[e], wv0[e], "row_shr:1", "row_shr:2");
;                         if (m == 0) { const float x2g = (fr == 0) ? g14[e] : g15[e], x2v = (fr == 0) ? v14[e] : v15[e];
;                             G = __builtin_fmaf(g15[e], ag[e], G); G = __builtin_fmaf(x2g, bgm[e], G); V = __builtin_fmaf(v15[e], av[e], V); V = __builtin_fmaf(x2v, bvm[e], V); }
;                         else { FMAC_DPP4(G, V, pg[e], pv[e], ag[e], bgm[e], av[e], bvm[e], "row_ror:1", "row_ror:2"); }
;                         o[e] = G * __builtin_amdgcn_rcpf(1.f + __expf(-G)) * V;
;                     }
;                     pg = cg_; pv = cv_;
;                     bool outv; int tg;
;                     if (tail) { outv = (m & 1) != 0; tg = (r >> 5) * S_ + 2016 + (r & 31); } else { outv = r >= 2; tg = tok0 + r; }
;                     if (outv) { u32x2 w; w.x = pk2(o[0], o[1]); w.y = pk2(o[2], o[3]); *(u32x2*)(act + ((unsigned)tg * DFF + chan0 + 4 * n)) = w; }
	v_pk_fma_f32 v[14:15], v[2:3], v[120:121], v[14:15] op_sel_hi:[1,0,1]
	v_pk_fma_f32 v[12:13], v[0:1], v[120:121], v[12:13] op_sel_hi:[1,0,1]
	global_load_dwordx4 v[0:3], v[76:77], off offset:16
	global_load_dwordx4 v[4:7], v[78:79], off offset:3088
	v_add_u32_e32 v184, v84, v102
	s_waitcnt vmcnt(1)
	v_pk_add_f32 v[2:3], v[130:131], v[2:3]
	v_pk_add_f32 v[0:1], v[128:129], v[0:1]
	s_waitcnt vmcnt(0)
	v_pk_add_f32 v[6:7], v[134:135], v[6:7]
	v_pk_add_f32 v[4:5], v[132:133], v[4:5]
	v_mul_f32_e32 v16, v64, v0
	v_mul_f32_e32 v17, v68, v4
	v_mul_f32_e32 v18, v65, v1
	v_mul_f32_e32 v19, v69, v5
	v_mul_f32_e32 v20, v66, v2
	v_mul_f32_e32 v21, v70, v6
	v_mul_f32_e32 v22, v67, v3
	v_mul_f32_e32 v23, v71, v7
	v_fmac_f32_dpp v16, v0, v48 row_shr:1 row_mask:0xf bank_mask:0xf bound_ctrl:1
	v_fmac_f32_dpp v16, v0, v52 row_shr:2 row_mask:0xf bank_mask:0xf bound_ctrl:1
	v_fmac_f32_dpp v17, v4, v56 row_shr:1 row_mask:0xf bank_mask:0xf bound_ctrl:1
	v_fmac_f32_dpp v17, v4, v60 row_shr:2 row_mask:0xf bank_mask:0xf bound_ctrl:1
	v_fmac_f32_dpp v18, v1, v49 row_shr:1 row_mask:0xf bank_mask:0xf bound_ctrl:1
	v_fmac_f32_dpp v18, v1, v53 row_shr:2 row_mask:0xf bank_mask:0xf bound_ctrl:1
	v_fmac_f32_dpp v19, v5, v57 row_shr:1 row_mask:0xf bank_mask:0xf bound_ctrl:1
	v_fmac_f32_dpp v19, v5, v61 row_shr:2 row_mask:0xf bank_mask:0xf bound_ctrl:1
	v_fmac_f32_dpp v20, v2, v50 row_shr:1 row_mask:0xf bank_mask:0xf bound_ctrl:1
	v_fmac_f32_dpp v20, v2, v54 row_shr:2 row_mask:0xf bank_mask:0xf bound_ctrl:1
	v_fmac_f32_dpp v21, v6, v58 row_shr:1 row_mask:0xf bank_mask:0xf bound_ctrl:1
	v_fmac_f32_dpp v21, v6, v62 row_shr:2 row_mask:0xf bank_mask:0xf bound_ctrl:1
	v_fmac_f32_dpp v22, v3, v51 row_shr:1 row_mask:0xf bank_mask:0xf bound_ctrl:1
	v_fmac_f32_dpp v22, v3, v55 row_shr:2 row_mask:0xf bank_mask:0xf bound_ctrl:1
	v_fmac_f32_dpp v23, v7, v59 row_shr:1 row_mask:0xf bank_mask:0xf bound_ctrl:1
	v_fmac_f32_dpp v23, v7, v63 row_shr:2 row_mask:0xf bank_mask:0xf bound_ctrl:1
	s_nop 0
	v_fmac_f32_dpp v16, v8, v85 row_ror:1 row_mask:0xf bank_mask:0xf bound_ctrl:1
	v_fmac_f32_dpp v16, v8, v86 row_ror:2 row_mask:0xf bank_mask:0xf bound_ctrl:1
	v_fmac_f32_dpp v17, v12, v87 row_ror:1 row_mask:0xf bank_mask:0xf bound_ctrl:1
	v_fmac_f32_dpp v17, v12, v89 row_ror:2 row_mask:0xf bank_mask:0xf bound_ctrl:1
	v_fmac_f32_dpp v18, v9, v90 row_ror:1 row_mask:0xf bank_mask:0xf bound_ctrl:1
	v_fmac_f32_dpp v18, v9, v91 row_ror:2 row_mask:0xf bank_mask:0xf bound_ctrl:1
	v_fmac_f32_dpp v19, v13, v92 row_ror:1 row_mask:0xf bank_mask:0xf bound_ctrl:1
	v_fmac_f32_dpp v19, v13, v93 row_ror:2 row_mask:0xf bank_mask:0xf bound_ctrl:1
	v_fmac_f32_dpp v20, v10, v94 row_ror:1 row_mask:0xf bank_mask:0xf bound_ctrl:1
	v_fmac_f32_dpp v20, v10, v95 row_ror:2 row_mask:0xf bank_mask:0xf bound_ctrl:1
	v_fmac_f32_dpp v21, v14, v96 row_ror:1 row_mask:0xf bank_mask:0xf bound_ctrl:1
	v_fmac_f32_dpp v21, v14, v97 row_ror:2 row_mask:0xf bank_mask:0xf bound_ctrl:1
	v_fmac_f32_dpp v22, v11, v98 row_ror:1 row_mask:0xf bank_mask:0xf bound_ctrl:1
	v_fmac_f32_dpp v22, v11, v99 row_ror:2 row_mask:0xf bank_mask:0xf bound_ctrl:1
	v_fmac_f32_dpp v23, v15, v100 row_ror:1 row_mask:0xf bank_mask:0xf bound_ctrl:1
	v_fmac_f32_dpp v23, v15, v101 row_ror:2 row_mask:0xf bank_mask:0xf bound_ctrl:1
	s_nop 0
	v_mul_f32_e32 v0, 0xbfb8aa3b, v16
	v_mul_f32_e32 v1, 0xbfb8aa3b, v18
	v_mul_f32_e32 v2, 0xbfb8aa3b, v20
	v_mul_f32_e32 v3, 0xbfb8aa3b, v22
	v_exp_f32_e32 v0, v0
	v_exp_f32_e32 v1, v1
	v_exp_f32_e32 v2, v2
	v_exp_f32_e32 v3, v3
	v_add_f32_e32 v0, 1.0, v0
	v_add_f32_e32 v1, 1.0, v1
	v_add_f32_e32 v2, 1.0, v2
	v_add_f32_e32 v3, 1.0, v3
	v_rcp_f32_e32 v0, v0
	v_rcp_f32_e32 v1, v1
	v_rcp_f32_e32 v2, v2
	v_rcp_f32_e32 v3, v3
	v_mul_f32_e32 v0, v16, v0
	v_mul_f32_e32 v1, v18, v1
	v_mul_f32_e32 v2, v20, v2
	v_mul_f32_e32 v3, v22, v3
	v_mul_f32_e32 v0, v17, v0
	v_mul_f32_e32 v1, v19, v1
	v_mul_f32_e32 v2, v21, v2
	v_mul_f32_e32 v3, v23, v3
	v_cvt_pk_bf16_f32 v0, v0, v1
	v_cvt_pk_bf16_f32 v1, v2, v3
	v_lshl_add_u64 v[2:3], v[184:185], 1, s[38:39]
	global_store_dwordx2 v[2:3], v[0:1], off
	s_and_b64 vcc, exec, s[8:9]
	s_mov_b64 s[8:9], -1
	s_cbranch_vccnz .LBB0_562
